# p0_weights hand-written + SGPR-base LDS-DMA addressing in GEMM loops + static s_setprio 1 for waves 4-7 in attention chains
# speedup vs baseline: 1.0131x; 1.0062x over previous
.LBB0_230:
	s_add_u32 s12, s80, 0xfff80080
	s_addc_u32 s13, s81, -1
	s_add_i32 s30, 0, 0x10000
	s_cmp_eq_u32 s28, 28
	s_cselect_b32 s85, s15, s13
	s_cselect_b32 s84, s20, s12
	s_cselect_b32 s83, s21, s25
	s_cselect_b32 s82, s22, s23
	s_add_i32 s12, 0, 0x14000
	v_add_u32_e32 v156, s30, v141
	v_add_u32_e32 v168, s12, v141
	ds_read_b128 v[144:147], v156
	ds_read_b128 v[148:151], v156 offset:1024
	ds_read_b128 v[152:155], v156 offset:2048
	ds_read_b128 v[156:159], v156 offset:3072
	ds_read_b128 v[160:163], v168
	ds_read_b128 v[164:167], v168 offset:1024
	ds_read_b128 v[182:185], v168 offset:2048
	ds_read_b128 v[186:189], v168 offset:3072
	s_add_i32 m0, s1, 0xc000
	ds_read_b128 v[190:193], v143
	ds_read_b128 v[194:197], v143 offset:1024
	ds_read_b128 v[198:201], v143 offset:2048
	ds_read_b128 v[202:205], v143 offset:3072
	ds_read_b128 v[206:209], v143 offset:4096
	ds_read_b128 v[210:213], v143 offset:5120
	ds_read_b128 v[214:217], v143 offset:6144
	ds_read_b128 v[218:221], v143 offset:7168
	global_load_lds_dwordx4 v136, s[80:81]
	s_add_i32 m0, s1, 0xe000
	s_nop 0
	global_load_lds_dwordx4 v138, s[80:81]
	s_waitcnt vmcnt(8)
	s_waitcnt lgkmcnt(0)
	s_barrier
	s_setprio 1
	s_waitcnt lgkmcnt(0)
	v_mfma_f32_16x16x32_bf16 v[124:127], v[144:147], v[190:193], v[124:127]
	v_mfma_f32_16x16x32_bf16 v[120:123], v[152:155], v[190:193], v[120:123]
	v_mfma_f32_16x16x32_bf16 v[108:111], v[144:147], v[198:201], v[108:111]
	v_mfma_f32_16x16x32_bf16 v[104:107], v[152:155], v[198:201], v[104:107]
	v_mfma_f32_16x16x32_bf16 v[92:95], v[144:147], v[206:209], v[92:95]
	v_mfma_f32_16x16x32_bf16 v[88:91], v[152:155], v[206:209], v[88:91]
	v_mfma_f32_16x16x32_bf16 v[76:79], v[144:147], v[214:217], v[76:79]
	v_mfma_f32_16x16x32_bf16 v[72:75], v[152:155], v[214:217], v[72:75]
	v_mfma_f32_16x16x32_bf16 v[124:127], v[148:151], v[194:197], v[124:127]
	v_mfma_f32_16x16x32_bf16 v[120:123], v[156:159], v[194:197], v[120:123]
	v_mfma_f32_16x16x32_bf16 v[108:111], v[148:151], v[202:205], v[108:111]
	v_mfma_f32_16x16x32_bf16 v[104:107], v[156:159], v[202:205], v[104:107]
	v_mfma_f32_16x16x32_bf16 v[92:95], v[148:151], v[210:213], v[92:95]
	v_mfma_f32_16x16x32_bf16 v[88:91], v[156:159], v[210:213], v[88:91]
	v_mfma_f32_16x16x32_bf16 v[76:79], v[148:151], v[218:221], v[76:79]
	v_mfma_f32_16x16x32_bf16 v[72:75], v[156:159], v[218:221], v[72:75]
	s_setprio 0
	s_setprio 1
	v_mfma_f32_16x16x32_bf16 v[116:119], v[160:163], v[190:193], v[116:119]
	v_mfma_f32_16x16x32_bf16 v[112:115], v[182:185], v[190:193], v[112:115]
	v_mfma_f32_16x16x32_bf16 v[100:103], v[160:163], v[198:201], v[100:103]
	v_mfma_f32_16x16x32_bf16 v[96:99], v[182:185], v[198:201], v[96:99]
	v_mfma_f32_16x16x32_bf16 v[84:87], v[160:163], v[206:209], v[84:87]
	v_mfma_f32_16x16x32_bf16 v[80:83], v[182:185], v[206:209], v[80:83]
	v_mfma_f32_16x16x32_bf16 v[68:71], v[160:163], v[214:217], v[68:71]
	v_mfma_f32_16x16x32_bf16 v[64:67], v[182:185], v[214:217], v[64:67]
	v_mfma_f32_16x16x32_bf16 v[116:119], v[164:167], v[194:197], v[116:119]
	v_mfma_f32_16x16x32_bf16 v[112:115], v[186:189], v[194:197], v[112:115]
	v_mfma_f32_16x16x32_bf16 v[100:103], v[164:167], v[202:205], v[100:103]
	v_mfma_f32_16x16x32_bf16 v[96:99], v[186:189], v[202:205], v[96:99]
	v_mfma_f32_16x16x32_bf16 v[84:87], v[164:167], v[210:213], v[84:87]
	v_mfma_f32_16x16x32_bf16 v[80:83], v[186:189], v[210:213], v[80:83]
	v_mfma_f32_16x16x32_bf16 v[68:71], v[164:167], v[218:221], v[68:71]
	v_mfma_f32_16x16x32_bf16 v[64:67], v[186:189], v[218:221], v[64:67]
	s_setprio 0
	s_barrier
	s_add_i32 s13, s30, s0
	s_mov_b32 m0, s13
	ds_read_b128 v[190:193], v143 offset:16384
	ds_read_b128 v[194:197], v143 offset:17408
	ds_read_b128 v[198:201], v143 offset:18432
	ds_read_b128 v[202:205], v143 offset:19456
	ds_read_b128 v[206:209], v143 offset:20480
	ds_read_b128 v[210:213], v143 offset:21504
	ds_read_b128 v[214:217], v143 offset:22528
	ds_read_b128 v[218:221], v143 offset:23552
	global_load_lds_dwordx4 v132, s[82:83]
	s_add_i32 m0, s13, 0x2000
	s_add_u32 s42, s82, 0x80000
	s_addc_u32 s43, s83, 0
	s_add_i32 s12, s12, s0
	global_load_lds_dwordx4 v128, s[82:83]
	s_mov_b32 m0, s12
	s_nop 0
	global_load_lds_dwordx4 v132, s[42:43]
	s_add_i32 m0, s12, 0x2000
	s_nop 0
	global_load_lds_dwordx4 v128, s[42:43]
	s_mov_b32 m0, s1
	s_nop 0
	global_load_lds_dwordx4 v134, s[84:85]
	s_mov_b32 m0, s2
	s_nop 0
	global_load_lds_dwordx4 v130, s[84:85]
	s_waitcnt vmcnt(8)
	s_waitcnt lgkmcnt(0)
	s_barrier
	s_setprio 1
	s_waitcnt lgkmcnt(0)
	v_mfma_f32_16x16x32_bf16 v[60:63], v[144:147], v[190:193], v[60:63]
	v_mfma_f32_16x16x32_bf16 v[56:59], v[152:155], v[190:193], v[56:59]
	v_mfma_f32_16x16x32_bf16 v[44:47], v[144:147], v[198:201], v[44:47]
	v_mfma_f32_16x16x32_bf16 v[40:43], v[152:155], v[198:201], v[40:43]
	v_mfma_f32_16x16x32_bf16 v[28:31], v[144:147], v[206:209], v[28:31]
	v_mfma_f32_16x16x32_bf16 v[24:27], v[152:155], v[206:209], v[24:27]
	v_mfma_f32_16x16x32_bf16 v[12:15], v[144:147], v[214:217], v[12:15]
	v_mfma_f32_16x16x32_bf16 v[8:11], v[152:155], v[214:217], v[8:11]
	v_mfma_f32_16x16x32_bf16 v[60:63], v[148:151], v[194:197], v[60:63]
	v_mfma_f32_16x16x32_bf16 v[56:59], v[156:159], v[194:197], v[56:59]
	v_mfma_f32_16x16x32_bf16 v[44:47], v[148:151], v[202:205], v[44:47]
	v_mfma_f32_16x16x32_bf16 v[40:43], v[156:159], v[202:205], v[40:43]
	v_mfma_f32_16x16x32_bf16 v[28:31], v[148:151], v[210:213], v[28:31]
	v_mfma_f32_16x16x32_bf16 v[24:27], v[156:159], v[210:213], v[24:27]
	v_mfma_f32_16x16x32_bf16 v[12:15], v[148:151], v[218:221], v[12:15]
	v_mfma_f32_16x16x32_bf16 v[8:11], v[156:159], v[218:221], v[8:11]
	s_setprio 0
	s_setprio 1
	v_mfma_f32_16x16x32_bf16 v[52:55], v[160:163], v[190:193], v[52:55]
	v_mfma_f32_16x16x32_bf16 v[48:51], v[182:185], v[190:193], v[48:51]
	v_mfma_f32_16x16x32_bf16 v[36:39], v[160:163], v[198:201], v[36:39]
	v_mfma_f32_16x16x32_bf16 v[32:35], v[182:185], v[198:201], v[32:35]
	v_mfma_f32_16x16x32_bf16 v[20:23], v[160:163], v[206:209], v[20:23]
	v_mfma_f32_16x16x32_bf16 v[16:19], v[182:185], v[206:209], v[16:19]
	v_mfma_f32_16x16x32_bf16 v[4:7], v[160:163], v[214:217], v[4:7]
	v_mfma_f32_16x16x32_bf16 v[0:3], v[182:185], v[214:217], v[0:3]
	v_mfma_f32_16x16x32_bf16 v[52:55], v[164:167], v[194:197], v[52:55]
	v_mfma_f32_16x16x32_bf16 v[48:51], v[186:189], v[194:197], v[48:51]
	v_mfma_f32_16x16x32_bf16 v[36:39], v[164:167], v[202:205], v[36:39]
	v_mfma_f32_16x16x32_bf16 v[32:35], v[186:189], v[202:205], v[32:35]
	v_mfma_f32_16x16x32_bf16 v[20:23], v[164:167], v[210:213], v[20:23]
	v_mfma_f32_16x16x32_bf16 v[16:19], v[186:189], v[210:213], v[16:19]
	v_mfma_f32_16x16x32_bf16 v[4:7], v[164:167], v[218:221], v[4:7]
	v_mfma_f32_16x16x32_bf16 v[0:3], v[186:189], v[218:221], v[0:3]
	s_setprio 0
	s_barrier
	s_add_i32 s12, 0, 0x18000
	s_add_i32 s13, 0, 0x1c000
	v_add_u32_e32 v156, s12, v141
	v_add_u32_e32 v168, s13, v141
	ds_read_b128 v[144:147], v156
	ds_read_b128 v[148:151], v156 offset:1024
	ds_read_b128 v[152:155], v156 offset:2048
	ds_read_b128 v[156:159], v156 offset:3072
	ds_read_b128 v[160:163], v168
	ds_read_b128 v[164:167], v168 offset:1024
	ds_read_b128 v[182:185], v168 offset:2048
	ds_read_b128 v[186:189], v168 offset:3072
	s_add_u32 s42, s84, 0x80000
	s_addc_u32 s43, s85, 0
	s_mov_b32 m0, s3
	ds_read_b128 v[190:193], v143 offset:32768
	ds_read_b128 v[194:197], v143 offset:33792
	ds_read_b128 v[198:201], v143 offset:34816
	ds_read_b128 v[202:205], v143 offset:35840
	ds_read_b128 v[206:209], v143 offset:36864
	ds_read_b128 v[210:213], v143 offset:37888
	ds_read_b128 v[214:217], v143 offset:38912
	ds_read_b128 v[218:221], v143 offset:39936
	global_load_lds_dwordx4 v134, s[42:43]
	s_mov_b32 m0, s8
	s_nop 0
	global_load_lds_dwordx4 v130, s[42:43]
	s_waitcnt vmcnt(8)
	s_waitcnt lgkmcnt(0)
	s_barrier
	s_setprio 1
	s_waitcnt lgkmcnt(0)
	v_mfma_f32_16x16x32_bf16 v[124:127], v[144:147], v[190:193], v[124:127]
	v_mfma_f32_16x16x32_bf16 v[120:123], v[152:155], v[190:193], v[120:123]
	v_mfma_f32_16x16x32_bf16 v[108:111], v[144:147], v[198:201], v[108:111]
	v_mfma_f32_16x16x32_bf16 v[104:107], v[152:155], v[198:201], v[104:107]
	v_mfma_f32_16x16x32_bf16 v[92:95], v[144:147], v[206:209], v[92:95]
	v_mfma_f32_16x16x32_bf16 v[88:91], v[152:155], v[206:209], v[88:91]
	v_mfma_f32_16x16x32_bf16 v[76:79], v[144:147], v[214:217], v[76:79]
	v_mfma_f32_16x16x32_bf16 v[72:75], v[152:155], v[214:217], v[72:75]
	v_mfma_f32_16x16x32_bf16 v[124:127], v[148:151], v[194:197], v[124:127]
	v_mfma_f32_16x16x32_bf16 v[120:123], v[156:159], v[194:197], v[120:123]
	v_mfma_f32_16x16x32_bf16 v[108:111], v[148:151], v[202:205], v[108:111]
	v_mfma_f32_16x16x32_bf16 v[104:107], v[156:159], v[202:205], v[104:107]
	v_mfma_f32_16x16x32_bf16 v[92:95], v[148:151], v[210:213], v[92:95]
	v_mfma_f32_16x16x32_bf16 v[88:91], v[156:159], v[210:213], v[88:91]
	v_mfma_f32_16x16x32_bf16 v[76:79], v[148:151], v[218:221], v[76:79]
	v_mfma_f32_16x16x32_bf16 v[72:75], v[156:159], v[218:221], v[72:75]
	s_setprio 0
	s_setprio 1
	v_mfma_f32_16x16x32_bf16 v[116:119], v[160:163], v[190:193], v[116:119]
	v_mfma_f32_16x16x32_bf16 v[112:115], v[182:185], v[190:193], v[112:115]
	v_mfma_f32_16x16x32_bf16 v[100:103], v[160:163], v[198:201], v[100:103]
	v_mfma_f32_16x16x32_bf16 v[96:99], v[182:185], v[198:201], v[96:99]
	v_mfma_f32_16x16x32_bf16 v[84:87], v[160:163], v[206:209], v[84:87]
	v_mfma_f32_16x16x32_bf16 v[80:83], v[182:185], v[206:209], v[80:83]
	v_mfma_f32_16x16x32_bf16 v[68:71], v[160:163], v[214:217], v[68:71]
	v_mfma_f32_16x16x32_bf16 v[64:67], v[182:185], v[214:217], v[64:67]
	v_mfma_f32_16x16x32_bf16 v[116:119], v[164:167], v[194:197], v[116:119]
	v_mfma_f32_16x16x32_bf16 v[112:115], v[186:189], v[194:197], v[112:115]
	v_mfma_f32_16x16x32_bf16 v[100:103], v[164:167], v[202:205], v[100:103]
	v_mfma_f32_16x16x32_bf16 v[96:99], v[186:189], v[202:205], v[96:99]
	v_mfma_f32_16x16x32_bf16 v[84:87], v[164:167], v[210:213], v[84:87]
	v_mfma_f32_16x16x32_bf16 v[80:83], v[186:189], v[210:213], v[80:83]
	v_mfma_f32_16x16x32_bf16 v[68:71], v[164:167], v[218:221], v[68:71]
	v_mfma_f32_16x16x32_bf16 v[64:67], v[186:189], v[218:221], v[64:67]
	s_setprio 0
	s_barrier
	s_add_i32 s12, s12, s0
	s_mov_b32 m0, s12
	ds_read_b128 v[190:193], v143 offset:49152
	ds_read_b128 v[194:197], v143 offset:50176
	ds_read_b128 v[198:201], v143 offset:51200
	ds_read_b128 v[202:205], v143 offset:52224
	ds_read_b128 v[206:209], v143 offset:53248
	ds_read_b128 v[210:213], v143 offset:54272
	ds_read_b128 v[214:217], v143 offset:55296
	ds_read_b128 v[218:221], v143 offset:56320
	s_add_u32 s100, s82, s16
	s_addc_u32 s101, s83, s17
	global_load_lds_dwordx4 v132, s[100:101]
	s_add_i32 m0, s12, 0x2000
	s_add_u32 s42, s82, 0x80080
	s_addc_u32 s43, s83, 0
	s_add_i32 s12, s13, s0
	global_load_lds_dwordx4 v128, s[100:101]
	s_mov_b32 m0, s12
	s_nop 0
	global_load_lds_dwordx4 v132, s[42:43]
	s_add_i32 m0, s12, 0x2000
	s_nop 0
	global_load_lds_dwordx4 v128, s[42:43]
	s_mov_b32 m0, s9
	s_nop 0
	s_add_u32 s100, s84, s16
	s_addc_u32 s101, s85, s17
	global_load_lds_dwordx4 v134, s[100:101]
	s_mov_b32 m0, s10
	s_nop 0
	global_load_lds_dwordx4 v130, s[100:101]
	s_waitcnt vmcnt(8)
	s_waitcnt lgkmcnt(0)
	s_barrier
	s_setprio 1
	s_waitcnt lgkmcnt(0)
	v_mfma_f32_16x16x32_bf16 v[60:63], v[144:147], v[190:193], v[60:63]
	v_mfma_f32_16x16x32_bf16 v[56:59], v[152:155], v[190:193], v[56:59]
	v_mfma_f32_16x16x32_bf16 v[44:47], v[144:147], v[198:201], v[44:47]
	v_mfma_f32_16x16x32_bf16 v[40:43], v[152:155], v[198:201], v[40:43]
	v_mfma_f32_16x16x32_bf16 v[28:31], v[144:147], v[206:209], v[28:31]
	v_mfma_f32_16x16x32_bf16 v[24:27], v[152:155], v[206:209], v[24:27]
	v_mfma_f32_16x16x32_bf16 v[12:15], v[144:147], v[214:217], v[12:15]
	v_mfma_f32_16x16x32_bf16 v[8:11], v[152:155], v[214:217], v[8:11]
	v_mfma_f32_16x16x32_bf16 v[60:63], v[148:151], v[194:197], v[60:63]
	v_mfma_f32_16x16x32_bf16 v[56:59], v[156:159], v[194:197], v[56:59]
	v_mfma_f32_16x16x32_bf16 v[44:47], v[148:151], v[202:205], v[44:47]
	v_mfma_f32_16x16x32_bf16 v[40:43], v[156:159], v[202:205], v[40:43]
	v_mfma_f32_16x16x32_bf16 v[28:31], v[148:151], v[210:213], v[28:31]
	v_mfma_f32_16x16x32_bf16 v[24:27], v[156:159], v[210:213], v[24:27]
	v_mfma_f32_16x16x32_bf16 v[12:15], v[148:151], v[218:221], v[12:15]
	v_mfma_f32_16x16x32_bf16 v[8:11], v[156:159], v[218:221], v[8:11]
	s_setprio 0
	s_setprio 1
	v_mfma_f32_16x16x32_bf16 v[52:55], v[160:163], v[190:193], v[52:55]
	v_mfma_f32_16x16x32_bf16 v[48:51], v[182:185], v[190:193], v[48:51]
	v_mfma_f32_16x16x32_bf16 v[36:39], v[160:163], v[198:201], v[36:39]
	v_mfma_f32_16x16x32_bf16 v[32:35], v[182:185], v[198:201], v[32:35]
	v_mfma_f32_16x16x32_bf16 v[20:23], v[160:163], v[206:209], v[20:23]
	v_mfma_f32_16x16x32_bf16 v[16:19], v[182:185], v[206:209], v[16:19]
	v_mfma_f32_16x16x32_bf16 v[4:7], v[160:163], v[214:217], v[4:7]
	v_mfma_f32_16x16x32_bf16 v[0:3], v[182:185], v[214:217], v[0:3]
	v_mfma_f32_16x16x32_bf16 v[52:55], v[164:167], v[194:197], v[52:55]
	v_mfma_f32_16x16x32_bf16 v[48:51], v[186:189], v[194:197], v[48:51]
	v_mfma_f32_16x16x32_bf16 v[36:39], v[164:167], v[202:205], v[36:39]
	v_mfma_f32_16x16x32_bf16 v[32:35], v[186:189], v[202:205], v[32:35]
	v_mfma_f32_16x16x32_bf16 v[20:23], v[164:167], v[210:213], v[20:23]
	v_mfma_f32_16x16x32_bf16 v[16:19], v[186:189], v[210:213], v[16:19]
	v_mfma_f32_16x16x32_bf16 v[4:7], v[164:167], v[218:221], v[4:7]
	v_mfma_f32_16x16x32_bf16 v[0:3], v[186:189], v[218:221], v[0:3]
	s_setprio 0
	s_barrier
	s_add_i32 s28, s28, 2
	s_add_u32 s80, s80, 0x100
	s_addc_u32 s81, s81, 0
	s_add_u32 s23, s23, 0x100
	s_addc_u32 s25, s25, 0
	s_cmp_gt_u32 s28, 29
	s_cbranch_scc0 .LBB0_230
	s_and_b64 vcc, exec, s[68:69]
	s_cbranch_vccz .LBB0_233
	s_barrier

.LBB0_313:
	s_add_u32 s78, s76, 0xffffff00
	s_addc_u32 s79, s77, -1
	s_add_i32 s12, 0, 0x10000
	s_cmpk_eq_i32 s3, 0x54
	s_cselect_b32 s83, s7, s79
	s_cselect_b32 s82, s6, s78
	s_cselect_b32 s81, s75, s30
	s_cselect_b32 s80, s74, s2
	s_add_i32 s13, 0, 0x14000
	v_add_u32_e32 v152, s12, v166
	v_add_u32_e32 v164, s13, v166
	ds_read_b128 v[128:131], v152
	ds_read_b128 v[132:135], v152 offset:1024
	ds_read_b128 v[148:151], v152 offset:2048
	ds_read_b128 v[152:155], v152 offset:3072
	ds_read_b128 v[156:159], v164
	ds_read_b128 v[160:163], v164 offset:1024
	ds_read_b128 v[170:173], v164 offset:2048
	ds_read_b128 v[178:181], v164 offset:3072
	s_add_i32 m0, s9, 0xc000
	ds_read_b128 v[184:187], v183
	ds_read_b128 v[188:191], v183 offset:1024
	ds_read_b128 v[192:195], v183 offset:2048
	ds_read_b128 v[196:199], v183 offset:3072
	ds_read_b128 v[200:203], v183 offset:4096
	ds_read_b128 v[204:207], v183 offset:5120
	ds_read_b128 v[208:211], v183 offset:6144
	ds_read_b128 v[212:215], v183 offset:7168
	global_load_lds_dwordx4 v144, s[76:77]
	s_add_i32 m0, s9, 0xe000
	s_nop 0
	global_load_lds_dwordx4 v146, s[76:77]
	s_waitcnt vmcnt(8)
	s_waitcnt lgkmcnt(0)
	s_barrier
	s_setprio 1
	s_waitcnt lgkmcnt(0)
	v_mfma_f32_16x16x32_bf16 v[124:127], v[128:131], v[184:187], v[124:127]
	v_mfma_f32_16x16x32_bf16 v[120:123], v[148:151], v[184:187], v[120:123]
	v_mfma_f32_16x16x32_bf16 v[112:115], v[128:131], v[192:195], v[112:115]
	v_mfma_f32_16x16x32_bf16 v[104:107], v[148:151], v[192:195], v[104:107]
	v_mfma_f32_16x16x32_bf16 v[92:95], v[128:131], v[200:203], v[92:95]
	v_mfma_f32_16x16x32_bf16 v[88:91], v[148:151], v[200:203], v[88:91]
	v_mfma_f32_16x16x32_bf16 v[80:83], v[128:131], v[208:211], v[80:83]
	v_mfma_f32_16x16x32_bf16 v[72:75], v[148:151], v[208:211], v[72:75]
	v_mfma_f32_16x16x32_bf16 v[124:127], v[132:135], v[188:191], v[124:127]
	v_mfma_f32_16x16x32_bf16 v[120:123], v[152:155], v[188:191], v[120:123]
	v_mfma_f32_16x16x32_bf16 v[112:115], v[132:135], v[196:199], v[112:115]
	v_mfma_f32_16x16x32_bf16 v[104:107], v[152:155], v[196:199], v[104:107]
	v_mfma_f32_16x16x32_bf16 v[92:95], v[132:135], v[204:207], v[92:95]
	v_mfma_f32_16x16x32_bf16 v[88:91], v[152:155], v[204:207], v[88:91]
	v_mfma_f32_16x16x32_bf16 v[80:83], v[132:135], v[212:215], v[80:83]
	v_mfma_f32_16x16x32_bf16 v[72:75], v[152:155], v[212:215], v[72:75]
	s_setprio 0
	s_setprio 1
	v_mfma_f32_16x16x32_bf16 v[116:119], v[156:159], v[184:187], v[116:119]
	v_mfma_f32_16x16x32_bf16 v[108:111], v[170:173], v[184:187], v[108:111]
	v_mfma_f32_16x16x32_bf16 v[100:103], v[156:159], v[192:195], v[100:103]
	v_mfma_f32_16x16x32_bf16 v[96:99], v[170:173], v[192:195], v[96:99]
	v_mfma_f32_16x16x32_bf16 v[84:87], v[156:159], v[200:203], v[84:87]
	v_mfma_f32_16x16x32_bf16 v[76:79], v[170:173], v[200:203], v[76:79]
	v_mfma_f32_16x16x32_bf16 v[68:71], v[156:159], v[208:211], v[68:71]
	v_mfma_f32_16x16x32_bf16 v[64:67], v[170:173], v[208:211], v[64:67]
	v_mfma_f32_16x16x32_bf16 v[116:119], v[160:163], v[188:191], v[116:119]
	v_mfma_f32_16x16x32_bf16 v[108:111], v[178:181], v[188:191], v[108:111]
	v_mfma_f32_16x16x32_bf16 v[100:103], v[160:163], v[196:199], v[100:103]
	v_mfma_f32_16x16x32_bf16 v[96:99], v[178:181], v[196:199], v[96:99]
	v_mfma_f32_16x16x32_bf16 v[84:87], v[160:163], v[204:207], v[84:87]
	v_mfma_f32_16x16x32_bf16 v[76:79], v[178:181], v[204:207], v[76:79]
	v_mfma_f32_16x16x32_bf16 v[68:71], v[160:163], v[212:215], v[68:71]
	v_mfma_f32_16x16x32_bf16 v[64:67], v[178:181], v[212:215], v[64:67]
	s_setprio 0
	s_barrier
	s_add_i32 s12, s12, s8
	s_mov_b32 m0, s12
	ds_read_b128 v[184:187], v183 offset:16384
	ds_read_b128 v[188:191], v183 offset:17408
	ds_read_b128 v[192:195], v183 offset:18432
	ds_read_b128 v[196:199], v183 offset:19456
	ds_read_b128 v[200:203], v183 offset:20480
	ds_read_b128 v[204:207], v183 offset:21504
	ds_read_b128 v[208:211], v183 offset:22528
	ds_read_b128 v[212:215], v183 offset:23552
	global_load_lds_dwordx4 v138, s[80:81]
	s_add_i32 m0, s12, 0x2000
	s_add_u32 s42, s80, 0x160000
	s_addc_u32 s43, s81, 0
	s_add_i32 s12, s13, s8
	global_load_lds_dwordx4 v142, s[80:81]
	s_mov_b32 m0, s12
	s_nop 0
	global_load_lds_dwordx4 v138, s[42:43]
	s_add_i32 m0, s12, 0x2000
	s_nop 0
	global_load_lds_dwordx4 v142, s[42:43]
	s_mov_b32 m0, s9
	s_nop 0
	global_load_lds_dwordx4 v136, s[82:83]
	s_mov_b32 m0, s10
	s_nop 0
	global_load_lds_dwordx4 v140, s[82:83]
	s_waitcnt vmcnt(8)
	s_waitcnt lgkmcnt(0)
	s_barrier
	s_setprio 1
	s_waitcnt lgkmcnt(0)
	v_mfma_f32_16x16x32_bf16 v[60:63], v[128:131], v[184:187], v[60:63]
	v_mfma_f32_16x16x32_bf16 v[56:59], v[148:151], v[184:187], v[56:59]
	v_mfma_f32_16x16x32_bf16 v[48:51], v[128:131], v[192:195], v[48:51]
	v_mfma_f32_16x16x32_bf16 v[40:43], v[148:151], v[192:195], v[40:43]
	v_mfma_f32_16x16x32_bf16 v[28:31], v[128:131], v[200:203], v[28:31]
	v_mfma_f32_16x16x32_bf16 v[24:27], v[148:151], v[200:203], v[24:27]
	v_mfma_f32_16x16x32_bf16 v[16:19], v[128:131], v[208:211], v[16:19]
	v_mfma_f32_16x16x32_bf16 v[8:11], v[148:151], v[208:211], v[8:11]
	v_mfma_f32_16x16x32_bf16 v[60:63], v[132:135], v[188:191], v[60:63]
	v_mfma_f32_16x16x32_bf16 v[56:59], v[152:155], v[188:191], v[56:59]
	v_mfma_f32_16x16x32_bf16 v[48:51], v[132:135], v[196:199], v[48:51]
	v_mfma_f32_16x16x32_bf16 v[40:43], v[152:155], v[196:199], v[40:43]
	v_mfma_f32_16x16x32_bf16 v[28:31], v[132:135], v[204:207], v[28:31]
	v_mfma_f32_16x16x32_bf16 v[24:27], v[152:155], v[204:207], v[24:27]
	v_mfma_f32_16x16x32_bf16 v[16:19], v[132:135], v[212:215], v[16:19]
	v_mfma_f32_16x16x32_bf16 v[8:11], v[152:155], v[212:215], v[8:11]
	s_setprio 0
	s_setprio 1
	v_mfma_f32_16x16x32_bf16 v[52:55], v[156:159], v[184:187], v[52:55]
	v_mfma_f32_16x16x32_bf16 v[44:47], v[170:173], v[184:187], v[44:47]
	v_mfma_f32_16x16x32_bf16 v[36:39], v[156:159], v[192:195], v[36:39]
	v_mfma_f32_16x16x32_bf16 v[32:35], v[170:173], v[192:195], v[32:35]
	v_mfma_f32_16x16x32_bf16 v[20:23], v[156:159], v[200:203], v[20:23]
	v_mfma_f32_16x16x32_bf16 v[12:15], v[170:173], v[200:203], v[12:15]
	v_mfma_f32_16x16x32_bf16 v[4:7], v[156:159], v[208:211], v[4:7]
	v_mfma_f32_16x16x32_bf16 v[0:3], v[170:173], v[208:211], v[0:3]
	v_mfma_f32_16x16x32_bf16 v[52:55], v[160:163], v[188:191], v[52:55]
	v_mfma_f32_16x16x32_bf16 v[44:47], v[178:181], v[188:191], v[44:47]
	v_mfma_f32_16x16x32_bf16 v[36:39], v[160:163], v[196:199], v[36:39]
	v_mfma_f32_16x16x32_bf16 v[32:35], v[178:181], v[196:199], v[32:35]
	v_mfma_f32_16x16x32_bf16 v[20:23], v[160:163], v[204:207], v[20:23]
	v_mfma_f32_16x16x32_bf16 v[12:15], v[178:181], v[204:207], v[12:15]
	v_mfma_f32_16x16x32_bf16 v[4:7], v[160:163], v[212:215], v[4:7]
	v_mfma_f32_16x16x32_bf16 v[0:3], v[178:181], v[212:215], v[0:3]
	s_setprio 0
	s_barrier
	s_add_i32 s12, 0, 0x18000
	s_add_i32 s13, 0, 0x1c000
	v_add_u32_e32 v152, s12, v166
	v_add_u32_e32 v168, s13, v166
	ds_read_b128 v[128:131], v152
	ds_read_b128 v[132:135], v152 offset:1024
	ds_read_b128 v[148:151], v152 offset:2048
	ds_read_b128 v[152:155], v152 offset:3072
	ds_read_b128 v[156:159], v168
	ds_read_b128 v[160:163], v168 offset:1024
	ds_read_b128 v[170:173], v168 offset:2048
	ds_read_b128 v[178:181], v168 offset:3072
	s_add_u32 s42, s82, 0x160000
	s_addc_u32 s43, s83, 0
	s_mov_b32 m0, s18
	ds_read_b128 v[184:187], v183 offset:32768
	ds_read_b128 v[188:191], v183 offset:33792
	ds_read_b128 v[192:195], v183 offset:34816
	ds_read_b128 v[196:199], v183 offset:35840
	ds_read_b128 v[200:203], v183 offset:36864
	ds_read_b128 v[204:207], v183 offset:37888
	ds_read_b128 v[208:211], v183 offset:38912
	ds_read_b128 v[212:215], v183 offset:39936
	global_load_lds_dwordx4 v136, s[42:43]
	s_mov_b32 m0, s19
	s_nop 0
	global_load_lds_dwordx4 v140, s[42:43]
	s_waitcnt vmcnt(8)
	s_waitcnt lgkmcnt(0)
	s_barrier
	s_setprio 1
	s_waitcnt lgkmcnt(0)
	v_mfma_f32_16x16x32_bf16 v[124:127], v[128:131], v[184:187], v[124:127]
	v_mfma_f32_16x16x32_bf16 v[120:123], v[148:151], v[184:187], v[120:123]
	v_mfma_f32_16x16x32_bf16 v[112:115], v[128:131], v[192:195], v[112:115]
	v_mfma_f32_16x16x32_bf16 v[104:107], v[148:151], v[192:195], v[104:107]
	v_mfma_f32_16x16x32_bf16 v[92:95], v[128:131], v[200:203], v[92:95]
	v_mfma_f32_16x16x32_bf16 v[88:91], v[148:151], v[200:203], v[88:91]
	v_mfma_f32_16x16x32_bf16 v[80:83], v[128:131], v[208:211], v[80:83]
	v_mfma_f32_16x16x32_bf16 v[72:75], v[148:151], v[208:211], v[72:75]
	v_mfma_f32_16x16x32_bf16 v[124:127], v[132:135], v[188:191], v[124:127]
	v_mfma_f32_16x16x32_bf16 v[120:123], v[152:155], v[188:191], v[120:123]
	v_mfma_f32_16x16x32_bf16 v[112:115], v[132:135], v[196:199], v[112:115]
	v_mfma_f32_16x16x32_bf16 v[104:107], v[152:155], v[196:199], v[104:107]
	v_mfma_f32_16x16x32_bf16 v[92:95], v[132:135], v[204:207], v[92:95]
	v_mfma_f32_16x16x32_bf16 v[88:91], v[152:155], v[204:207], v[88:91]
	v_mfma_f32_16x16x32_bf16 v[80:83], v[132:135], v[212:215], v[80:83]
	v_mfma_f32_16x16x32_bf16 v[72:75], v[152:155], v[212:215], v[72:75]
	s_setprio 0
	s_setprio 1
	v_mfma_f32_16x16x32_bf16 v[116:119], v[156:159], v[184:187], v[116:119]
	v_mfma_f32_16x16x32_bf16 v[108:111], v[170:173], v[184:187], v[108:111]
	v_mfma_f32_16x16x32_bf16 v[100:103], v[156:159], v[192:195], v[100:103]
	v_mfma_f32_16x16x32_bf16 v[96:99], v[170:173], v[192:195], v[96:99]
	v_mfma_f32_16x16x32_bf16 v[84:87], v[156:159], v[200:203], v[84:87]
	v_mfma_f32_16x16x32_bf16 v[76:79], v[170:173], v[200:203], v[76:79]
	v_mfma_f32_16x16x32_bf16 v[68:71], v[156:159], v[208:211], v[68:71]
	v_mfma_f32_16x16x32_bf16 v[64:67], v[170:173], v[208:211], v[64:67]
	v_mfma_f32_16x16x32_bf16 v[116:119], v[160:163], v[188:191], v[116:119]
	v_mfma_f32_16x16x32_bf16 v[108:111], v[178:181], v[188:191], v[108:111]
	v_mfma_f32_16x16x32_bf16 v[100:103], v[160:163], v[196:199], v[100:103]
	v_mfma_f32_16x16x32_bf16 v[96:99], v[178:181], v[196:199], v[96:99]
	v_mfma_f32_16x16x32_bf16 v[84:87], v[160:163], v[204:207], v[84:87]
	v_mfma_f32_16x16x32_bf16 v[76:79], v[178:181], v[204:207], v[76:79]
	v_mfma_f32_16x16x32_bf16 v[68:71], v[160:163], v[212:215], v[68:71]
	v_mfma_f32_16x16x32_bf16 v[64:67], v[178:181], v[212:215], v[64:67]
	s_setprio 0
	s_barrier
	s_add_i32 s12, s12, s8
	s_mov_b32 m0, s12
	ds_read_b128 v[184:187], v183 offset:49152
	ds_read_b128 v[188:191], v183 offset:50176
	ds_read_b128 v[192:195], v183 offset:51200
	ds_read_b128 v[196:199], v183 offset:52224
	ds_read_b128 v[200:203], v183 offset:53248
	ds_read_b128 v[204:207], v183 offset:54272
	ds_read_b128 v[208:211], v183 offset:55296
	ds_read_b128 v[212:215], v183 offset:56320
	s_add_u32 s100, s80, s38
	s_addc_u32 s101, s81, s39
	global_load_lds_dwordx4 v138, s[100:101]
	s_add_i32 m0, s12, 0x2000
	s_add_u32 s42, s80, 0x15ff80
	s_addc_u32 s43, s81, 0
	s_add_i32 s12, s13, s8
	global_load_lds_dwordx4 v142, s[100:101]
	s_mov_b32 m0, s12
	s_nop 0
	global_load_lds_dwordx4 v138, s[42:43]
	s_add_i32 m0, s12, 0x2000
	s_nop 0
	global_load_lds_dwordx4 v142, s[42:43]
	s_mov_b32 m0, s20
	s_nop 0
	s_add_u32 s100, s82, s38
	s_addc_u32 s101, s83, s39
	global_load_lds_dwordx4 v136, s[100:101]
	s_mov_b32 m0, s21
	s_nop 0
	global_load_lds_dwordx4 v140, s[100:101]
	s_waitcnt vmcnt(8)
	s_waitcnt lgkmcnt(0)
	s_barrier
	s_setprio 1
	s_waitcnt lgkmcnt(0)
	v_mfma_f32_16x16x32_bf16 v[60:63], v[128:131], v[184:187], v[60:63]
	v_mfma_f32_16x16x32_bf16 v[56:59], v[148:151], v[184:187], v[56:59]
	v_mfma_f32_16x16x32_bf16 v[48:51], v[128:131], v[192:195], v[48:51]
	v_mfma_f32_16x16x32_bf16 v[40:43], v[148:151], v[192:195], v[40:43]
	v_mfma_f32_16x16x32_bf16 v[28:31], v[128:131], v[200:203], v[28:31]
	v_mfma_f32_16x16x32_bf16 v[24:27], v[148:151], v[200:203], v[24:27]
	v_mfma_f32_16x16x32_bf16 v[16:19], v[128:131], v[208:211], v[16:19]
	v_mfma_f32_16x16x32_bf16 v[8:11], v[148:151], v[208:211], v[8:11]
	v_mfma_f32_16x16x32_bf16 v[60:63], v[132:135], v[188:191], v[60:63]
	v_mfma_f32_16x16x32_bf16 v[56:59], v[152:155], v[188:191], v[56:59]
	v_mfma_f32_16x16x32_bf16 v[48:51], v[132:135], v[196:199], v[48:51]
	v_mfma_f32_16x16x32_bf16 v[40:43], v[152:155], v[196:199], v[40:43]
	v_mfma_f32_16x16x32_bf16 v[28:31], v[132:135], v[204:207], v[28:31]
	v_mfma_f32_16x16x32_bf16 v[24:27], v[152:155], v[204:207], v[24:27]
	v_mfma_f32_16x16x32_bf16 v[16:19], v[132:135], v[212:215], v[16:19]
	v_mfma_f32_16x16x32_bf16 v[8:11], v[152:155], v[212:215], v[8:11]
	s_setprio 0
	s_setprio 1
	v_mfma_f32_16x16x32_bf16 v[52:55], v[156:159], v[184:187], v[52:55]
	v_mfma_f32_16x16x32_bf16 v[44:47], v[170:173], v[184:187], v[44:47]
	v_mfma_f32_16x16x32_bf16 v[36:39], v[156:159], v[192:195], v[36:39]
	v_mfma_f32_16x16x32_bf16 v[32:35], v[170:173], v[192:195], v[32:35]
	v_mfma_f32_16x16x32_bf16 v[20:23], v[156:159], v[200:203], v[20:23]
	v_mfma_f32_16x16x32_bf16 v[12:15], v[170:173], v[200:203], v[12:15]
	v_mfma_f32_16x16x32_bf16 v[4:7], v[156:159], v[208:211], v[4:7]
	v_mfma_f32_16x16x32_bf16 v[0:3], v[170:173], v[208:211], v[0:3]
	v_mfma_f32_16x16x32_bf16 v[52:55], v[160:163], v[188:191], v[52:55]
	v_mfma_f32_16x16x32_bf16 v[44:47], v[178:181], v[188:191], v[44:47]
	v_mfma_f32_16x16x32_bf16 v[36:39], v[160:163], v[196:199], v[36:39]
	v_mfma_f32_16x16x32_bf16 v[32:35], v[178:181], v[196:199], v[32:35]
	v_mfma_f32_16x16x32_bf16 v[20:23], v[160:163], v[204:207], v[20:23]
	v_mfma_f32_16x16x32_bf16 v[12:15], v[178:181], v[204:207], v[12:15]
	v_mfma_f32_16x16x32_bf16 v[4:7], v[160:163], v[212:215], v[4:7]
	v_mfma_f32_16x16x32_bf16 v[0:3], v[178:181], v[212:215], v[0:3]
	s_setprio 0
	s_barrier
	s_add_i32 s3, s3, 2
	s_add_u32 s2, s2, 0xffffff00
	s_addc_u32 s30, s30, -1
	s_cmpk_gt_u32 s3, 0x55
	s_mov_b64 s[76:77], s[78:79]
	s_cbranch_scc0 .LBB0_313
	s_and_b64 vcc, exec, s[72:73]
	s_cbranch_vccz .LBB0_316
	s_barrier

.LBB0_343:
	s_add_u32 s78, s76, 0xffffff00
	s_addc_u32 s79, s77, -1
	s_add_i32 s12, 0, 0x10000
	s_cmpk_eq_i32 s3, 0x54
	s_cselect_b32 s83, s7, s79
	s_cselect_b32 s82, s6, s78
	s_cselect_b32 s81, s75, s30
	s_cselect_b32 s80, s74, s2
	s_add_i32 s13, 0, 0x14000
	v_add_u32_e32 v140, s12, v233
	v_add_u32_e32 v156, s13, v233
	ds_read_b128 v[128:131], v140
	ds_read_b128 v[132:135], v140 offset:1024
	ds_read_b128 v[136:139], v140 offset:2048
	ds_read_b128 v[140:143], v140 offset:3072
	ds_read_b128 v[144:147], v156
	ds_read_b128 v[148:151], v156 offset:1024
	ds_read_b128 v[152:155], v156 offset:2048
	ds_read_b128 v[156:159], v156 offset:3072
	s_add_i32 m0, s9, 0xc000
	ds_read_b128 v[160:163], v236
	ds_read_b128 v[164:167], v236 offset:1024
	ds_read_b128 v[194:197], v236 offset:2048
	ds_read_b128 v[198:201], v236 offset:3072
	ds_read_b128 v[202:205], v236 offset:4096
	ds_read_b128 v[206:209], v236 offset:5120
	ds_read_b128 v[210:213], v236 offset:6144
	ds_read_b128 v[214:217], v236 offset:7168
	global_load_lds_dwordx4 v190, s[76:77]
	s_add_i32 m0, s9, 0xe000
	s_nop 0
	global_load_lds_dwordx4 v192, s[76:77]
	s_waitcnt vmcnt(8)
	s_waitcnt lgkmcnt(0)
	s_barrier
	s_setprio 1
	s_waitcnt lgkmcnt(0)
	v_mfma_f32_16x16x32_bf16 v[124:127], v[128:131], v[160:163], v[124:127]
	v_mfma_f32_16x16x32_bf16 v[120:123], v[136:139], v[160:163], v[120:123]
	v_mfma_f32_16x16x32_bf16 v[108:111], v[128:131], v[194:197], v[108:111]
	v_mfma_f32_16x16x32_bf16 v[104:107], v[136:139], v[194:197], v[104:107]
	v_mfma_f32_16x16x32_bf16 v[100:103], v[128:131], v[202:205], v[100:103]
	v_mfma_f32_16x16x32_bf16 v[92:95], v[136:139], v[202:205], v[92:95]
	v_mfma_f32_16x16x32_bf16 v[84:87], v[128:131], v[210:213], v[84:87]
	v_mfma_f32_16x16x32_bf16 v[76:79], v[136:139], v[210:213], v[76:79]
	v_mfma_f32_16x16x32_bf16 v[124:127], v[132:135], v[164:167], v[124:127]
	v_mfma_f32_16x16x32_bf16 v[120:123], v[140:143], v[164:167], v[120:123]
	v_mfma_f32_16x16x32_bf16 v[108:111], v[132:135], v[198:201], v[108:111]
	v_mfma_f32_16x16x32_bf16 v[104:107], v[140:143], v[198:201], v[104:107]
	v_mfma_f32_16x16x32_bf16 v[100:103], v[132:135], v[206:209], v[100:103]
	v_mfma_f32_16x16x32_bf16 v[92:95], v[140:143], v[206:209], v[92:95]
	v_mfma_f32_16x16x32_bf16 v[84:87], v[132:135], v[214:217], v[84:87]
	v_mfma_f32_16x16x32_bf16 v[76:79], v[140:143], v[214:217], v[76:79]
	s_setprio 0
	s_setprio 1
	v_mfma_f32_16x16x32_bf16 v[116:119], v[144:147], v[160:163], v[116:119]
	v_mfma_f32_16x16x32_bf16 v[112:115], v[152:155], v[160:163], v[112:115]
	v_mfma_f32_16x16x32_bf16 v[96:99], v[144:147], v[194:197], v[96:99]
	v_mfma_f32_16x16x32_bf16 v[88:91], v[152:155], v[194:197], v[88:91]
	v_mfma_f32_16x16x32_bf16 v[80:83], v[144:147], v[202:205], v[80:83]
	v_mfma_f32_16x16x32_bf16 v[72:75], v[152:155], v[202:205], v[72:75]
	v_mfma_f32_16x16x32_bf16 v[68:71], v[144:147], v[210:213], v[68:71]
	v_mfma_f32_16x16x32_bf16 v[64:67], v[152:155], v[210:213], v[64:67]
	v_mfma_f32_16x16x32_bf16 v[116:119], v[148:151], v[164:167], v[116:119]
	v_mfma_f32_16x16x32_bf16 v[112:115], v[156:159], v[164:167], v[112:115]
	v_mfma_f32_16x16x32_bf16 v[96:99], v[148:151], v[198:201], v[96:99]
	v_mfma_f32_16x16x32_bf16 v[88:91], v[156:159], v[198:201], v[88:91]
	v_mfma_f32_16x16x32_bf16 v[80:83], v[148:151], v[206:209], v[80:83]
	v_mfma_f32_16x16x32_bf16 v[72:75], v[156:159], v[206:209], v[72:75]
	v_mfma_f32_16x16x32_bf16 v[68:71], v[148:151], v[214:217], v[68:71]
	v_mfma_f32_16x16x32_bf16 v[64:67], v[156:159], v[214:217], v[64:67]
	s_setprio 0
	s_barrier
	s_add_i32 s12, s12, s8
	s_mov_b32 m0, s12
	ds_read_b128 v[160:163], v236 offset:16384
	ds_read_b128 v[164:167], v236 offset:17408
	ds_read_b128 v[194:197], v236 offset:18432
	ds_read_b128 v[198:201], v236 offset:19456
	ds_read_b128 v[202:205], v236 offset:20480
	ds_read_b128 v[206:209], v236 offset:21504
	ds_read_b128 v[210:213], v236 offset:22528
	ds_read_b128 v[214:217], v236 offset:23552
	global_load_lds_dwordx4 v184, s[80:81]
	s_add_i32 m0, s12, 0x2000
	s_add_u32 s42, s80, 0x160000
	s_addc_u32 s43, s81, 0
	s_add_i32 s12, s13, s8
	global_load_lds_dwordx4 v188, s[80:81]
	s_mov_b32 m0, s12
	s_nop 0
	global_load_lds_dwordx4 v184, s[42:43]
	s_add_i32 m0, s12, 0x2000
	s_nop 0
	global_load_lds_dwordx4 v188, s[42:43]
	s_mov_b32 m0, s9
	s_nop 0
	global_load_lds_dwordx4 v182, s[82:83]
	s_mov_b32 m0, s10
	s_nop 0
	global_load_lds_dwordx4 v186, s[82:83]
	s_waitcnt vmcnt(8)
	s_waitcnt lgkmcnt(0)
	s_barrier
	s_setprio 1
	s_waitcnt lgkmcnt(0)
	v_mfma_f32_16x16x32_bf16 v[60:63], v[128:131], v[160:163], v[60:63]
	v_mfma_f32_16x16x32_bf16 v[56:59], v[136:139], v[160:163], v[56:59]
	v_mfma_f32_16x16x32_bf16 v[52:55], v[128:131], v[194:197], v[52:55]
	v_mfma_f32_16x16x32_bf16 v[44:47], v[136:139], v[194:197], v[44:47]
	v_mfma_f32_16x16x32_bf16 v[36:39], v[128:131], v[202:205], v[36:39]
	v_mfma_f32_16x16x32_bf16 v[28:31], v[136:139], v[202:205], v[28:31]
	v_mfma_f32_16x16x32_bf16 v[20:23], v[128:131], v[210:213], v[20:23]
	v_mfma_f32_16x16x32_bf16 v[12:15], v[136:139], v[210:213], v[12:15]
	v_mfma_f32_16x16x32_bf16 v[60:63], v[132:135], v[164:167], v[60:63]
	v_mfma_f32_16x16x32_bf16 v[56:59], v[140:143], v[164:167], v[56:59]
	v_mfma_f32_16x16x32_bf16 v[52:55], v[132:135], v[198:201], v[52:55]
	v_mfma_f32_16x16x32_bf16 v[44:47], v[140:143], v[198:201], v[44:47]
	v_mfma_f32_16x16x32_bf16 v[36:39], v[132:135], v[206:209], v[36:39]
	v_mfma_f32_16x16x32_bf16 v[28:31], v[140:143], v[206:209], v[28:31]
	v_mfma_f32_16x16x32_bf16 v[20:23], v[132:135], v[214:217], v[20:23]
	v_mfma_f32_16x16x32_bf16 v[12:15], v[140:143], v[214:217], v[12:15]
	s_setprio 0
	s_setprio 1
	v_mfma_f32_16x16x32_bf16 v[48:51], v[144:147], v[160:163], v[48:51]
	v_mfma_f32_16x16x32_bf16 v[40:43], v[152:155], v[160:163], v[40:43]
	v_mfma_f32_16x16x32_bf16 v[32:35], v[144:147], v[194:197], v[32:35]
	v_mfma_f32_16x16x32_bf16 v[24:27], v[152:155], v[194:197], v[24:27]
	v_mfma_f32_16x16x32_bf16 v[16:19], v[144:147], v[202:205], v[16:19]
	v_mfma_f32_16x16x32_bf16 v[8:11], v[152:155], v[202:205], v[8:11]
	v_mfma_f32_16x16x32_bf16 v[4:7], v[144:147], v[210:213], v[4:7]
	v_mfma_f32_16x16x32_bf16 v[0:3], v[152:155], v[210:213], v[0:3]
	v_mfma_f32_16x16x32_bf16 v[48:51], v[148:151], v[164:167], v[48:51]
	v_mfma_f32_16x16x32_bf16 v[40:43], v[156:159], v[164:167], v[40:43]
	v_mfma_f32_16x16x32_bf16 v[32:35], v[148:151], v[198:201], v[32:35]
	v_mfma_f32_16x16x32_bf16 v[24:27], v[156:159], v[198:201], v[24:27]
	v_mfma_f32_16x16x32_bf16 v[16:19], v[148:151], v[206:209], v[16:19]
	v_mfma_f32_16x16x32_bf16 v[8:11], v[156:159], v[206:209], v[8:11]
	v_mfma_f32_16x16x32_bf16 v[4:7], v[148:151], v[214:217], v[4:7]
	v_mfma_f32_16x16x32_bf16 v[0:3], v[156:159], v[214:217], v[0:3]
	s_setprio 0
	s_barrier
	s_add_i32 s12, 0, 0x18000
	s_add_i32 s13, 0, 0x1c000
	v_add_u32_e32 v140, s12, v233
	v_add_u32_e32 v156, s13, v233
	ds_read_b128 v[128:131], v140
	ds_read_b128 v[132:135], v140 offset:1024
	ds_read_b128 v[136:139], v140 offset:2048
	ds_read_b128 v[140:143], v140 offset:3072
	ds_read_b128 v[144:147], v156
	ds_read_b128 v[148:151], v156 offset:1024
	ds_read_b128 v[152:155], v156 offset:2048
	ds_read_b128 v[156:159], v156 offset:3072
	s_add_u32 s42, s82, 0x160000
	s_addc_u32 s43, s83, 0
	s_mov_b32 m0, s18
	ds_read_b128 v[160:163], v236 offset:32768
	ds_read_b128 v[164:167], v236 offset:33792
	ds_read_b128 v[194:197], v236 offset:34816
	ds_read_b128 v[198:201], v236 offset:35840
	ds_read_b128 v[202:205], v236 offset:36864
	ds_read_b128 v[206:209], v236 offset:37888
	ds_read_b128 v[210:213], v236 offset:38912
	ds_read_b128 v[214:217], v236 offset:39936
	global_load_lds_dwordx4 v182, s[42:43]
	s_mov_b32 m0, s19
	s_nop 0
	global_load_lds_dwordx4 v186, s[42:43]
	s_waitcnt vmcnt(8)
	s_waitcnt lgkmcnt(0)
	s_barrier
	s_setprio 1
	s_waitcnt lgkmcnt(0)
	v_mfma_f32_16x16x32_bf16 v[124:127], v[128:131], v[160:163], v[124:127]
	v_mfma_f32_16x16x32_bf16 v[120:123], v[136:139], v[160:163], v[120:123]
	v_mfma_f32_16x16x32_bf16 v[108:111], v[128:131], v[194:197], v[108:111]
	v_mfma_f32_16x16x32_bf16 v[104:107], v[136:139], v[194:197], v[104:107]
	v_mfma_f32_16x16x32_bf16 v[100:103], v[128:131], v[202:205], v[100:103]
	v_mfma_f32_16x16x32_bf16 v[92:95], v[136:139], v[202:205], v[92:95]
	v_mfma_f32_16x16x32_bf16 v[84:87], v[128:131], v[210:213], v[84:87]
	v_mfma_f32_16x16x32_bf16 v[76:79], v[136:139], v[210:213], v[76:79]
	v_mfma_f32_16x16x32_bf16 v[124:127], v[132:135], v[164:167], v[124:127]
	v_mfma_f32_16x16x32_bf16 v[120:123], v[140:143], v[164:167], v[120:123]
	v_mfma_f32_16x16x32_bf16 v[108:111], v[132:135], v[198:201], v[108:111]
	v_mfma_f32_16x16x32_bf16 v[104:107], v[140:143], v[198:201], v[104:107]
	v_mfma_f32_16x16x32_bf16 v[100:103], v[132:135], v[206:209], v[100:103]
	v_mfma_f32_16x16x32_bf16 v[92:95], v[140:143], v[206:209], v[92:95]
	v_mfma_f32_16x16x32_bf16 v[84:87], v[132:135], v[214:217], v[84:87]
	v_mfma_f32_16x16x32_bf16 v[76:79], v[140:143], v[214:217], v[76:79]
	s_setprio 0
	s_setprio 1
	v_mfma_f32_16x16x32_bf16 v[116:119], v[144:147], v[160:163], v[116:119]
	v_mfma_f32_16x16x32_bf16 v[112:115], v[152:155], v[160:163], v[112:115]
	v_mfma_f32_16x16x32_bf16 v[96:99], v[144:147], v[194:197], v[96:99]
	v_mfma_f32_16x16x32_bf16 v[88:91], v[152:155], v[194:197], v[88:91]
	v_mfma_f32_16x16x32_bf16 v[80:83], v[144:147], v[202:205], v[80:83]
	v_mfma_f32_16x16x32_bf16 v[72:75], v[152:155], v[202:205], v[72:75]
	v_mfma_f32_16x16x32_bf16 v[68:71], v[144:147], v[210:213], v[68:71]
	v_mfma_f32_16x16x32_bf16 v[64:67], v[152:155], v[210:213], v[64:67]
	v_mfma_f32_16x16x32_bf16 v[116:119], v[148:151], v[164:167], v[116:119]
	v_mfma_f32_16x16x32_bf16 v[112:115], v[156:159], v[164:167], v[112:115]
	v_mfma_f32_16x16x32_bf16 v[96:99], v[148:151], v[198:201], v[96:99]
	v_mfma_f32_16x16x32_bf16 v[88:91], v[156:159], v[198:201], v[88:91]
	v_mfma_f32_16x16x32_bf16 v[80:83], v[148:151], v[206:209], v[80:83]
	v_mfma_f32_16x16x32_bf16 v[72:75], v[156:159], v[206:209], v[72:75]
	v_mfma_f32_16x16x32_bf16 v[68:71], v[148:151], v[214:217], v[68:71]
	v_mfma_f32_16x16x32_bf16 v[64:67], v[156:159], v[214:217], v[64:67]
	s_setprio 0
	s_barrier
	s_add_i32 s12, s12, s8
	s_mov_b32 m0, s12
	ds_read_b128 v[160:163], v236 offset:49152
	ds_read_b128 v[164:167], v236 offset:50176
	ds_read_b128 v[194:197], v236 offset:51200
	ds_read_b128 v[198:201], v236 offset:52224
	ds_read_b128 v[202:205], v236 offset:53248
	ds_read_b128 v[206:209], v236 offset:54272
	ds_read_b128 v[210:213], v236 offset:55296
	ds_read_b128 v[214:217], v236 offset:56320
	s_add_u32 s100, s80, s38
	s_addc_u32 s101, s81, s39
	global_load_lds_dwordx4 v184, s[100:101]
	s_add_i32 m0, s12, 0x2000
	s_add_u32 s42, s80, 0x15ff80
	s_addc_u32 s43, s81, 0
	s_add_i32 s12, s13, s8
	global_load_lds_dwordx4 v188, s[100:101]
	s_mov_b32 m0, s12
	s_nop 0
	global_load_lds_dwordx4 v184, s[42:43]
	s_add_i32 m0, s12, 0x2000
	s_nop 0
	global_load_lds_dwordx4 v188, s[42:43]
	s_mov_b32 m0, s20
	s_nop 0
	s_add_u32 s100, s82, s38
	s_addc_u32 s101, s83, s39
	global_load_lds_dwordx4 v182, s[100:101]
	s_mov_b32 m0, s21
	s_nop 0
	global_load_lds_dwordx4 v186, s[100:101]
	s_waitcnt vmcnt(8)
	s_waitcnt lgkmcnt(0)
	s_barrier
	s_setprio 1
	s_waitcnt lgkmcnt(0)
	v_mfma_f32_16x16x32_bf16 v[60:63], v[128:131], v[160:163], v[60:63]
	v_mfma_f32_16x16x32_bf16 v[56:59], v[136:139], v[160:163], v[56:59]
	v_mfma_f32_16x16x32_bf16 v[52:55], v[128:131], v[194:197], v[52:55]
	v_mfma_f32_16x16x32_bf16 v[44:47], v[136:139], v[194:197], v[44:47]
	v_mfma_f32_16x16x32_bf16 v[36:39], v[128:131], v[202:205], v[36:39]
	v_mfma_f32_16x16x32_bf16 v[28:31], v[136:139], v[202:205], v[28:31]
	v_mfma_f32_16x16x32_bf16 v[20:23], v[128:131], v[210:213], v[20:23]
	v_mfma_f32_16x16x32_bf16 v[12:15], v[136:139], v[210:213], v[12:15]
	v_mfma_f32_16x16x32_bf16 v[60:63], v[132:135], v[164:167], v[60:63]
	v_mfma_f32_16x16x32_bf16 v[56:59], v[140:143], v[164:167], v[56:59]
	v_mfma_f32_16x16x32_bf16 v[52:55], v[132:135], v[198:201], v[52:55]
	v_mfma_f32_16x16x32_bf16 v[44:47], v[140:143], v[198:201], v[44:47]
	v_mfma_f32_16x16x32_bf16 v[36:39], v[132:135], v[206:209], v[36:39]
	v_mfma_f32_16x16x32_bf16 v[28:31], v[140:143], v[206:209], v[28:31]
	v_mfma_f32_16x16x32_bf16 v[20:23], v[132:135], v[214:217], v[20:23]
	v_mfma_f32_16x16x32_bf16 v[12:15], v[140:143], v[214:217], v[12:15]
	s_setprio 0
	s_setprio 1
	v_mfma_f32_16x16x32_bf16 v[48:51], v[144:147], v[160:163], v[48:51]
	v_mfma_f32_16x16x32_bf16 v[40:43], v[152:155], v[160:163], v[40:43]
	v_mfma_f32_16x16x32_bf16 v[32:35], v[144:147], v[194:197], v[32:35]
	v_mfma_f32_16x16x32_bf16 v[24:27], v[152:155], v[194:197], v[24:27]
	v_mfma_f32_16x16x32_bf16 v[16:19], v[144:147], v[202:205], v[16:19]
	v_mfma_f32_16x16x32_bf16 v[8:11], v[152:155], v[202:205], v[8:11]
	v_mfma_f32_16x16x32_bf16 v[4:7], v[144:147], v[210:213], v[4:7]
	v_mfma_f32_16x16x32_bf16 v[0:3], v[152:155], v[210:213], v[0:3]
	v_mfma_f32_16x16x32_bf16 v[48:51], v[148:151], v[164:167], v[48:51]
	v_mfma_f32_16x16x32_bf16 v[40:43], v[156:159], v[164:167], v[40:43]
	v_mfma_f32_16x16x32_bf16 v[32:35], v[148:151], v[198:201], v[32:35]
	v_mfma_f32_16x16x32_bf16 v[24:27], v[156:159], v[198:201], v[24:27]
	v_mfma_f32_16x16x32_bf16 v[16:19], v[148:151], v[206:209], v[16:19]
	v_mfma_f32_16x16x32_bf16 v[8:11], v[156:159], v[206:209], v[8:11]
	v_mfma_f32_16x16x32_bf16 v[4:7], v[148:151], v[214:217], v[4:7]
	v_mfma_f32_16x16x32_bf16 v[0:3], v[156:159], v[214:217], v[0:3]
	s_setprio 0
	s_barrier
	s_add_i32 s3, s3, 2
	s_add_u32 s2, s2, 0xffffff00
	s_addc_u32 s30, s30, -1
	s_cmpk_gt_u32 s3, 0x55
	s_mov_b64 s[76:77], s[78:79]
	s_cbranch_scc0 .LBB0_343
	v_mov_b64_e32 v[234:235], 0x7f
	v_mov_b64_e32 v[174:175], 0x80
	v_mov_b64_e32 v[226:227], 0xb00
	s_and_b64 vcc, exec, s[72:73]
	s_cbranch_vccz .LBB0_346
	s_barrier

.LBB0_490:
	s_add_u32 s3, s86, 0xfff80080
	s_addc_u32 s12, s87, -1
	s_add_i32 s13, 0, 0x10000
	s_cmp_eq_u32 s2, 28
	s_cselect_b32 s91, s23, s12
	s_cselect_b32 s90, s25, s3
	s_cselect_b32 s89, s28, s40
	s_cselect_b32 s88, s30, s33
	s_add_i32 s3, 0, 0x14000
	v_add_u32_e32 v156, s13, v141
	v_add_u32_e32 v168, s3, v141
	ds_read_b128 v[144:147], v156
	ds_read_b128 v[148:151], v156 offset:1024
	ds_read_b128 v[152:155], v156 offset:2048
	ds_read_b128 v[156:159], v156 offset:3072
	ds_read_b128 v[160:163], v168
	ds_read_b128 v[164:167], v168 offset:1024
	ds_read_b128 v[170:173], v168 offset:2048
	ds_read_b128 v[178:181], v168 offset:3072
	s_add_i32 m0, s9, 0xc000
	ds_read_b128 v[182:185], v143
	ds_read_b128 v[186:189], v143 offset:1024
	ds_read_b128 v[190:193], v143 offset:2048
	ds_read_b128 v[194:197], v143 offset:3072
	ds_read_b128 v[198:201], v143 offset:4096
	ds_read_b128 v[202:205], v143 offset:5120
	ds_read_b128 v[206:209], v143 offset:6144
	ds_read_b128 v[210:213], v143 offset:7168
	global_load_lds_dwordx4 v136, s[86:87]
	s_add_i32 m0, s9, 0xe000
	s_nop 0
	global_load_lds_dwordx4 v138, s[86:87]
	s_waitcnt vmcnt(8)
	s_waitcnt lgkmcnt(0)
	s_barrier
	s_setprio 1
	s_waitcnt lgkmcnt(0)
	v_mfma_f32_16x16x32_bf16 v[124:127], v[144:147], v[182:185], v[124:127]
	v_mfma_f32_16x16x32_bf16 v[120:123], v[152:155], v[182:185], v[120:123]
	v_mfma_f32_16x16x32_bf16 v[116:119], v[144:147], v[190:193], v[116:119]
	v_mfma_f32_16x16x32_bf16 v[112:115], v[152:155], v[190:193], v[112:115]
	v_mfma_f32_16x16x32_bf16 v[100:103], v[144:147], v[198:201], v[100:103]
	v_mfma_f32_16x16x32_bf16 v[96:99], v[152:155], v[198:201], v[96:99]
	v_mfma_f32_16x16x32_bf16 v[84:87], v[144:147], v[206:209], v[84:87]
	v_mfma_f32_16x16x32_bf16 v[80:83], v[152:155], v[206:209], v[80:83]
	v_mfma_f32_16x16x32_bf16 v[124:127], v[148:151], v[186:189], v[124:127]
	v_mfma_f32_16x16x32_bf16 v[120:123], v[156:159], v[186:189], v[120:123]
	v_mfma_f32_16x16x32_bf16 v[116:119], v[148:151], v[194:197], v[116:119]
	v_mfma_f32_16x16x32_bf16 v[112:115], v[156:159], v[194:197], v[112:115]
	v_mfma_f32_16x16x32_bf16 v[100:103], v[148:151], v[202:205], v[100:103]
	v_mfma_f32_16x16x32_bf16 v[96:99], v[156:159], v[202:205], v[96:99]
	v_mfma_f32_16x16x32_bf16 v[84:87], v[148:151], v[210:213], v[84:87]
	v_mfma_f32_16x16x32_bf16 v[80:83], v[156:159], v[210:213], v[80:83]
	s_setprio 0
	s_setprio 1
	v_mfma_f32_16x16x32_bf16 v[108:111], v[160:163], v[182:185], v[108:111]
	v_mfma_f32_16x16x32_bf16 v[104:107], v[170:173], v[182:185], v[104:107]
	v_mfma_f32_16x16x32_bf16 v[92:95], v[160:163], v[190:193], v[92:95]
	v_mfma_f32_16x16x32_bf16 v[88:91], v[170:173], v[190:193], v[88:91]
	v_mfma_f32_16x16x32_bf16 v[76:79], v[160:163], v[198:201], v[76:79]
	v_mfma_f32_16x16x32_bf16 v[72:75], v[170:173], v[198:201], v[72:75]
	v_mfma_f32_16x16x32_bf16 v[68:71], v[160:163], v[206:209], v[68:71]
	v_mfma_f32_16x16x32_bf16 v[64:67], v[170:173], v[206:209], v[64:67]
	v_mfma_f32_16x16x32_bf16 v[108:111], v[164:167], v[186:189], v[108:111]
	v_mfma_f32_16x16x32_bf16 v[104:107], v[178:181], v[186:189], v[104:107]
	v_mfma_f32_16x16x32_bf16 v[92:95], v[164:167], v[194:197], v[92:95]
	v_mfma_f32_16x16x32_bf16 v[88:91], v[178:181], v[194:197], v[88:91]
	v_mfma_f32_16x16x32_bf16 v[76:79], v[164:167], v[202:205], v[76:79]
	v_mfma_f32_16x16x32_bf16 v[72:75], v[178:181], v[202:205], v[72:75]
	v_mfma_f32_16x16x32_bf16 v[68:71], v[164:167], v[210:213], v[68:71]
	v_mfma_f32_16x16x32_bf16 v[64:67], v[178:181], v[210:213], v[64:67]
	s_setprio 0
	s_barrier
	s_add_i32 s12, s13, s8
	s_mov_b32 m0, s12
	ds_read_b128 v[182:185], v143 offset:16384
	ds_read_b128 v[186:189], v143 offset:17408
	ds_read_b128 v[190:193], v143 offset:18432
	ds_read_b128 v[194:197], v143 offset:19456
	ds_read_b128 v[198:201], v143 offset:20480
	ds_read_b128 v[202:205], v143 offset:21504
	ds_read_b128 v[206:209], v143 offset:22528
	ds_read_b128 v[210:213], v143 offset:23552
	global_load_lds_dwordx4 v130, s[88:89]
	s_add_i32 m0, s12, 0x2000
	s_add_u32 s42, s88, 0x80000
	s_addc_u32 s43, s89, 0
	s_add_i32 s3, s3, s8
	global_load_lds_dwordx4 v134, s[88:89]
	s_mov_b32 m0, s3
	s_nop 0
	global_load_lds_dwordx4 v130, s[42:43]
	s_add_i32 m0, s3, 0x2000
	s_nop 0
	global_load_lds_dwordx4 v134, s[42:43]
	s_mov_b32 m0, s9
	s_nop 0
	global_load_lds_dwordx4 v128, s[90:91]
	s_mov_b32 m0, s10
	s_nop 0
	global_load_lds_dwordx4 v132, s[90:91]
	s_waitcnt vmcnt(8)
	s_waitcnt lgkmcnt(0)
	s_barrier
	s_setprio 1
	s_waitcnt lgkmcnt(0)
	v_mfma_f32_16x16x32_bf16 v[60:63], v[144:147], v[182:185], v[60:63]
	v_mfma_f32_16x16x32_bf16 v[56:59], v[152:155], v[182:185], v[56:59]
	v_mfma_f32_16x16x32_bf16 v[52:55], v[144:147], v[190:193], v[52:55]
	v_mfma_f32_16x16x32_bf16 v[48:51], v[152:155], v[190:193], v[48:51]
	v_mfma_f32_16x16x32_bf16 v[36:39], v[144:147], v[198:201], v[36:39]
	v_mfma_f32_16x16x32_bf16 v[32:35], v[152:155], v[198:201], v[32:35]
	v_mfma_f32_16x16x32_bf16 v[20:23], v[144:147], v[206:209], v[20:23]
	v_mfma_f32_16x16x32_bf16 v[16:19], v[152:155], v[206:209], v[16:19]
	v_mfma_f32_16x16x32_bf16 v[60:63], v[148:151], v[186:189], v[60:63]
	v_mfma_f32_16x16x32_bf16 v[56:59], v[156:159], v[186:189], v[56:59]
	v_mfma_f32_16x16x32_bf16 v[52:55], v[148:151], v[194:197], v[52:55]
	v_mfma_f32_16x16x32_bf16 v[48:51], v[156:159], v[194:197], v[48:51]
	v_mfma_f32_16x16x32_bf16 v[36:39], v[148:151], v[202:205], v[36:39]
	v_mfma_f32_16x16x32_bf16 v[32:35], v[156:159], v[202:205], v[32:35]
	v_mfma_f32_16x16x32_bf16 v[20:23], v[148:151], v[210:213], v[20:23]
	v_mfma_f32_16x16x32_bf16 v[16:19], v[156:159], v[210:213], v[16:19]
	s_setprio 0
	s_setprio 1
	v_mfma_f32_16x16x32_bf16 v[44:47], v[160:163], v[182:185], v[44:47]
	v_mfma_f32_16x16x32_bf16 v[40:43], v[170:173], v[182:185], v[40:43]
	v_mfma_f32_16x16x32_bf16 v[28:31], v[160:163], v[190:193], v[28:31]
	v_mfma_f32_16x16x32_bf16 v[24:27], v[170:173], v[190:193], v[24:27]
	v_mfma_f32_16x16x32_bf16 v[12:15], v[160:163], v[198:201], v[12:15]
	v_mfma_f32_16x16x32_bf16 v[8:11], v[170:173], v[198:201], v[8:11]
	v_mfma_f32_16x16x32_bf16 v[4:7], v[160:163], v[206:209], v[4:7]
	v_mfma_f32_16x16x32_bf16 v[0:3], v[170:173], v[206:209], v[0:3]
	v_mfma_f32_16x16x32_bf16 v[44:47], v[164:167], v[186:189], v[44:47]
	v_mfma_f32_16x16x32_bf16 v[40:43], v[178:181], v[186:189], v[40:43]
	v_mfma_f32_16x16x32_bf16 v[28:31], v[164:167], v[194:197], v[28:31]
	v_mfma_f32_16x16x32_bf16 v[24:27], v[178:181], v[194:197], v[24:27]
	v_mfma_f32_16x16x32_bf16 v[12:15], v[164:167], v[202:205], v[12:15]
	v_mfma_f32_16x16x32_bf16 v[8:11], v[178:181], v[202:205], v[8:11]
	v_mfma_f32_16x16x32_bf16 v[4:7], v[164:167], v[210:213], v[4:7]
	v_mfma_f32_16x16x32_bf16 v[0:3], v[178:181], v[210:213], v[0:3]
	s_setprio 0
	s_barrier
	s_add_i32 s3, 0, 0x18000
	s_add_i32 s12, 0, 0x1c000
	v_add_u32_e32 v156, s3, v141
	v_add_u32_e32 v168, s12, v141
	ds_read_b128 v[144:147], v156
	ds_read_b128 v[148:151], v156 offset:1024
	ds_read_b128 v[152:155], v156 offset:2048
	ds_read_b128 v[156:159], v156 offset:3072
	ds_read_b128 v[160:163], v168
	ds_read_b128 v[164:167], v168 offset:1024
	ds_read_b128 v[170:173], v168 offset:2048
	ds_read_b128 v[178:181], v168 offset:3072
	s_add_u32 s42, s90, 0x80000
	s_addc_u32 s43, s91, 0
	s_mov_b32 m0, s18
	ds_read_b128 v[182:185], v143 offset:32768
	ds_read_b128 v[186:189], v143 offset:33792
	ds_read_b128 v[190:193], v143 offset:34816
	ds_read_b128 v[194:197], v143 offset:35840
	ds_read_b128 v[198:201], v143 offset:36864
	ds_read_b128 v[202:205], v143 offset:37888
	ds_read_b128 v[206:209], v143 offset:38912
	ds_read_b128 v[210:213], v143 offset:39936
	global_load_lds_dwordx4 v128, s[42:43]
	s_mov_b32 m0, s19
	s_nop 0
	global_load_lds_dwordx4 v132, s[42:43]
	s_waitcnt vmcnt(8)
	s_waitcnt lgkmcnt(0)
	s_barrier
	s_setprio 1
	s_waitcnt lgkmcnt(0)
	v_mfma_f32_16x16x32_bf16 v[124:127], v[144:147], v[182:185], v[124:127]
	v_mfma_f32_16x16x32_bf16 v[120:123], v[152:155], v[182:185], v[120:123]
	v_mfma_f32_16x16x32_bf16 v[116:119], v[144:147], v[190:193], v[116:119]
	v_mfma_f32_16x16x32_bf16 v[112:115], v[152:155], v[190:193], v[112:115]
	v_mfma_f32_16x16x32_bf16 v[100:103], v[144:147], v[198:201], v[100:103]
	v_mfma_f32_16x16x32_bf16 v[96:99], v[152:155], v[198:201], v[96:99]
	v_mfma_f32_16x16x32_bf16 v[84:87], v[144:147], v[206:209], v[84:87]
	v_mfma_f32_16x16x32_bf16 v[80:83], v[152:155], v[206:209], v[80:83]
	v_mfma_f32_16x16x32_bf16 v[124:127], v[148:151], v[186:189], v[124:127]
	v_mfma_f32_16x16x32_bf16 v[120:123], v[156:159], v[186:189], v[120:123]
	v_mfma_f32_16x16x32_bf16 v[116:119], v[148:151], v[194:197], v[116:119]
	v_mfma_f32_16x16x32_bf16 v[112:115], v[156:159], v[194:197], v[112:115]
	v_mfma_f32_16x16x32_bf16 v[100:103], v[148:151], v[202:205], v[100:103]
	v_mfma_f32_16x16x32_bf16 v[96:99], v[156:159], v[202:205], v[96:99]
	v_mfma_f32_16x16x32_bf16 v[84:87], v[148:151], v[210:213], v[84:87]
	v_mfma_f32_16x16x32_bf16 v[80:83], v[156:159], v[210:213], v[80:83]
	s_setprio 0
	s_setprio 1
	v_mfma_f32_16x16x32_bf16 v[108:111], v[160:163], v[182:185], v[108:111]
	v_mfma_f32_16x16x32_bf16 v[104:107], v[170:173], v[182:185], v[104:107]
	v_mfma_f32_16x16x32_bf16 v[92:95], v[160:163], v[190:193], v[92:95]
	v_mfma_f32_16x16x32_bf16 v[88:91], v[170:173], v[190:193], v[88:91]
	v_mfma_f32_16x16x32_bf16 v[76:79], v[160:163], v[198:201], v[76:79]
	v_mfma_f32_16x16x32_bf16 v[72:75], v[170:173], v[198:201], v[72:75]
	v_mfma_f32_16x16x32_bf16 v[68:71], v[160:163], v[206:209], v[68:71]
	v_mfma_f32_16x16x32_bf16 v[64:67], v[170:173], v[206:209], v[64:67]
	v_mfma_f32_16x16x32_bf16 v[108:111], v[164:167], v[186:189], v[108:111]
	v_mfma_f32_16x16x32_bf16 v[104:107], v[178:181], v[186:189], v[104:107]
	v_mfma_f32_16x16x32_bf16 v[92:95], v[164:167], v[194:197], v[92:95]
	v_mfma_f32_16x16x32_bf16 v[88:91], v[178:181], v[194:197], v[88:91]
	v_mfma_f32_16x16x32_bf16 v[76:79], v[164:167], v[202:205], v[76:79]
	v_mfma_f32_16x16x32_bf16 v[72:75], v[178:181], v[202:205], v[72:75]
	v_mfma_f32_16x16x32_bf16 v[68:71], v[164:167], v[210:213], v[68:71]
	v_mfma_f32_16x16x32_bf16 v[64:67], v[178:181], v[210:213], v[64:67]
	s_setprio 0
	s_barrier
	s_add_i32 s3, s3, s8
	s_mov_b32 m0, s3
	ds_read_b128 v[182:185], v143 offset:49152
	ds_read_b128 v[186:189], v143 offset:50176
	ds_read_b128 v[190:193], v143 offset:51200
	ds_read_b128 v[194:197], v143 offset:52224
	ds_read_b128 v[198:201], v143 offset:53248
	ds_read_b128 v[202:205], v143 offset:54272
	ds_read_b128 v[206:209], v143 offset:55296
	ds_read_b128 v[210:213], v143 offset:56320
	s_add_u32 s100, s88, s16
	s_addc_u32 s101, s89, s17
	global_load_lds_dwordx4 v130, s[100:101]
	s_add_i32 m0, s3, 0x2000
	s_add_u32 s42, s88, 0x80080
	s_addc_u32 s43, s89, 0
	s_add_i32 s3, s12, s8
	global_load_lds_dwordx4 v134, s[100:101]
	s_mov_b32 m0, s3
	s_nop 0
	global_load_lds_dwordx4 v130, s[42:43]
	s_add_i32 m0, s3, 0x2000
	s_nop 0
	global_load_lds_dwordx4 v134, s[42:43]
	s_mov_b32 m0, s20
	s_nop 0
	s_add_u32 s100, s90, s16
	s_addc_u32 s101, s91, s17
	global_load_lds_dwordx4 v128, s[100:101]
	s_mov_b32 m0, s21
	s_nop 0
	global_load_lds_dwordx4 v132, s[100:101]
	s_waitcnt vmcnt(8)
	s_waitcnt lgkmcnt(0)
	s_barrier
	s_setprio 1
	s_waitcnt lgkmcnt(0)
	v_mfma_f32_16x16x32_bf16 v[60:63], v[144:147], v[182:185], v[60:63]
	v_mfma_f32_16x16x32_bf16 v[56:59], v[152:155], v[182:185], v[56:59]
	v_mfma_f32_16x16x32_bf16 v[52:55], v[144:147], v[190:193], v[52:55]
	v_mfma_f32_16x16x32_bf16 v[48:51], v[152:155], v[190:193], v[48:51]
	v_mfma_f32_16x16x32_bf16 v[36:39], v[144:147], v[198:201], v[36:39]
	v_mfma_f32_16x16x32_bf16 v[32:35], v[152:155], v[198:201], v[32:35]
	v_mfma_f32_16x16x32_bf16 v[20:23], v[144:147], v[206:209], v[20:23]
	v_mfma_f32_16x16x32_bf16 v[16:19], v[152:155], v[206:209], v[16:19]
	v_mfma_f32_16x16x32_bf16 v[60:63], v[148:151], v[186:189], v[60:63]
	v_mfma_f32_16x16x32_bf16 v[56:59], v[156:159], v[186:189], v[56:59]
	v_mfma_f32_16x16x32_bf16 v[52:55], v[148:151], v[194:197], v[52:55]
	v_mfma_f32_16x16x32_bf16 v[48:51], v[156:159], v[194:197], v[48:51]
	v_mfma_f32_16x16x32_bf16 v[36:39], v[148:151], v[202:205], v[36:39]
	v_mfma_f32_16x16x32_bf16 v[32:35], v[156:159], v[202:205], v[32:35]
	v_mfma_f32_16x16x32_bf16 v[20:23], v[148:151], v[210:213], v[20:23]
	v_mfma_f32_16x16x32_bf16 v[16:19], v[156:159], v[210:213], v[16:19]
	s_setprio 0
	s_setprio 1
	v_mfma_f32_16x16x32_bf16 v[44:47], v[160:163], v[182:185], v[44:47]
	v_mfma_f32_16x16x32_bf16 v[40:43], v[170:173], v[182:185], v[40:43]
	v_mfma_f32_16x16x32_bf16 v[28:31], v[160:163], v[190:193], v[28:31]
	v_mfma_f32_16x16x32_bf16 v[24:27], v[170:173], v[190:193], v[24:27]
	v_mfma_f32_16x16x32_bf16 v[12:15], v[160:163], v[198:201], v[12:15]
	v_mfma_f32_16x16x32_bf16 v[8:11], v[170:173], v[198:201], v[8:11]
	v_mfma_f32_16x16x32_bf16 v[4:7], v[160:163], v[206:209], v[4:7]
	v_mfma_f32_16x16x32_bf16 v[0:3], v[170:173], v[206:209], v[0:3]
	v_mfma_f32_16x16x32_bf16 v[44:47], v[164:167], v[186:189], v[44:47]
	v_mfma_f32_16x16x32_bf16 v[40:43], v[178:181], v[186:189], v[40:43]
	v_mfma_f32_16x16x32_bf16 v[28:31], v[164:167], v[194:197], v[28:31]
	v_mfma_f32_16x16x32_bf16 v[24:27], v[178:181], v[194:197], v[24:27]
	v_mfma_f32_16x16x32_bf16 v[12:15], v[164:167], v[202:205], v[12:15]
	v_mfma_f32_16x16x32_bf16 v[8:11], v[178:181], v[202:205], v[8:11]
	v_mfma_f32_16x16x32_bf16 v[4:7], v[164:167], v[210:213], v[4:7]
	v_mfma_f32_16x16x32_bf16 v[0:3], v[178:181], v[210:213], v[0:3]
	s_setprio 0
	s_barrier
	s_add_i32 s2, s2, 2
	s_add_u32 s86, s86, 0x100
	s_addc_u32 s87, s87, 0
	s_add_u32 s33, s33, 0x100
	s_addc_u32 s40, s40, 0
	s_cmp_gt_u32 s2, 29
	s_cbranch_scc0 .LBB0_490
	s_and_b64 vcc, exec, s[74:75]
	s_cbranch_vccz .LBB0_493
	s_barrier

.LBB0_514:
	s_add_u32 s3, s86, 0xfff80080
	s_addc_u32 s12, s87, -1
	s_add_i32 s13, 0, 0x10000
	s_cmp_eq_u32 s2, 28
	s_cselect_b32 s91, s28, s12
	s_cselect_b32 s90, s30, s3
	s_cselect_b32 s89, s33, s43
	s_cselect_b32 s88, s40, s42
	s_add_i32 s3, 0, 0x14000
	v_add_u32_e32 v156, s13, v141
	v_add_u32_e32 v168, s3, v141
	ds_read_b128 v[144:147], v156
	ds_read_b128 v[148:151], v156 offset:1024
	ds_read_b128 v[152:155], v156 offset:2048
	ds_read_b128 v[156:159], v156 offset:3072
	ds_read_b128 v[160:163], v168
	ds_read_b128 v[164:167], v168 offset:1024
	ds_read_b128 v[170:173], v168 offset:2048
	ds_read_b128 v[178:181], v168 offset:3072
	s_add_i32 m0, s18, 0xc000
	ds_read_b128 v[182:185], v143
	ds_read_b128 v[186:189], v143 offset:1024
	ds_read_b128 v[190:193], v143 offset:2048
	ds_read_b128 v[194:197], v143 offset:3072
	ds_read_b128 v[198:201], v143 offset:4096
	ds_read_b128 v[202:205], v143 offset:5120
	ds_read_b128 v[206:209], v143 offset:6144
	ds_read_b128 v[210:213], v143 offset:7168
	global_load_lds_dwordx4 v136, s[86:87]
	s_add_i32 m0, s18, 0xe000
	s_nop 0
	global_load_lds_dwordx4 v138, s[86:87]
	s_waitcnt vmcnt(8)
	s_waitcnt lgkmcnt(0)
	s_barrier
	s_setprio 1
	s_waitcnt lgkmcnt(0)
	v_mfma_f32_16x16x32_bf16 v[124:127], v[144:147], v[182:185], v[124:127]
	v_mfma_f32_16x16x32_bf16 v[120:123], v[152:155], v[182:185], v[120:123]
	v_mfma_f32_16x16x32_bf16 v[116:119], v[144:147], v[190:193], v[116:119]
	v_mfma_f32_16x16x32_bf16 v[112:115], v[152:155], v[190:193], v[112:115]
	v_mfma_f32_16x16x32_bf16 v[100:103], v[144:147], v[198:201], v[100:103]
	v_mfma_f32_16x16x32_bf16 v[96:99], v[152:155], v[198:201], v[96:99]
	v_mfma_f32_16x16x32_bf16 v[84:87], v[144:147], v[206:209], v[84:87]
	v_mfma_f32_16x16x32_bf16 v[80:83], v[152:155], v[206:209], v[80:83]
	v_mfma_f32_16x16x32_bf16 v[124:127], v[148:151], v[186:189], v[124:127]
	v_mfma_f32_16x16x32_bf16 v[120:123], v[156:159], v[186:189], v[120:123]
	v_mfma_f32_16x16x32_bf16 v[116:119], v[148:151], v[194:197], v[116:119]
	v_mfma_f32_16x16x32_bf16 v[112:115], v[156:159], v[194:197], v[112:115]
	v_mfma_f32_16x16x32_bf16 v[100:103], v[148:151], v[202:205], v[100:103]
	v_mfma_f32_16x16x32_bf16 v[96:99], v[156:159], v[202:205], v[96:99]
	v_mfma_f32_16x16x32_bf16 v[84:87], v[148:151], v[210:213], v[84:87]
	v_mfma_f32_16x16x32_bf16 v[80:83], v[156:159], v[210:213], v[80:83]
	s_setprio 0
	s_setprio 1
	v_mfma_f32_16x16x32_bf16 v[108:111], v[160:163], v[182:185], v[108:111]
	v_mfma_f32_16x16x32_bf16 v[104:107], v[170:173], v[182:185], v[104:107]
	v_mfma_f32_16x16x32_bf16 v[92:95], v[160:163], v[190:193], v[92:95]
	v_mfma_f32_16x16x32_bf16 v[88:91], v[170:173], v[190:193], v[88:91]
	v_mfma_f32_16x16x32_bf16 v[76:79], v[160:163], v[198:201], v[76:79]
	v_mfma_f32_16x16x32_bf16 v[72:75], v[170:173], v[198:201], v[72:75]
	v_mfma_f32_16x16x32_bf16 v[68:71], v[160:163], v[206:209], v[68:71]
	v_mfma_f32_16x16x32_bf16 v[64:67], v[170:173], v[206:209], v[64:67]
	v_mfma_f32_16x16x32_bf16 v[108:111], v[164:167], v[186:189], v[108:111]
	v_mfma_f32_16x16x32_bf16 v[104:107], v[178:181], v[186:189], v[104:107]
	v_mfma_f32_16x16x32_bf16 v[92:95], v[164:167], v[194:197], v[92:95]
	v_mfma_f32_16x16x32_bf16 v[88:91], v[178:181], v[194:197], v[88:91]
	v_mfma_f32_16x16x32_bf16 v[76:79], v[164:167], v[202:205], v[76:79]
	v_mfma_f32_16x16x32_bf16 v[72:75], v[178:181], v[202:205], v[72:75]
	v_mfma_f32_16x16x32_bf16 v[68:71], v[164:167], v[210:213], v[68:71]
	v_mfma_f32_16x16x32_bf16 v[64:67], v[178:181], v[210:213], v[64:67]
	s_setprio 0
	s_barrier
	s_add_i32 s12, s13, s10
	s_mov_b32 m0, s12
	ds_read_b128 v[182:185], v143 offset:16384
	ds_read_b128 v[186:189], v143 offset:17408
	ds_read_b128 v[190:193], v143 offset:18432
	ds_read_b128 v[194:197], v143 offset:19456
	ds_read_b128 v[198:201], v143 offset:20480
	ds_read_b128 v[202:205], v143 offset:21504
	ds_read_b128 v[206:209], v143 offset:22528
	ds_read_b128 v[210:213], v143 offset:23552
	global_load_lds_dwordx4 v130, s[88:89]
	s_add_i32 m0, s12, 0x2000
	s_add_u32 vcc_lo, s88, 0x80000
	v_lshl_add_u64 v[216:217], s[88:89], 0, v[134:135]
	s_addc_u32 vcc_hi, s89, 0
	s_add_i32 s3, s3, s10
	global_load_lds_dwordx4 v134, s[88:89]
	s_mov_b32 m0, s3
	v_lshl_add_u64 v[220:221], s[90:91], 0, v[132:133]
	global_load_lds_dwordx4 v130, vcc
	s_add_i32 m0, s3, 0x2000
	s_nop 0
	global_load_lds_dwordx4 v134, vcc
	v_lshl_add_u64 v[218:219], s[90:91], 0, v[128:129]
	s_mov_b32 m0, s18
	s_nop 0
	global_load_lds_dwordx4 v128, s[90:91]
	s_mov_b32 m0, s19
	s_nop 0
	global_load_lds_dwordx4 v132, s[90:91]
	s_waitcnt vmcnt(8)
	s_waitcnt lgkmcnt(0)
	s_barrier
	s_setprio 1
	s_waitcnt lgkmcnt(0)
	v_mfma_f32_16x16x32_bf16 v[60:63], v[144:147], v[182:185], v[60:63]
	v_mfma_f32_16x16x32_bf16 v[56:59], v[152:155], v[182:185], v[56:59]
	v_mfma_f32_16x16x32_bf16 v[52:55], v[144:147], v[190:193], v[52:55]
	v_mfma_f32_16x16x32_bf16 v[48:51], v[152:155], v[190:193], v[48:51]
	v_mfma_f32_16x16x32_bf16 v[36:39], v[144:147], v[198:201], v[36:39]
	v_mfma_f32_16x16x32_bf16 v[32:35], v[152:155], v[198:201], v[32:35]
	v_mfma_f32_16x16x32_bf16 v[20:23], v[144:147], v[206:209], v[20:23]
	v_mfma_f32_16x16x32_bf16 v[16:19], v[152:155], v[206:209], v[16:19]
	v_mfma_f32_16x16x32_bf16 v[60:63], v[148:151], v[186:189], v[60:63]
	v_mfma_f32_16x16x32_bf16 v[56:59], v[156:159], v[186:189], v[56:59]
	v_mfma_f32_16x16x32_bf16 v[52:55], v[148:151], v[194:197], v[52:55]
	v_mfma_f32_16x16x32_bf16 v[48:51], v[156:159], v[194:197], v[48:51]
	v_mfma_f32_16x16x32_bf16 v[36:39], v[148:151], v[202:205], v[36:39]
	v_mfma_f32_16x16x32_bf16 v[32:35], v[156:159], v[202:205], v[32:35]
	v_mfma_f32_16x16x32_bf16 v[20:23], v[148:151], v[210:213], v[20:23]
	v_mfma_f32_16x16x32_bf16 v[16:19], v[156:159], v[210:213], v[16:19]
	s_setprio 0
	s_setprio 1
	v_mfma_f32_16x16x32_bf16 v[44:47], v[160:163], v[182:185], v[44:47]
	v_mfma_f32_16x16x32_bf16 v[40:43], v[170:173], v[182:185], v[40:43]
	v_mfma_f32_16x16x32_bf16 v[28:31], v[160:163], v[190:193], v[28:31]
	v_mfma_f32_16x16x32_bf16 v[24:27], v[170:173], v[190:193], v[24:27]
	v_mfma_f32_16x16x32_bf16 v[12:15], v[160:163], v[198:201], v[12:15]
	v_mfma_f32_16x16x32_bf16 v[8:11], v[170:173], v[198:201], v[8:11]
	v_mfma_f32_16x16x32_bf16 v[4:7], v[160:163], v[206:209], v[4:7]
	v_mfma_f32_16x16x32_bf16 v[0:3], v[170:173], v[206:209], v[0:3]
	v_mfma_f32_16x16x32_bf16 v[44:47], v[164:167], v[186:189], v[44:47]
	v_mfma_f32_16x16x32_bf16 v[40:43], v[178:181], v[186:189], v[40:43]
	v_mfma_f32_16x16x32_bf16 v[28:31], v[164:167], v[194:197], v[28:31]
	v_mfma_f32_16x16x32_bf16 v[24:27], v[178:181], v[194:197], v[24:27]
	v_mfma_f32_16x16x32_bf16 v[12:15], v[164:167], v[202:205], v[12:15]
	v_mfma_f32_16x16x32_bf16 v[8:11], v[178:181], v[202:205], v[8:11]
	v_mfma_f32_16x16x32_bf16 v[4:7], v[164:167], v[210:213], v[4:7]
	v_mfma_f32_16x16x32_bf16 v[0:3], v[178:181], v[210:213], v[0:3]
	s_setprio 0
	s_barrier
	s_add_i32 s3, 0, 0x18000
	s_add_i32 s12, 0, 0x1c000
	v_add_u32_e32 v156, s3, v141
	v_add_u32_e32 v168, s12, v141
	ds_read_b128 v[144:147], v156
	ds_read_b128 v[148:151], v156 offset:1024
	ds_read_b128 v[152:155], v156 offset:2048
	ds_read_b128 v[156:159], v156 offset:3072
	ds_read_b128 v[160:163], v168
	ds_read_b128 v[164:167], v168 offset:1024
	ds_read_b128 v[170:173], v168 offset:2048
	ds_read_b128 v[178:181], v168 offset:3072
	s_add_u32 s90, s90, 0x80000
	s_addc_u32 s91, s91, 0
	s_mov_b32 m0, s20
	ds_read_b128 v[182:185], v143 offset:32768
	ds_read_b128 v[186:189], v143 offset:33792
	ds_read_b128 v[190:193], v143 offset:34816
	ds_read_b128 v[194:197], v143 offset:35840
	ds_read_b128 v[198:201], v143 offset:36864
	ds_read_b128 v[202:205], v143 offset:37888
	ds_read_b128 v[206:209], v143 offset:38912
	ds_read_b128 v[210:213], v143 offset:39936
	global_load_lds_dwordx4 v128, s[90:91]
	s_mov_b32 m0, s21
	s_nop 0
	global_load_lds_dwordx4 v132, s[90:91]
	s_waitcnt vmcnt(8)
	s_waitcnt lgkmcnt(0)
	s_barrier
	s_setprio 1
	s_waitcnt lgkmcnt(0)
	v_mfma_f32_16x16x32_bf16 v[124:127], v[144:147], v[182:185], v[124:127]
	v_mfma_f32_16x16x32_bf16 v[120:123], v[152:155], v[182:185], v[120:123]
	v_mfma_f32_16x16x32_bf16 v[116:119], v[144:147], v[190:193], v[116:119]
	v_mfma_f32_16x16x32_bf16 v[112:115], v[152:155], v[190:193], v[112:115]
	v_mfma_f32_16x16x32_bf16 v[100:103], v[144:147], v[198:201], v[100:103]
	v_mfma_f32_16x16x32_bf16 v[96:99], v[152:155], v[198:201], v[96:99]
	v_mfma_f32_16x16x32_bf16 v[84:87], v[144:147], v[206:209], v[84:87]
	v_mfma_f32_16x16x32_bf16 v[80:83], v[152:155], v[206:209], v[80:83]
	v_mfma_f32_16x16x32_bf16 v[124:127], v[148:151], v[186:189], v[124:127]
	v_mfma_f32_16x16x32_bf16 v[120:123], v[156:159], v[186:189], v[120:123]
	v_mfma_f32_16x16x32_bf16 v[116:119], v[148:151], v[194:197], v[116:119]
	v_mfma_f32_16x16x32_bf16 v[112:115], v[156:159], v[194:197], v[112:115]
	v_mfma_f32_16x16x32_bf16 v[100:103], v[148:151], v[202:205], v[100:103]
	v_mfma_f32_16x16x32_bf16 v[96:99], v[156:159], v[202:205], v[96:99]
	v_mfma_f32_16x16x32_bf16 v[84:87], v[148:151], v[210:213], v[84:87]
	v_mfma_f32_16x16x32_bf16 v[80:83], v[156:159], v[210:213], v[80:83]
	s_setprio 0
	s_setprio 1
	v_mfma_f32_16x16x32_bf16 v[108:111], v[160:163], v[182:185], v[108:111]
	v_mfma_f32_16x16x32_bf16 v[104:107], v[170:173], v[182:185], v[104:107]
	v_mfma_f32_16x16x32_bf16 v[92:95], v[160:163], v[190:193], v[92:95]
	v_mfma_f32_16x16x32_bf16 v[88:91], v[170:173], v[190:193], v[88:91]
	v_mfma_f32_16x16x32_bf16 v[76:79], v[160:163], v[198:201], v[76:79]
	v_mfma_f32_16x16x32_bf16 v[72:75], v[170:173], v[198:201], v[72:75]
	v_mfma_f32_16x16x32_bf16 v[68:71], v[160:163], v[206:209], v[68:71]
	v_mfma_f32_16x16x32_bf16 v[64:67], v[170:173], v[206:209], v[64:67]
	v_mfma_f32_16x16x32_bf16 v[108:111], v[164:167], v[186:189], v[108:111]
	v_mfma_f32_16x16x32_bf16 v[104:107], v[178:181], v[186:189], v[104:107]
	v_mfma_f32_16x16x32_bf16 v[92:95], v[164:167], v[194:197], v[92:95]
	v_mfma_f32_16x16x32_bf16 v[88:91], v[178:181], v[194:197], v[88:91]
	v_mfma_f32_16x16x32_bf16 v[76:79], v[164:167], v[202:205], v[76:79]
	v_mfma_f32_16x16x32_bf16 v[72:75], v[178:181], v[202:205], v[72:75]
	v_mfma_f32_16x16x32_bf16 v[68:71], v[164:167], v[210:213], v[68:71]
	v_mfma_f32_16x16x32_bf16 v[64:67], v[178:181], v[210:213], v[64:67]
	s_setprio 0
	s_barrier
	s_add_i32 s3, s3, s10
	s_mov_b32 m0, s3
	ds_read_b128 v[182:185], v143 offset:49152
	ds_read_b128 v[186:189], v143 offset:50176
	ds_read_b128 v[190:193], v143 offset:51200
	ds_read_b128 v[194:197], v143 offset:52224
	ds_read_b128 v[198:201], v143 offset:53248
	ds_read_b128 v[202:205], v143 offset:54272
	ds_read_b128 v[206:209], v143 offset:55296
	ds_read_b128 v[210:213], v143 offset:56320
	s_add_u32 s100, s88, s16
	s_addc_u32 s101, s89, s17
	global_load_lds_dwordx4 v130, s[100:101]
	s_add_i32 m0, s3, 0x2000
	s_add_u32 s88, s88, 0x80080
	v_lshl_add_u64 v[214:215], v[216:217], 0, s[16:17]
	s_addc_u32 s89, s89, 0
	s_add_i32 s3, s12, s10
	global_load_lds_dwordx4 v[214:215], off
	s_mov_b32 m0, s3
	s_nop 0
	global_load_lds_dwordx4 v130, s[88:89]
	s_add_i32 m0, s3, 0x2000
	s_nop 0
	global_load_lds_dwordx4 v134, s[88:89]
	v_lshl_add_u64 v[214:215], v[218:219], 0, s[16:17]
	s_mov_b32 m0, s22
	s_nop 0
	global_load_lds_dwordx4 v[214:215], off
	v_lshl_add_u64 v[214:215], v[220:221], 0, s[16:17]
	s_mov_b32 m0, s23
	s_nop 0
	global_load_lds_dwordx4 v[214:215], off
	s_waitcnt vmcnt(8)
	s_waitcnt lgkmcnt(0)
	s_barrier
	s_setprio 1
	s_waitcnt lgkmcnt(0)
	v_mfma_f32_16x16x32_bf16 v[60:63], v[144:147], v[182:185], v[60:63]
	v_mfma_f32_16x16x32_bf16 v[56:59], v[152:155], v[182:185], v[56:59]
	v_mfma_f32_16x16x32_bf16 v[52:55], v[144:147], v[190:193], v[52:55]
	v_mfma_f32_16x16x32_bf16 v[48:51], v[152:155], v[190:193], v[48:51]
	v_mfma_f32_16x16x32_bf16 v[36:39], v[144:147], v[198:201], v[36:39]
	v_mfma_f32_16x16x32_bf16 v[32:35], v[152:155], v[198:201], v[32:35]
	v_mfma_f32_16x16x32_bf16 v[20:23], v[144:147], v[206:209], v[20:23]
	v_mfma_f32_16x16x32_bf16 v[16:19], v[152:155], v[206:209], v[16:19]
	v_mfma_f32_16x16x32_bf16 v[60:63], v[148:151], v[186:189], v[60:63]
	v_mfma_f32_16x16x32_bf16 v[56:59], v[156:159], v[186:189], v[56:59]
	v_mfma_f32_16x16x32_bf16 v[52:55], v[148:151], v[194:197], v[52:55]
	v_mfma_f32_16x16x32_bf16 v[48:51], v[156:159], v[194:197], v[48:51]
	v_mfma_f32_16x16x32_bf16 v[36:39], v[148:151], v[202:205], v[36:39]
	v_mfma_f32_16x16x32_bf16 v[32:35], v[156:159], v[202:205], v[32:35]
	v_mfma_f32_16x16x32_bf16 v[20:23], v[148:151], v[210:213], v[20:23]
	v_mfma_f32_16x16x32_bf16 v[16:19], v[156:159], v[210:213], v[16:19]
	s_setprio 0
	s_setprio 1
	v_mfma_f32_16x16x32_bf16 v[44:47], v[160:163], v[182:185], v[44:47]
	v_mfma_f32_16x16x32_bf16 v[40:43], v[170:173], v[182:185], v[40:43]
	v_mfma_f32_16x16x32_bf16 v[28:31], v[160:163], v[190:193], v[28:31]
	v_mfma_f32_16x16x32_bf16 v[24:27], v[170:173], v[190:193], v[24:27]
	v_mfma_f32_16x16x32_bf16 v[12:15], v[160:163], v[198:201], v[12:15]
	v_mfma_f32_16x16x32_bf16 v[8:11], v[170:173], v[198:201], v[8:11]
	v_mfma_f32_16x16x32_bf16 v[4:7], v[160:163], v[206:209], v[4:7]
	v_mfma_f32_16x16x32_bf16 v[0:3], v[170:173], v[206:209], v[0:3]
	v_mfma_f32_16x16x32_bf16 v[44:47], v[164:167], v[186:189], v[44:47]
	v_mfma_f32_16x16x32_bf16 v[40:43], v[178:181], v[186:189], v[40:43]
	v_mfma_f32_16x16x32_bf16 v[28:31], v[164:167], v[194:197], v[28:31]
	v_mfma_f32_16x16x32_bf16 v[24:27], v[178:181], v[194:197], v[24:27]
	v_mfma_f32_16x16x32_bf16 v[12:15], v[164:167], v[202:205], v[12:15]
	v_mfma_f32_16x16x32_bf16 v[8:11], v[178:181], v[202:205], v[8:11]
	v_mfma_f32_16x16x32_bf16 v[4:7], v[164:167], v[210:213], v[4:7]
	v_mfma_f32_16x16x32_bf16 v[0:3], v[178:181], v[210:213], v[0:3]
	s_setprio 0
	s_barrier
	s_add_i32 s2, s2, 2
	s_add_u32 s86, s86, 0x100
	s_addc_u32 s87, s87, 0
	s_add_u32 s42, s42, 0x100
	s_addc_u32 s43, s43, 0
	s_cmp_gt_u32 s2, 29
	s_cbranch_scc0 .LBB0_514
	s_and_b64 vcc, exec, s[74:75]
	s_cbranch_vccz .LBB0_517
	s_barrier

.LBB0_541:
	s_add_u32 s3, s88, 0xfff80080
	s_addc_u32 s12, s89, -1
	s_add_i32 s13, 0, 0x10000
	s_cmp_eq_u32 s2, 28
	s_cselect_b32 s93, s15, s12
	s_cselect_b32 s92, s30, s3
	v_add_u32_e32 v140, s13, v142
	s_cselect_b32 s91, s33, s43
	s_cselect_b32 s90, s40, s42
	s_add_i32 s3, 0, 0x14000
	ds_read_b128 v[146:149], v140
	ds_read_b128 v[150:153], v140 offset:1024
	ds_read_b128 v[154:157], v140 offset:2048
	ds_read_b128 v[158:161], v140 offset:3072
	v_add_u32_e32 v140, s3, v142
	ds_read_b128 v[162:165], v140
	ds_read_b128 v[170:173], v140 offset:1024
	ds_read_b128 v[178:181], v140 offset:2048
	ds_read_b128 v[182:185], v140 offset:3072
	s_add_i32 m0, s21, 0xc000
	ds_read_b128 v[186:189], v145
	ds_read_b128 v[190:193], v145 offset:1024
	ds_read_b128 v[194:197], v145 offset:2048
	ds_read_b128 v[198:201], v145 offset:3072
	ds_read_b128 v[202:205], v145 offset:4096
	ds_read_b128 v[206:209], v145 offset:5120
	ds_read_b128 v[210:213], v145 offset:6144
	ds_read_b128 v[214:217], v145 offset:7168
	global_load_lds_dwordx4 v136, s[88:89]
	s_add_i32 m0, s21, 0xe000
	s_nop 0
	global_load_lds_dwordx4 v138, s[88:89]
	s_waitcnt vmcnt(8)
	s_waitcnt lgkmcnt(0)
	s_barrier
	s_setprio 1
	s_waitcnt lgkmcnt(0)
	v_mfma_f32_16x16x32_bf16 v[124:127], v[146:149], v[186:189], v[124:127]
	v_mfma_f32_16x16x32_bf16 v[120:123], v[154:157], v[186:189], v[120:123]
	v_mfma_f32_16x16x32_bf16 v[116:119], v[146:149], v[194:197], v[116:119]
	v_mfma_f32_16x16x32_bf16 v[112:115], v[154:157], v[194:197], v[112:115]
	v_mfma_f32_16x16x32_bf16 v[100:103], v[146:149], v[202:205], v[100:103]
	v_mfma_f32_16x16x32_bf16 v[96:99], v[154:157], v[202:205], v[96:99]
	v_mfma_f32_16x16x32_bf16 v[84:87], v[146:149], v[210:213], v[84:87]
	v_mfma_f32_16x16x32_bf16 v[80:83], v[154:157], v[210:213], v[80:83]
	v_mfma_f32_16x16x32_bf16 v[124:127], v[150:153], v[190:193], v[124:127]
	v_mfma_f32_16x16x32_bf16 v[120:123], v[158:161], v[190:193], v[120:123]
	v_mfma_f32_16x16x32_bf16 v[116:119], v[150:153], v[198:201], v[116:119]
	v_mfma_f32_16x16x32_bf16 v[112:115], v[158:161], v[198:201], v[112:115]
	v_mfma_f32_16x16x32_bf16 v[100:103], v[150:153], v[206:209], v[100:103]
	v_mfma_f32_16x16x32_bf16 v[96:99], v[158:161], v[206:209], v[96:99]
	v_mfma_f32_16x16x32_bf16 v[84:87], v[150:153], v[214:217], v[84:87]
	v_mfma_f32_16x16x32_bf16 v[80:83], v[158:161], v[214:217], v[80:83]
	s_setprio 0
	s_setprio 1
	v_mfma_f32_16x16x32_bf16 v[108:111], v[162:165], v[186:189], v[108:111]
	v_mfma_f32_16x16x32_bf16 v[104:107], v[178:181], v[186:189], v[104:107]
	v_mfma_f32_16x16x32_bf16 v[92:95], v[162:165], v[194:197], v[92:95]
	v_mfma_f32_16x16x32_bf16 v[88:91], v[178:181], v[194:197], v[88:91]
	v_mfma_f32_16x16x32_bf16 v[76:79], v[162:165], v[202:205], v[76:79]
	v_mfma_f32_16x16x32_bf16 v[72:75], v[178:181], v[202:205], v[72:75]
	v_mfma_f32_16x16x32_bf16 v[68:71], v[162:165], v[210:213], v[68:71]
	v_mfma_f32_16x16x32_bf16 v[64:67], v[178:181], v[210:213], v[64:67]
	v_mfma_f32_16x16x32_bf16 v[108:111], v[170:173], v[190:193], v[108:111]
	v_mfma_f32_16x16x32_bf16 v[104:107], v[182:185], v[190:193], v[104:107]
	v_mfma_f32_16x16x32_bf16 v[92:95], v[170:173], v[198:201], v[92:95]
	v_mfma_f32_16x16x32_bf16 v[88:91], v[182:185], v[198:201], v[88:91]
	v_mfma_f32_16x16x32_bf16 v[76:79], v[170:173], v[206:209], v[76:79]
	v_mfma_f32_16x16x32_bf16 v[72:75], v[182:185], v[206:209], v[72:75]
	v_mfma_f32_16x16x32_bf16 v[68:71], v[170:173], v[214:217], v[68:71]
	v_mfma_f32_16x16x32_bf16 v[64:67], v[182:185], v[214:217], v[64:67]
	s_setprio 0
	s_barrier
	s_add_i32 s12, s13, s20
	s_mov_b32 m0, s12
	ds_read_b128 v[186:189], v145 offset:16384
	ds_read_b128 v[190:193], v145 offset:17408
	ds_read_b128 v[194:197], v145 offset:18432
	ds_read_b128 v[198:201], v145 offset:19456
	ds_read_b128 v[202:205], v145 offset:20480
	ds_read_b128 v[206:209], v145 offset:21504
	ds_read_b128 v[210:213], v145 offset:22528
	ds_read_b128 v[214:217], v145 offset:23552
	global_load_lds_dwordx4 v132, s[90:91]
	s_add_i32 m0, s12, 0x2000
	s_add_u32 vcc_lo, s90, 0x80000
	v_lshl_add_u64 v[218:219], s[90:91], 0, v[128:129]
	s_addc_u32 vcc_hi, s91, 0
	s_add_i32 s3, s3, s20
	global_load_lds_dwordx4 v128, s[90:91]
	s_mov_b32 m0, s3
	v_lshl_add_u64 v[222:223], s[92:93], 0, v[130:131]
	global_load_lds_dwordx4 v132, vcc
	s_add_i32 m0, s3, 0x2000
	s_nop 0
	global_load_lds_dwordx4 v128, vcc
	v_lshl_add_u64 v[220:221], s[92:93], 0, v[134:135]
	s_mov_b32 m0, s21
	s_nop 0
	global_load_lds_dwordx4 v134, s[92:93]
	s_mov_b32 m0, s22
	s_nop 0
	global_load_lds_dwordx4 v130, s[92:93]
	s_waitcnt vmcnt(8)
	s_waitcnt lgkmcnt(0)
	s_barrier
	s_setprio 1
	s_waitcnt lgkmcnt(0)
	v_mfma_f32_16x16x32_bf16 v[60:63], v[146:149], v[186:189], v[60:63]
	v_mfma_f32_16x16x32_bf16 v[56:59], v[154:157], v[186:189], v[56:59]
	v_mfma_f32_16x16x32_bf16 v[52:55], v[146:149], v[194:197], v[52:55]
	v_mfma_f32_16x16x32_bf16 v[48:51], v[154:157], v[194:197], v[48:51]
	v_mfma_f32_16x16x32_bf16 v[36:39], v[146:149], v[202:205], v[36:39]
	v_mfma_f32_16x16x32_bf16 v[32:35], v[154:157], v[202:205], v[32:35]
	v_mfma_f32_16x16x32_bf16 v[20:23], v[146:149], v[210:213], v[20:23]
	v_mfma_f32_16x16x32_bf16 v[16:19], v[154:157], v[210:213], v[16:19]
	v_mfma_f32_16x16x32_bf16 v[60:63], v[150:153], v[190:193], v[60:63]
	v_mfma_f32_16x16x32_bf16 v[56:59], v[158:161], v[190:193], v[56:59]
	v_mfma_f32_16x16x32_bf16 v[52:55], v[150:153], v[198:201], v[52:55]
	v_mfma_f32_16x16x32_bf16 v[48:51], v[158:161], v[198:201], v[48:51]
	v_mfma_f32_16x16x32_bf16 v[36:39], v[150:153], v[206:209], v[36:39]
	v_mfma_f32_16x16x32_bf16 v[32:35], v[158:161], v[206:209], v[32:35]
	v_mfma_f32_16x16x32_bf16 v[20:23], v[150:153], v[214:217], v[20:23]
	v_mfma_f32_16x16x32_bf16 v[16:19], v[158:161], v[214:217], v[16:19]
	s_setprio 0
	s_setprio 1
	v_mfma_f32_16x16x32_bf16 v[44:47], v[162:165], v[186:189], v[44:47]
	v_mfma_f32_16x16x32_bf16 v[40:43], v[178:181], v[186:189], v[40:43]
	v_mfma_f32_16x16x32_bf16 v[28:31], v[162:165], v[194:197], v[28:31]
	v_mfma_f32_16x16x32_bf16 v[24:27], v[178:181], v[194:197], v[24:27]
	v_mfma_f32_16x16x32_bf16 v[12:15], v[162:165], v[202:205], v[12:15]
	v_mfma_f32_16x16x32_bf16 v[8:11], v[178:181], v[202:205], v[8:11]
	v_mfma_f32_16x16x32_bf16 v[4:7], v[162:165], v[210:213], v[4:7]
	v_mfma_f32_16x16x32_bf16 v[0:3], v[178:181], v[210:213], v[0:3]
	v_mfma_f32_16x16x32_bf16 v[44:47], v[170:173], v[190:193], v[44:47]
	v_mfma_f32_16x16x32_bf16 v[40:43], v[182:185], v[190:193], v[40:43]
	v_mfma_f32_16x16x32_bf16 v[28:31], v[170:173], v[198:201], v[28:31]
	v_mfma_f32_16x16x32_bf16 v[24:27], v[182:185], v[198:201], v[24:27]
	v_mfma_f32_16x16x32_bf16 v[12:15], v[170:173], v[206:209], v[12:15]
	v_mfma_f32_16x16x32_bf16 v[8:11], v[182:185], v[206:209], v[8:11]
	v_mfma_f32_16x16x32_bf16 v[4:7], v[170:173], v[214:217], v[4:7]
	v_mfma_f32_16x16x32_bf16 v[0:3], v[182:185], v[214:217], v[0:3]
	s_setprio 0
	s_barrier
	s_add_i32 s3, 0, 0x18000
	v_add_u32_e32 v140, s3, v142
	s_add_i32 s12, 0, 0x1c000
	ds_read_b128 v[146:149], v140
	ds_read_b128 v[150:153], v140 offset:1024
	ds_read_b128 v[154:157], v140 offset:2048
	ds_read_b128 v[158:161], v140 offset:3072
	v_add_u32_e32 v140, s12, v142
	ds_read_b128 v[162:165], v140
	ds_read_b128 v[170:173], v140 offset:1024
	ds_read_b128 v[178:181], v140 offset:2048
	ds_read_b128 v[182:185], v140 offset:3072
	s_add_u32 s92, s92, 0x80000
	s_addc_u32 s93, s93, 0
	s_mov_b32 m0, s23
	ds_read_b128 v[186:189], v145 offset:32768
	ds_read_b128 v[190:193], v145 offset:33792
	ds_read_b128 v[194:197], v145 offset:34816
	ds_read_b128 v[198:201], v145 offset:35840
	ds_read_b128 v[202:205], v145 offset:36864
	ds_read_b128 v[206:209], v145 offset:37888
	ds_read_b128 v[210:213], v145 offset:38912
	ds_read_b128 v[214:217], v145 offset:39936
	global_load_lds_dwordx4 v134, s[92:93]
	s_mov_b32 m0, s57
	s_nop 0
	global_load_lds_dwordx4 v130, s[92:93]
	s_waitcnt vmcnt(8)
	s_waitcnt lgkmcnt(0)
	s_barrier
	s_setprio 1
	s_waitcnt lgkmcnt(0)
	v_mfma_f32_16x16x32_bf16 v[124:127], v[146:149], v[186:189], v[124:127]
	v_mfma_f32_16x16x32_bf16 v[120:123], v[154:157], v[186:189], v[120:123]
	v_mfma_f32_16x16x32_bf16 v[116:119], v[146:149], v[194:197], v[116:119]
	v_mfma_f32_16x16x32_bf16 v[112:115], v[154:157], v[194:197], v[112:115]
	v_mfma_f32_16x16x32_bf16 v[100:103], v[146:149], v[202:205], v[100:103]
	v_mfma_f32_16x16x32_bf16 v[96:99], v[154:157], v[202:205], v[96:99]
	v_mfma_f32_16x16x32_bf16 v[84:87], v[146:149], v[210:213], v[84:87]
	v_mfma_f32_16x16x32_bf16 v[80:83], v[154:157], v[210:213], v[80:83]
	v_mfma_f32_16x16x32_bf16 v[124:127], v[150:153], v[190:193], v[124:127]
	v_mfma_f32_16x16x32_bf16 v[120:123], v[158:161], v[190:193], v[120:123]
	v_mfma_f32_16x16x32_bf16 v[116:119], v[150:153], v[198:201], v[116:119]
	v_mfma_f32_16x16x32_bf16 v[112:115], v[158:161], v[198:201], v[112:115]
	v_mfma_f32_16x16x32_bf16 v[100:103], v[150:153], v[206:209], v[100:103]
	v_mfma_f32_16x16x32_bf16 v[96:99], v[158:161], v[206:209], v[96:99]
	v_mfma_f32_16x16x32_bf16 v[84:87], v[150:153], v[214:217], v[84:87]
	v_mfma_f32_16x16x32_bf16 v[80:83], v[158:161], v[214:217], v[80:83]
	s_setprio 0
	s_setprio 1
	v_mfma_f32_16x16x32_bf16 v[108:111], v[162:165], v[186:189], v[108:111]
	v_mfma_f32_16x16x32_bf16 v[104:107], v[178:181], v[186:189], v[104:107]
	v_mfma_f32_16x16x32_bf16 v[92:95], v[162:165], v[194:197], v[92:95]
	v_mfma_f32_16x16x32_bf16 v[88:91], v[178:181], v[194:197], v[88:91]
	v_mfma_f32_16x16x32_bf16 v[76:79], v[162:165], v[202:205], v[76:79]
	v_mfma_f32_16x16x32_bf16 v[72:75], v[178:181], v[202:205], v[72:75]
	v_mfma_f32_16x16x32_bf16 v[68:71], v[162:165], v[210:213], v[68:71]
	v_mfma_f32_16x16x32_bf16 v[64:67], v[178:181], v[210:213], v[64:67]
	v_mfma_f32_16x16x32_bf16 v[108:111], v[170:173], v[190:193], v[108:111]
	v_mfma_f32_16x16x32_bf16 v[104:107], v[182:185], v[190:193], v[104:107]
	v_mfma_f32_16x16x32_bf16 v[92:95], v[170:173], v[198:201], v[92:95]
	v_mfma_f32_16x16x32_bf16 v[88:91], v[182:185], v[198:201], v[88:91]
	v_mfma_f32_16x16x32_bf16 v[76:79], v[170:173], v[206:209], v[76:79]
	v_mfma_f32_16x16x32_bf16 v[72:75], v[182:185], v[206:209], v[72:75]
	v_mfma_f32_16x16x32_bf16 v[68:71], v[170:173], v[214:217], v[68:71]
	v_mfma_f32_16x16x32_bf16 v[64:67], v[182:185], v[214:217], v[64:67]
	s_setprio 0
	s_barrier
	s_add_i32 s3, s3, s20
	s_mov_b32 m0, s3
	ds_read_b128 v[186:189], v145 offset:49152
	ds_read_b128 v[190:193], v145 offset:50176
	ds_read_b128 v[194:197], v145 offset:51200
	ds_read_b128 v[198:201], v145 offset:52224
	ds_read_b128 v[202:205], v145 offset:53248
	ds_read_b128 v[206:209], v145 offset:54272
	ds_read_b128 v[210:213], v145 offset:55296
	ds_read_b128 v[214:217], v145 offset:56320
	s_add_u32 s100, s90, s16
	s_addc_u32 s101, s91, s17
	global_load_lds_dwordx4 v132, s[100:101]
	s_add_i32 m0, s3, 0x2000
	s_add_u32 s90, s90, 0x80080
	v_lshl_add_u64 v[166:167], v[218:219], 0, s[16:17]
	s_addc_u32 s91, s91, 0
	s_add_i32 s3, s12, s20
	global_load_lds_dwordx4 v[166:167], off
	s_mov_b32 m0, s3
	s_nop 0
	global_load_lds_dwordx4 v132, s[90:91]
	s_add_i32 m0, s3, 0x2000
	s_nop 0
	global_load_lds_dwordx4 v128, s[90:91]
	v_lshl_add_u64 v[166:167], v[220:221], 0, s[16:17]
	s_mov_b32 m0, s59
	s_nop 0
	global_load_lds_dwordx4 v[166:167], off
	v_lshl_add_u64 v[166:167], v[222:223], 0, s[16:17]
	s_mov_b32 m0, s8
	s_nop 0
	global_load_lds_dwordx4 v[166:167], off
	s_waitcnt vmcnt(8)
	s_waitcnt lgkmcnt(0)
	s_barrier
	s_setprio 1
	s_waitcnt lgkmcnt(0)
	v_mfma_f32_16x16x32_bf16 v[60:63], v[146:149], v[186:189], v[60:63]
	v_mfma_f32_16x16x32_bf16 v[56:59], v[154:157], v[186:189], v[56:59]
	v_mfma_f32_16x16x32_bf16 v[52:55], v[146:149], v[194:197], v[52:55]
	v_mfma_f32_16x16x32_bf16 v[48:51], v[154:157], v[194:197], v[48:51]
	v_mfma_f32_16x16x32_bf16 v[36:39], v[146:149], v[202:205], v[36:39]
	v_mfma_f32_16x16x32_bf16 v[32:35], v[154:157], v[202:205], v[32:35]
	v_mfma_f32_16x16x32_bf16 v[20:23], v[146:149], v[210:213], v[20:23]
	v_mfma_f32_16x16x32_bf16 v[16:19], v[154:157], v[210:213], v[16:19]
	v_mfma_f32_16x16x32_bf16 v[60:63], v[150:153], v[190:193], v[60:63]
	v_mfma_f32_16x16x32_bf16 v[56:59], v[158:161], v[190:193], v[56:59]
	v_mfma_f32_16x16x32_bf16 v[52:55], v[150:153], v[198:201], v[52:55]
	v_mfma_f32_16x16x32_bf16 v[48:51], v[158:161], v[198:201], v[48:51]
	v_mfma_f32_16x16x32_bf16 v[36:39], v[150:153], v[206:209], v[36:39]
	v_mfma_f32_16x16x32_bf16 v[32:35], v[158:161], v[206:209], v[32:35]
	v_mfma_f32_16x16x32_bf16 v[20:23], v[150:153], v[214:217], v[20:23]
	v_mfma_f32_16x16x32_bf16 v[16:19], v[158:161], v[214:217], v[16:19]
	s_setprio 0
	s_setprio 1
	v_mfma_f32_16x16x32_bf16 v[44:47], v[162:165], v[186:189], v[44:47]
	v_mfma_f32_16x16x32_bf16 v[40:43], v[178:181], v[186:189], v[40:43]
	v_mfma_f32_16x16x32_bf16 v[28:31], v[162:165], v[194:197], v[28:31]
	v_mfma_f32_16x16x32_bf16 v[24:27], v[178:181], v[194:197], v[24:27]
	v_mfma_f32_16x16x32_bf16 v[12:15], v[162:165], v[202:205], v[12:15]
	v_mfma_f32_16x16x32_bf16 v[8:11], v[178:181], v[202:205], v[8:11]
	v_mfma_f32_16x16x32_bf16 v[4:7], v[162:165], v[210:213], v[4:7]
	v_mfma_f32_16x16x32_bf16 v[0:3], v[178:181], v[210:213], v[0:3]
	v_mfma_f32_16x16x32_bf16 v[44:47], v[170:173], v[190:193], v[44:47]
	v_mfma_f32_16x16x32_bf16 v[40:43], v[182:185], v[190:193], v[40:43]
	v_mfma_f32_16x16x32_bf16 v[28:31], v[170:173], v[198:201], v[28:31]
	v_mfma_f32_16x16x32_bf16 v[24:27], v[182:185], v[198:201], v[24:27]
	v_mfma_f32_16x16x32_bf16 v[12:15], v[170:173], v[206:209], v[12:15]
	v_mfma_f32_16x16x32_bf16 v[8:11], v[182:185], v[206:209], v[8:11]
	v_mfma_f32_16x16x32_bf16 v[4:7], v[170:173], v[214:217], v[4:7]
	v_mfma_f32_16x16x32_bf16 v[0:3], v[182:185], v[214:217], v[0:3]
	s_setprio 0
	s_barrier
	s_add_i32 s2, s2, 2
	s_add_u32 s88, s88, 0x100
	s_addc_u32 s89, s89, 0
	s_add_u32 s42, s42, 0x100
	s_addc_u32 s43, s43, 0
	s_cmp_gt_u32 s2, 29
	s_cbranch_scc0 .LBB0_541
	s_and_b64 vcc, exec, s[76:77]
	s_cbranch_vccz .LBB0_544
	s_barrier

.LBB0_626:
	s_add_u32 s12, s86, 0xfffc0080
	s_addc_u32 s13, s87, -1
	s_add_i32 s96, 0, 0x10000
	s_cmp_eq_u32 s3, 12
	s_cselect_b32 s91, s75, s13
	s_cselect_b32 s90, s81, s12
	v_add_u32_e32 v143, s96, v140
	s_cselect_b32 s89, s79, s2
	s_cselect_b32 s88, vcc_lo, vcc_hi
	s_add_i32 s31, 0, 0x14000
	ds_read_b128 v[144:147], v143
	ds_read_b128 v[148:151], v143 offset:1024
	ds_read_b128 v[152:155], v143 offset:2048
	ds_read_b128 v[156:159], v143 offset:3072
	v_add_u32_e32 v143, s31, v140
	ds_read_b128 v[160:163], v143
	ds_read_b128 v[164:167], v143 offset:1024
	ds_read_b128 v[170:173], v143 offset:2048
	ds_read_b128 v[178:181], v143 offset:3072
	s_add_i32 m0, s97, 0xc000
	ds_read_b128 v[182:185], v142
	ds_read_b128 v[186:189], v142 offset:1024
	ds_read_b128 v[190:193], v142 offset:2048
	ds_read_b128 v[194:197], v142 offset:3072
	ds_read_b128 v[198:201], v142 offset:4096
	ds_read_b128 v[202:205], v142 offset:5120
	ds_read_b128 v[206:209], v142 offset:6144
	ds_read_b128 v[210:213], v142 offset:7168
	global_load_lds_dwordx4 v136, s[86:87]
	s_add_i32 m0, s97, 0xe000
	s_nop 0
	global_load_lds_dwordx4 v138, s[86:87]
	s_waitcnt vmcnt(8)
	s_waitcnt lgkmcnt(0)
	s_barrier
	s_setprio 1
	s_waitcnt lgkmcnt(0)
	v_mfma_f32_16x16x32_bf16 v[124:127], v[144:147], v[182:185], v[124:127]
	v_mfma_f32_16x16x32_bf16 v[120:123], v[152:155], v[182:185], v[120:123]
	v_mfma_f32_16x16x32_bf16 v[116:119], v[144:147], v[190:193], v[116:119]
	v_mfma_f32_16x16x32_bf16 v[112:115], v[152:155], v[190:193], v[112:115]
	v_mfma_f32_16x16x32_bf16 v[100:103], v[144:147], v[198:201], v[100:103]
	v_mfma_f32_16x16x32_bf16 v[96:99], v[152:155], v[198:201], v[96:99]
	v_mfma_f32_16x16x32_bf16 v[84:87], v[144:147], v[206:209], v[84:87]
	v_mfma_f32_16x16x32_bf16 v[80:83], v[152:155], v[206:209], v[80:83]
	v_mfma_f32_16x16x32_bf16 v[124:127], v[148:151], v[186:189], v[124:127]
	v_mfma_f32_16x16x32_bf16 v[120:123], v[156:159], v[186:189], v[120:123]
	v_mfma_f32_16x16x32_bf16 v[116:119], v[148:151], v[194:197], v[116:119]
	v_mfma_f32_16x16x32_bf16 v[112:115], v[156:159], v[194:197], v[112:115]
	v_mfma_f32_16x16x32_bf16 v[100:103], v[148:151], v[202:205], v[100:103]
	v_mfma_f32_16x16x32_bf16 v[96:99], v[156:159], v[202:205], v[96:99]
	v_mfma_f32_16x16x32_bf16 v[84:87], v[148:151], v[210:213], v[84:87]
	v_mfma_f32_16x16x32_bf16 v[80:83], v[156:159], v[210:213], v[80:83]
	s_setprio 0
	s_setprio 1
	v_mfma_f32_16x16x32_bf16 v[108:111], v[160:163], v[182:185], v[108:111]
	v_mfma_f32_16x16x32_bf16 v[104:107], v[170:173], v[182:185], v[104:107]
	v_mfma_f32_16x16x32_bf16 v[92:95], v[160:163], v[190:193], v[92:95]
	v_mfma_f32_16x16x32_bf16 v[88:91], v[170:173], v[190:193], v[88:91]
	v_mfma_f32_16x16x32_bf16 v[76:79], v[160:163], v[198:201], v[76:79]
	v_mfma_f32_16x16x32_bf16 v[72:75], v[170:173], v[198:201], v[72:75]
	v_mfma_f32_16x16x32_bf16 v[68:71], v[160:163], v[206:209], v[68:71]
	v_mfma_f32_16x16x32_bf16 v[64:67], v[170:173], v[206:209], v[64:67]
	v_mfma_f32_16x16x32_bf16 v[108:111], v[164:167], v[186:189], v[108:111]
	v_mfma_f32_16x16x32_bf16 v[104:107], v[178:181], v[186:189], v[104:107]
	v_mfma_f32_16x16x32_bf16 v[92:95], v[164:167], v[194:197], v[92:95]
	v_mfma_f32_16x16x32_bf16 v[88:91], v[178:181], v[194:197], v[88:91]
	v_mfma_f32_16x16x32_bf16 v[76:79], v[164:167], v[202:205], v[76:79]
	v_mfma_f32_16x16x32_bf16 v[72:75], v[178:181], v[202:205], v[72:75]
	v_mfma_f32_16x16x32_bf16 v[68:71], v[164:167], v[210:213], v[68:71]
	v_mfma_f32_16x16x32_bf16 v[64:67], v[178:181], v[210:213], v[64:67]
	s_setprio 0
	s_barrier
	s_add_i32 s12, s96, s93
	s_mov_b32 m0, s12
	ds_read_b128 v[182:185], v142 offset:16384
	ds_read_b128 v[186:189], v142 offset:17408
	ds_read_b128 v[190:193], v142 offset:18432
	ds_read_b128 v[194:197], v142 offset:19456
	ds_read_b128 v[198:201], v142 offset:20480
	ds_read_b128 v[202:205], v142 offset:21504
	ds_read_b128 v[206:209], v142 offset:22528
	ds_read_b128 v[210:213], v142 offset:23552
	global_load_lds_dwordx4 v130, s[88:89]
	s_add_i32 m0, s12, 0x2000
	s_add_u32 s12, s88, 0x40000
	s_addc_u32 s13, s89, 0
	s_add_i32 s31, s31, s93
	global_load_lds_dwordx4 v134, s[88:89]
	s_mov_b32 m0, s31
	s_nop 0
	global_load_lds_dwordx4 v130, s[12:13]
	s_add_i32 m0, s31, 0x2000
	s_nop 0
	global_load_lds_dwordx4 v134, s[12:13]
	s_mov_b32 m0, s97
	s_nop 0
	global_load_lds_dwordx4 v128, s[90:91]
	s_mov_b32 m0, s40
	s_nop 0
	global_load_lds_dwordx4 v132, s[90:91]
	s_waitcnt vmcnt(8)
	s_waitcnt lgkmcnt(0)
	s_barrier
	s_setprio 1
	s_waitcnt lgkmcnt(0)
	v_mfma_f32_16x16x32_bf16 v[60:63], v[144:147], v[182:185], v[60:63]
	v_mfma_f32_16x16x32_bf16 v[56:59], v[152:155], v[182:185], v[56:59]
	v_mfma_f32_16x16x32_bf16 v[52:55], v[144:147], v[190:193], v[52:55]
	v_mfma_f32_16x16x32_bf16 v[48:51], v[152:155], v[190:193], v[48:51]
	v_mfma_f32_16x16x32_bf16 v[36:39], v[144:147], v[198:201], v[36:39]
	v_mfma_f32_16x16x32_bf16 v[32:35], v[152:155], v[198:201], v[32:35]
	v_mfma_f32_16x16x32_bf16 v[20:23], v[144:147], v[206:209], v[20:23]
	v_mfma_f32_16x16x32_bf16 v[16:19], v[152:155], v[206:209], v[16:19]
	v_mfma_f32_16x16x32_bf16 v[60:63], v[148:151], v[186:189], v[60:63]
	v_mfma_f32_16x16x32_bf16 v[56:59], v[156:159], v[186:189], v[56:59]
	v_mfma_f32_16x16x32_bf16 v[52:55], v[148:151], v[194:197], v[52:55]
	v_mfma_f32_16x16x32_bf16 v[48:51], v[156:159], v[194:197], v[48:51]
	v_mfma_f32_16x16x32_bf16 v[36:39], v[148:151], v[202:205], v[36:39]
	v_mfma_f32_16x16x32_bf16 v[32:35], v[156:159], v[202:205], v[32:35]
	v_mfma_f32_16x16x32_bf16 v[20:23], v[148:151], v[210:213], v[20:23]
	v_mfma_f32_16x16x32_bf16 v[16:19], v[156:159], v[210:213], v[16:19]
	s_setprio 0
	s_setprio 1
	v_mfma_f32_16x16x32_bf16 v[44:47], v[160:163], v[182:185], v[44:47]
	v_mfma_f32_16x16x32_bf16 v[40:43], v[170:173], v[182:185], v[40:43]
	v_mfma_f32_16x16x32_bf16 v[28:31], v[160:163], v[190:193], v[28:31]
	v_mfma_f32_16x16x32_bf16 v[24:27], v[170:173], v[190:193], v[24:27]
	v_mfma_f32_16x16x32_bf16 v[12:15], v[160:163], v[198:201], v[12:15]
	v_mfma_f32_16x16x32_bf16 v[8:11], v[170:173], v[198:201], v[8:11]
	v_mfma_f32_16x16x32_bf16 v[4:7], v[160:163], v[206:209], v[4:7]
	v_mfma_f32_16x16x32_bf16 v[0:3], v[170:173], v[206:209], v[0:3]
	v_mfma_f32_16x16x32_bf16 v[44:47], v[164:167], v[186:189], v[44:47]
	v_mfma_f32_16x16x32_bf16 v[40:43], v[178:181], v[186:189], v[40:43]
	v_mfma_f32_16x16x32_bf16 v[28:31], v[164:167], v[194:197], v[28:31]
	v_mfma_f32_16x16x32_bf16 v[24:27], v[178:181], v[194:197], v[24:27]
	v_mfma_f32_16x16x32_bf16 v[12:15], v[164:167], v[202:205], v[12:15]
	v_mfma_f32_16x16x32_bf16 v[8:11], v[178:181], v[202:205], v[8:11]
	v_mfma_f32_16x16x32_bf16 v[4:7], v[164:167], v[210:213], v[4:7]
	v_mfma_f32_16x16x32_bf16 v[0:3], v[178:181], v[210:213], v[0:3]
	s_setprio 0
	s_barrier
; #define PG8_STAGE(bufoff, gbase, voff) do { _Pragma("unroll") for (int _i = 0; _i < 2; ++_i) \
;         __builtin_amdgcn_global_load_lds((const unsigned*)((const char*)(gbase) + (voff)[_i]), (PG8_LAS unsigned*)(lds + (bufoff) + ldsw + _i * 8192), 16, 0, 0); } while (0)
; #define PG8_LDA(dst, b, h) do { _Pragma("unroll") for (int m = 0; m < 4; ++m) _Pragma("unroll") for (int k = 0; k < 2; ++k) dst[m][k] = *(const PG8_LAS bf16x8*)(lds + PG8_SA(b, h) + aoff + m * 2048 + k * 1024); } while (0)
; #define PG8_LDB(dst, b, h) do { _Pragma("unroll") for (int n = 0; n < 2; ++n) _Pragma("unroll") for (int k = 0; k < 2; ++k) dst[n][k] = *(const PG8_LAS bf16x8*)(lds + PG8_SB(b, h) + boff + n * 2048 + k * 1024); } while (0)
; #define PG8_MMA(ai, bj, At, Bt) do { __builtin_amdgcn_s_setprio(1); _Pragma("unroll") for (int m = 0; m < 4; ++m) _Pragma("unroll") for (int n = 0; n < 2; ++n) _Pragma("unroll") for (int k = 0; k < 2; ++k) \
;         acc[ai][bj][m][n] = __builtin_amdgcn_mfma_f32_16x16x32_bf16(Bt[n][k], At[m][k], acc[ai][bj][m][n], 0, 0, 0); __builtin_amdgcn_s_setprio(0); } while (0)
; #define PG8_WAIT_V(n) asm volatile("s_waitcnt vmcnt(" #n ")" ::: "memory")
; #define PG8_WAIT_L(n) asm volatile("s_waitcnt lgkmcnt(" #n ")" ::: "memory")
; #define PG8_BAR __builtin_amdgcn_s_barrier()
; #define PG8_SCHED __builtin_amdgcn_sched_barrier(0)
;     ...
;             PG8_LDB(B0, 1, 0); PG8_LDB(B1, 1, 1); PG8_SCHED; PG8_LDA(At, 1, 0); PG8_STAGE(PG8_SA(0, 1), a2 + hstep, voffA);
;             PG8_WAIT_V(8); PG8_WAIT_L(0); PG8_BAR; PG8_MMA(0, 0, At, B0); PG8_MMA(0, 1, At, B1); PG8_BAR; PG8_SCHED;
;             PG8_LDA(At, 1, 1); PG8_STAGE(PG8_SB(1, 0), b3, voffB); PG8_STAGE(PG8_SB(1, 1), b3 + hstep, voffB); PG8_STAGE(PG8_SA(1, 0), a3, voffA);
;             PG8_WAIT_V(8); PG8_WAIT_L(0); PG8_BAR; PG8_MMA(1, 0, At, B0); PG8_MMA(1, 1, At, B1); PG8_BAR; PG8_SCHED;
	s_add_i32 s31, 0, 0x18000
	v_add_u32_e32 v143, s31, v140
	s_add_i32 s96, 0, 0x1c000
	ds_read_b128 v[144:147], v143
	ds_read_b128 v[148:151], v143 offset:1024
	ds_read_b128 v[152:155], v143 offset:2048
	ds_read_b128 v[156:159], v143 offset:3072
	v_add_u32_e32 v143, s96, v140
	ds_read_b128 v[160:163], v143
	ds_read_b128 v[164:167], v143 offset:1024
	ds_read_b128 v[170:173], v143 offset:2048
	ds_read_b128 v[178:181], v143 offset:3072
	s_add_u32 s12, s90, 0x40000
	s_addc_u32 s13, s91, 0
	s_mov_b32 m0, s33
	ds_read_b128 v[182:185], v142 offset:32768
	ds_read_b128 v[186:189], v142 offset:33792
	ds_read_b128 v[190:193], v142 offset:34816
	ds_read_b128 v[194:197], v142 offset:35840
	ds_read_b128 v[198:201], v142 offset:36864
	ds_read_b128 v[202:205], v142 offset:37888
	ds_read_b128 v[206:209], v142 offset:38912
	ds_read_b128 v[210:213], v142 offset:39936
	global_load_lds_dwordx4 v128, s[12:13]
	s_mov_b32 m0, s30
	s_nop 0
	global_load_lds_dwordx4 v132, s[12:13]
	s_waitcnt vmcnt(8)
	s_waitcnt lgkmcnt(0)
	s_barrier
	s_setprio 1
	s_waitcnt lgkmcnt(0)
	v_mfma_f32_16x16x32_bf16 v[124:127], v[144:147], v[182:185], v[124:127]
	v_mfma_f32_16x16x32_bf16 v[120:123], v[152:155], v[182:185], v[120:123]
	v_mfma_f32_16x16x32_bf16 v[116:119], v[144:147], v[190:193], v[116:119]
	v_mfma_f32_16x16x32_bf16 v[112:115], v[152:155], v[190:193], v[112:115]
	v_mfma_f32_16x16x32_bf16 v[100:103], v[144:147], v[198:201], v[100:103]
	v_mfma_f32_16x16x32_bf16 v[96:99], v[152:155], v[198:201], v[96:99]
	v_mfma_f32_16x16x32_bf16 v[84:87], v[144:147], v[206:209], v[84:87]
	v_mfma_f32_16x16x32_bf16 v[80:83], v[152:155], v[206:209], v[80:83]
	v_mfma_f32_16x16x32_bf16 v[124:127], v[148:151], v[186:189], v[124:127]
	v_mfma_f32_16x16x32_bf16 v[120:123], v[156:159], v[186:189], v[120:123]
	v_mfma_f32_16x16x32_bf16 v[116:119], v[148:151], v[194:197], v[116:119]
	v_mfma_f32_16x16x32_bf16 v[112:115], v[156:159], v[194:197], v[112:115]
	v_mfma_f32_16x16x32_bf16 v[100:103], v[148:151], v[202:205], v[100:103]
	v_mfma_f32_16x16x32_bf16 v[96:99], v[156:159], v[202:205], v[96:99]
	v_mfma_f32_16x16x32_bf16 v[84:87], v[148:151], v[210:213], v[84:87]
	v_mfma_f32_16x16x32_bf16 v[80:83], v[156:159], v[210:213], v[80:83]
	s_setprio 0
	s_setprio 1
	v_mfma_f32_16x16x32_bf16 v[108:111], v[160:163], v[182:185], v[108:111]
	v_mfma_f32_16x16x32_bf16 v[104:107], v[170:173], v[182:185], v[104:107]
	v_mfma_f32_16x16x32_bf16 v[92:95], v[160:163], v[190:193], v[92:95]
	v_mfma_f32_16x16x32_bf16 v[88:91], v[170:173], v[190:193], v[88:91]
	v_mfma_f32_16x16x32_bf16 v[76:79], v[160:163], v[198:201], v[76:79]
	v_mfma_f32_16x16x32_bf16 v[72:75], v[170:173], v[198:201], v[72:75]
	v_mfma_f32_16x16x32_bf16 v[68:71], v[160:163], v[206:209], v[68:71]
	v_mfma_f32_16x16x32_bf16 v[64:67], v[170:173], v[206:209], v[64:67]
	v_mfma_f32_16x16x32_bf16 v[108:111], v[164:167], v[186:189], v[108:111]
	v_mfma_f32_16x16x32_bf16 v[104:107], v[178:181], v[186:189], v[104:107]
	v_mfma_f32_16x16x32_bf16 v[92:95], v[164:167], v[194:197], v[92:95]
	v_mfma_f32_16x16x32_bf16 v[88:91], v[178:181], v[194:197], v[88:91]
	v_mfma_f32_16x16x32_bf16 v[76:79], v[164:167], v[202:205], v[76:79]
	v_mfma_f32_16x16x32_bf16 v[72:75], v[178:181], v[202:205], v[72:75]
	v_mfma_f32_16x16x32_bf16 v[68:71], v[164:167], v[210:213], v[68:71]
	v_mfma_f32_16x16x32_bf16 v[64:67], v[178:181], v[210:213], v[64:67]
	s_setprio 0
	s_barrier
	s_add_i32 s12, s31, s93
	s_mov_b32 m0, s12
	ds_read_b128 v[182:185], v142 offset:49152
	ds_read_b128 v[186:189], v142 offset:50176
	ds_read_b128 v[190:193], v142 offset:51200
	ds_read_b128 v[194:197], v142 offset:52224
	ds_read_b128 v[198:201], v142 offset:53248
	ds_read_b128 v[202:205], v142 offset:54272
	ds_read_b128 v[206:209], v142 offset:55296
	ds_read_b128 v[210:213], v142 offset:56320
	s_add_u32 s100, s88, s16
	s_addc_u32 s101, s89, s17
	global_load_lds_dwordx4 v130, s[100:101]
	s_add_i32 m0, s12, 0x2000
	s_add_u32 s12, s88, 0x40080
	s_addc_u32 s13, s89, 0
	s_add_i32 s31, s96, s93
	global_load_lds_dwordx4 v134, s[100:101]
	s_mov_b32 m0, s31
	s_nop 0
	global_load_lds_dwordx4 v130, s[12:13]
	s_add_i32 m0, s31, 0x2000
	s_nop 0
	global_load_lds_dwordx4 v134, s[12:13]
	s_mov_b32 m0, s14
	s_nop 0
	s_add_u32 s100, s90, s16
	s_addc_u32 s101, s91, s17
	global_load_lds_dwordx4 v128, s[100:101]
	s_mov_b32 m0, s15
	s_nop 0
	global_load_lds_dwordx4 v132, s[100:101]
	s_waitcnt vmcnt(8)
	s_waitcnt lgkmcnt(0)
	s_barrier
	s_setprio 1
	s_waitcnt lgkmcnt(0)
	v_mfma_f32_16x16x32_bf16 v[60:63], v[144:147], v[182:185], v[60:63]
	v_mfma_f32_16x16x32_bf16 v[56:59], v[152:155], v[182:185], v[56:59]
	v_mfma_f32_16x16x32_bf16 v[52:55], v[144:147], v[190:193], v[52:55]
	v_mfma_f32_16x16x32_bf16 v[48:51], v[152:155], v[190:193], v[48:51]
	v_mfma_f32_16x16x32_bf16 v[36:39], v[144:147], v[198:201], v[36:39]
	v_mfma_f32_16x16x32_bf16 v[32:35], v[152:155], v[198:201], v[32:35]
	v_mfma_f32_16x16x32_bf16 v[20:23], v[144:147], v[206:209], v[20:23]
	v_mfma_f32_16x16x32_bf16 v[16:19], v[152:155], v[206:209], v[16:19]
	v_mfma_f32_16x16x32_bf16 v[60:63], v[148:151], v[186:189], v[60:63]
	v_mfma_f32_16x16x32_bf16 v[56:59], v[156:159], v[186:189], v[56:59]
	v_mfma_f32_16x16x32_bf16 v[52:55], v[148:151], v[194:197], v[52:55]
	v_mfma_f32_16x16x32_bf16 v[48:51], v[156:159], v[194:197], v[48:51]
	v_mfma_f32_16x16x32_bf16 v[36:39], v[148:151], v[202:205], v[36:39]
	v_mfma_f32_16x16x32_bf16 v[32:35], v[156:159], v[202:205], v[32:35]
	v_mfma_f32_16x16x32_bf16 v[20:23], v[148:151], v[210:213], v[20:23]
	v_mfma_f32_16x16x32_bf16 v[16:19], v[156:159], v[210:213], v[16:19]
	s_setprio 0
	s_setprio 1
	v_mfma_f32_16x16x32_bf16 v[44:47], v[160:163], v[182:185], v[44:47]
	v_mfma_f32_16x16x32_bf16 v[40:43], v[170:173], v[182:185], v[40:43]
	v_mfma_f32_16x16x32_bf16 v[28:31], v[160:163], v[190:193], v[28:31]
	v_mfma_f32_16x16x32_bf16 v[24:27], v[170:173], v[190:193], v[24:27]
	v_mfma_f32_16x16x32_bf16 v[12:15], v[160:163], v[198:201], v[12:15]
	v_mfma_f32_16x16x32_bf16 v[8:11], v[170:173], v[198:201], v[8:11]
	v_mfma_f32_16x16x32_bf16 v[4:7], v[160:163], v[206:209], v[4:7]
	v_mfma_f32_16x16x32_bf16 v[0:3], v[170:173], v[206:209], v[0:3]
	v_mfma_f32_16x16x32_bf16 v[44:47], v[164:167], v[186:189], v[44:47]
	v_mfma_f32_16x16x32_bf16 v[40:43], v[178:181], v[186:189], v[40:43]
	v_mfma_f32_16x16x32_bf16 v[28:31], v[164:167], v[194:197], v[28:31]
	v_mfma_f32_16x16x32_bf16 v[24:27], v[178:181], v[194:197], v[24:27]
	v_mfma_f32_16x16x32_bf16 v[12:15], v[164:167], v[202:205], v[12:15]
	v_mfma_f32_16x16x32_bf16 v[8:11], v[178:181], v[202:205], v[8:11]
	v_mfma_f32_16x16x32_bf16 v[4:7], v[164:167], v[210:213], v[4:7]
	v_mfma_f32_16x16x32_bf16 v[0:3], v[178:181], v[210:213], v[0:3]
	s_setprio 0
	s_barrier
	s_add_i32 s3, s3, 2
	s_add_u32 s86, s86, 0x100
	s_addc_u32 s87, s87, 0
	s_add_u32 vcc_hi, vcc_hi, 0x100
	s_addc_u32 s2, s2, 0
	s_cmp_gt_u32 s3, 13
	s_cbranch_scc0 .LBB0_626
	s_and_b64 vcc, exec, s[72:73]
	s_cbranch_vccz .LBB0_629
	s_barrier

; __device__ __forceinline__ void attn_chain(LAS unsigned char* lds, const bf16* Qb, const bf16* Kb, const bf16* Vb, bf16* Ob, float* lseb, int g0, int wave, int lane) {
;     ...
;     asm volatile("s_waitcnt vmcnt(0) lgkmcnt(0)" ::: "memory");
;     __builtin_amdgcn_s_barrier();
;     asm volatile("" ::: "memory");
; __device__ __forceinline__ void attn_phase(LAS unsigned char* lds, const bf16* Q, const bf16* K, const bf16* V, bf16* OP, float* LSE, int wave, int lane, int bx, int G) {
;     for (int item = bx; item < 256; item += G) {
;         const int xg = item & 7, lw = item >> 3, bh = 4 * xg + (lw >> 3), b = bh >> 3, h = bh & 7, cseg = lw & 7;
;         const size_t base = (size_t)b * SEQ * 1024 + h * 128;
;         attn_chain(lds, Q + base, K + base, V + base, OP + base, LSE + (size_t)b * SEQ * 8 + h, 48 * cseg, wave, lane);
.LBB0_639:
	s_or_b64 exec, exec, s[6:7]
	s_waitcnt vmcnt(0) lgkmcnt(0)
	s_barrier
	s_setprio 0
	s_add_i32 s21, s21, s51
	s_cmpk_lt_i32 s21, 0x100
	s_cbranch_scc0 .LBB0_714
.LBB0_640:
	v_readlane_b32 s100, v255, 21
	s_nop 1
	s_cmp_lt_u32 s100, 4
	s_cbranch_scc1 .Lattn_prio_skip
	s_setprio 1

; #define PG8_STAGE(bufoff, gbase, voff) do { _Pragma("unroll") for (int _i = 0; _i < 2; ++_i) \
;         __builtin_amdgcn_global_load_lds((const unsigned*)((const char*)(gbase) + (voff)[_i]), (PG8_LAS unsigned*)(lds + (bufoff) + ldsw + _i * 8192), 16, 0, 0); } while (0)
; #define PG8_LDA(dst, b, h) do { _Pragma("unroll") for (int m = 0; m < 4; ++m) _Pragma("unroll") for (int k = 0; k < 2; ++k) dst[m][k] = *(const PG8_LAS bf16x8*)(lds + PG8_SA(b, h) + aoff + m * 2048 + k * 1024); } while (0)
; #define PG8_LDB(dst, b, h) do { _Pragma("unroll") for (int n = 0; n < 2; ++n) _Pragma("unroll") for (int k = 0; k < 2; ++k) dst[n][k] = *(const PG8_LAS bf16x8*)(lds + PG8_SB(b, h) + boff + n * 2048 + k * 1024); } while (0)
; #define PG8_MMA(ai, bj, At, Bt) do { __builtin_amdgcn_s_setprio(1); _Pragma("unroll") for (int m = 0; m < 4; ++m) _Pragma("unroll") for (int n = 0; n < 2; ++n) _Pragma("unroll") for (int k = 0; k < 2; ++k) \
;         acc[ai][bj][m][n] = __builtin_amdgcn_mfma_f32_16x16x32_bf16(Bt[n][k], At[m][k], acc[ai][bj][m][n], 0, 0, 0); __builtin_amdgcn_s_setprio(0); } while (0)
; #define PG8_WAIT_V(n) asm volatile("s_waitcnt vmcnt(" #n ")" ::: "memory")
; #define PG8_WAIT_L(n) asm volatile("s_waitcnt lgkmcnt(" #n ")" ::: "memory")
; #define PG8_BAR __builtin_amdgcn_s_barrier()
; #define PG8_SCHED __builtin_amdgcn_sched_barrier(0)
;     ...
;             const bool last = (t == nt - 2);
;             const char* a1 = PG8_KADV(cA, (size_t)(t + 1) * kstep);
;             const char* a2 = last ? nA : PG8_KADV(cA, (size_t)(t + 2) * kstep); const char* b2 = last ? nB : PG8_KADV(cB, (size_t)(t + 2) * kstep);
;             const char* a3 = PG8_KADV(a2, kstep); const char* b3 = PG8_KADV(b2, kstep);
;             if (last && has_next) S.a_ready(nxt);
;             if constexpr (SP2) {
;             PG8_LDB(B0, 0, 0); PG8_LDB(B1, 0, 1); PG8_SCHED; PG8_LDA(At, 0, 0); PG8_STAGE(PG8_SA(1, 1), a1 + hstep, voffA);
;             PG8_WAIT_V(8); PG8_WAIT_L(0); PG8_BAR; PG8_MMA(0, 0, At, B0); PG8_MMA(0, 1, At, B1); PG8_BAR; PG8_SCHED;
;             PG8_LDA(At, 0, 1); PG8_STAGE(PG8_SB(0, 0), b2, voffB); PG8_STAGE(PG8_SB(0, 1), b2 + hstep, voffB); PG8_STAGE(PG8_SA(0, 0), a2, voffA);
;             PG8_WAIT_V(8); PG8_WAIT_L(0); PG8_BAR; PG8_MMA(1, 0, At, B0); PG8_MMA(1, 1, At, B1); PG8_BAR; PG8_SCHED;
.LBB0_856:
	s_add_u32 s12, s82, 0xfff80080
	s_addc_u32 s13, s83, -1
	s_add_i32 s31, 0, 0x10000
	s_cmp_eq_u32 s3, 28
	s_cselect_b32 s87, s15, s13
	s_cselect_b32 s86, s23, s12
	s_cselect_b32 s85, s25, s2
	s_cselect_b32 s84, s28, s30
	s_add_i32 s33, 0, 0x14000
	v_add_u32_e32 v140, s31, v166
	v_add_u32_e32 v164, s33, v166
	ds_read_b128 v[128:131], v140
	ds_read_b128 v[132:135], v140 offset:1024
	ds_read_b128 v[136:139], v140 offset:2048
	ds_read_b128 v[140:143], v140 offset:3072
	ds_read_b128 v[144:147], v164
	ds_read_b128 v[148:151], v164 offset:1024
	ds_read_b128 v[170:173], v164 offset:2048
	ds_read_b128 v[178:181], v164 offset:3072
	s_add_i32 m0, s9, 0xc000
	ds_read_b128 v[184:187], v183
	ds_read_b128 v[188:191], v183 offset:1024
	ds_read_b128 v[192:195], v183 offset:2048
	ds_read_b128 v[196:199], v183 offset:3072
	ds_read_b128 v[200:203], v183 offset:4096
	ds_read_b128 v[204:207], v183 offset:5120
	ds_read_b128 v[208:211], v183 offset:6144
	ds_read_b128 v[212:215], v183 offset:7168
	global_load_lds_dwordx4 v160, s[82:83]
	s_add_i32 m0, s9, 0xe000
	s_nop 0
	global_load_lds_dwordx4 v162, s[82:83]
	s_waitcnt vmcnt(8)
	s_waitcnt lgkmcnt(0)
	s_barrier
	s_setprio 1
	s_waitcnt lgkmcnt(0)
	v_mfma_f32_16x16x32_bf16 v[124:127], v[128:131], v[184:187], v[124:127]
	v_mfma_f32_16x16x32_bf16 v[120:123], v[136:139], v[184:187], v[120:123]
	v_mfma_f32_16x16x32_bf16 v[112:115], v[128:131], v[192:195], v[112:115]
	v_mfma_f32_16x16x32_bf16 v[104:107], v[136:139], v[192:195], v[104:107]
	v_mfma_f32_16x16x32_bf16 v[92:95], v[128:131], v[200:203], v[92:95]
	v_mfma_f32_16x16x32_bf16 v[88:91], v[136:139], v[200:203], v[88:91]
	v_mfma_f32_16x16x32_bf16 v[80:83], v[128:131], v[208:211], v[80:83]
	v_mfma_f32_16x16x32_bf16 v[72:75], v[136:139], v[208:211], v[72:75]
	v_mfma_f32_16x16x32_bf16 v[124:127], v[132:135], v[188:191], v[124:127]
	v_mfma_f32_16x16x32_bf16 v[120:123], v[140:143], v[188:191], v[120:123]
	v_mfma_f32_16x16x32_bf16 v[112:115], v[132:135], v[196:199], v[112:115]
	v_mfma_f32_16x16x32_bf16 v[104:107], v[140:143], v[196:199], v[104:107]
	v_mfma_f32_16x16x32_bf16 v[92:95], v[132:135], v[204:207], v[92:95]
	v_mfma_f32_16x16x32_bf16 v[88:91], v[140:143], v[204:207], v[88:91]
	v_mfma_f32_16x16x32_bf16 v[80:83], v[132:135], v[212:215], v[80:83]
	v_mfma_f32_16x16x32_bf16 v[72:75], v[140:143], v[212:215], v[72:75]
	s_setprio 0
	s_setprio 1
	v_mfma_f32_16x16x32_bf16 v[116:119], v[144:147], v[184:187], v[116:119]
	v_mfma_f32_16x16x32_bf16 v[108:111], v[170:173], v[184:187], v[108:111]
	v_mfma_f32_16x16x32_bf16 v[100:103], v[144:147], v[192:195], v[100:103]
	v_mfma_f32_16x16x32_bf16 v[96:99], v[170:173], v[192:195], v[96:99]
	v_mfma_f32_16x16x32_bf16 v[84:87], v[144:147], v[200:203], v[84:87]
	v_mfma_f32_16x16x32_bf16 v[76:79], v[170:173], v[200:203], v[76:79]
	v_mfma_f32_16x16x32_bf16 v[68:71], v[144:147], v[208:211], v[68:71]
	v_mfma_f32_16x16x32_bf16 v[64:67], v[170:173], v[208:211], v[64:67]
	v_mfma_f32_16x16x32_bf16 v[116:119], v[148:151], v[188:191], v[116:119]
	v_mfma_f32_16x16x32_bf16 v[108:111], v[178:181], v[188:191], v[108:111]
	v_mfma_f32_16x16x32_bf16 v[100:103], v[148:151], v[196:199], v[100:103]
	v_mfma_f32_16x16x32_bf16 v[96:99], v[178:181], v[196:199], v[96:99]
	v_mfma_f32_16x16x32_bf16 v[84:87], v[148:151], v[204:207], v[84:87]
	v_mfma_f32_16x16x32_bf16 v[76:79], v[178:181], v[204:207], v[76:79]
	v_mfma_f32_16x16x32_bf16 v[68:71], v[148:151], v[212:215], v[68:71]
	v_mfma_f32_16x16x32_bf16 v[64:67], v[178:181], v[212:215], v[64:67]
	s_setprio 0
	s_barrier
	s_add_i32 s12, s31, s8
	s_mov_b32 m0, s12
	ds_read_b128 v[184:187], v183 offset:16384
	ds_read_b128 v[188:191], v183 offset:17408
	ds_read_b128 v[192:195], v183 offset:18432
	ds_read_b128 v[196:199], v183 offset:19456
	ds_read_b128 v[200:203], v183 offset:20480
	ds_read_b128 v[204:207], v183 offset:21504
	ds_read_b128 v[208:211], v183 offset:22528
	ds_read_b128 v[212:215], v183 offset:23552
	global_load_lds_dwordx4 v154, s[84:85]
	s_add_i32 m0, s12, 0x2000
	s_add_u32 s12, s84, 0x80000
	s_addc_u32 s13, s85, 0
	s_add_i32 s31, s33, s8
	global_load_lds_dwordx4 v158, s[84:85]
	s_mov_b32 m0, s31
	s_nop 0
	global_load_lds_dwordx4 v154, s[12:13]
	s_add_i32 m0, s31, 0x2000
	s_nop 0
	global_load_lds_dwordx4 v158, s[12:13]
	s_mov_b32 m0, s9
	s_nop 0
	global_load_lds_dwordx4 v152, s[86:87]
	s_mov_b32 m0, s10
	s_nop 0
	global_load_lds_dwordx4 v156, s[86:87]
	s_waitcnt vmcnt(8)
	s_waitcnt lgkmcnt(0)
	s_barrier
	s_setprio 1
	s_waitcnt lgkmcnt(0)
	v_mfma_f32_16x16x32_bf16 v[60:63], v[128:131], v[184:187], v[60:63]
	v_mfma_f32_16x16x32_bf16 v[56:59], v[136:139], v[184:187], v[56:59]
	v_mfma_f32_16x16x32_bf16 v[48:51], v[128:131], v[192:195], v[48:51]
	v_mfma_f32_16x16x32_bf16 v[40:43], v[136:139], v[192:195], v[40:43]
	v_mfma_f32_16x16x32_bf16 v[28:31], v[128:131], v[200:203], v[28:31]
	v_mfma_f32_16x16x32_bf16 v[24:27], v[136:139], v[200:203], v[24:27]
	v_mfma_f32_16x16x32_bf16 v[16:19], v[128:131], v[208:211], v[16:19]
	v_mfma_f32_16x16x32_bf16 v[8:11], v[136:139], v[208:211], v[8:11]
	v_mfma_f32_16x16x32_bf16 v[60:63], v[132:135], v[188:191], v[60:63]
	v_mfma_f32_16x16x32_bf16 v[56:59], v[140:143], v[188:191], v[56:59]
	v_mfma_f32_16x16x32_bf16 v[48:51], v[132:135], v[196:199], v[48:51]
	v_mfma_f32_16x16x32_bf16 v[40:43], v[140:143], v[196:199], v[40:43]
	v_mfma_f32_16x16x32_bf16 v[28:31], v[132:135], v[204:207], v[28:31]
	v_mfma_f32_16x16x32_bf16 v[24:27], v[140:143], v[204:207], v[24:27]
	v_mfma_f32_16x16x32_bf16 v[16:19], v[132:135], v[212:215], v[16:19]
	v_mfma_f32_16x16x32_bf16 v[8:11], v[140:143], v[212:215], v[8:11]
	s_setprio 0
	s_setprio 1
	v_mfma_f32_16x16x32_bf16 v[52:55], v[144:147], v[184:187], v[52:55]
	v_mfma_f32_16x16x32_bf16 v[44:47], v[170:173], v[184:187], v[44:47]
	v_mfma_f32_16x16x32_bf16 v[36:39], v[144:147], v[192:195], v[36:39]
	v_mfma_f32_16x16x32_bf16 v[32:35], v[170:173], v[192:195], v[32:35]
	v_mfma_f32_16x16x32_bf16 v[20:23], v[144:147], v[200:203], v[20:23]
	v_mfma_f32_16x16x32_bf16 v[12:15], v[170:173], v[200:203], v[12:15]
	v_mfma_f32_16x16x32_bf16 v[4:7], v[144:147], v[208:211], v[4:7]
	v_mfma_f32_16x16x32_bf16 v[0:3], v[170:173], v[208:211], v[0:3]
	v_mfma_f32_16x16x32_bf16 v[52:55], v[148:151], v[188:191], v[52:55]
	v_mfma_f32_16x16x32_bf16 v[44:47], v[178:181], v[188:191], v[44:47]
	v_mfma_f32_16x16x32_bf16 v[36:39], v[148:151], v[196:199], v[36:39]
	v_mfma_f32_16x16x32_bf16 v[32:35], v[178:181], v[196:199], v[32:35]
	v_mfma_f32_16x16x32_bf16 v[20:23], v[148:151], v[204:207], v[20:23]
	v_mfma_f32_16x16x32_bf16 v[12:15], v[178:181], v[204:207], v[12:15]
	v_mfma_f32_16x16x32_bf16 v[4:7], v[148:151], v[212:215], v[4:7]
	v_mfma_f32_16x16x32_bf16 v[0:3], v[178:181], v[212:215], v[0:3]
	s_setprio 0
	s_barrier
; #define PG8_STAGE(bufoff, gbase, voff) do { _Pragma("unroll") for (int _i = 0; _i < 2; ++_i) \
;         __builtin_amdgcn_global_load_lds((const unsigned*)((const char*)(gbase) + (voff)[_i]), (PG8_LAS unsigned*)(lds + (bufoff) + ldsw + _i * 8192), 16, 0, 0); } while (0)
; #define PG8_LDA(dst, b, h) do { _Pragma("unroll") for (int m = 0; m < 4; ++m) _Pragma("unroll") for (int k = 0; k < 2; ++k) dst[m][k] = *(const PG8_LAS bf16x8*)(lds + PG8_SA(b, h) + aoff + m * 2048 + k * 1024); } while (0)
; #define PG8_LDB(dst, b, h) do { _Pragma("unroll") for (int n = 0; n < 2; ++n) _Pragma("unroll") for (int k = 0; k < 2; ++k) dst[n][k] = *(const PG8_LAS bf16x8*)(lds + PG8_SB(b, h) + boff + n * 2048 + k * 1024); } while (0)
; #define PG8_MMA(ai, bj, At, Bt) do { __builtin_amdgcn_s_setprio(1); _Pragma("unroll") for (int m = 0; m < 4; ++m) _Pragma("unroll") for (int n = 0; n < 2; ++n) _Pragma("unroll") for (int k = 0; k < 2; ++k) \
;         acc[ai][bj][m][n] = __builtin_amdgcn_mfma_f32_16x16x32_bf16(Bt[n][k], At[m][k], acc[ai][bj][m][n], 0, 0, 0); __builtin_amdgcn_s_setprio(0); } while (0)
; #define PG8_WAIT_V(n) asm volatile("s_waitcnt vmcnt(" #n ")" ::: "memory")
; #define PG8_WAIT_L(n) asm volatile("s_waitcnt lgkmcnt(" #n ")" ::: "memory")
; #define PG8_BAR __builtin_amdgcn_s_barrier()
; #define PG8_SCHED __builtin_amdgcn_sched_barrier(0)
;     ...
;             PG8_LDB(B0, 1, 0); PG8_LDB(B1, 1, 1); PG8_SCHED; PG8_LDA(At, 1, 0); PG8_STAGE(PG8_SA(0, 1), a2 + hstep, voffA);
;             PG8_WAIT_V(8); PG8_WAIT_L(0); PG8_BAR; PG8_MMA(0, 0, At, B0); PG8_MMA(0, 1, At, B1); PG8_BAR; PG8_SCHED;
;             PG8_LDA(At, 1, 1); PG8_STAGE(PG8_SB(1, 0), b3, voffB); PG8_STAGE(PG8_SB(1, 1), b3 + hstep, voffB); PG8_STAGE(PG8_SA(1, 0), a3, voffA);
;             PG8_WAIT_V(8); PG8_WAIT_L(0); PG8_BAR; PG8_MMA(1, 0, At, B0); PG8_MMA(1, 1, At, B1); PG8_BAR; PG8_SCHED;
	s_add_i32 s31, 0, 0x18000
	s_add_i32 s33, 0, 0x1c000
	v_add_u32_e32 v140, s31, v166
	v_add_u32_e32 v168, s33, v166
	ds_read_b128 v[128:131], v140
	ds_read_b128 v[132:135], v140 offset:1024
	ds_read_b128 v[136:139], v140 offset:2048
	ds_read_b128 v[140:143], v140 offset:3072
	ds_read_b128 v[144:147], v168
	ds_read_b128 v[148:151], v168 offset:1024
	ds_read_b128 v[170:173], v168 offset:2048
	ds_read_b128 v[178:181], v168 offset:3072
	s_add_u32 s12, s86, 0x80000
	s_addc_u32 s13, s87, 0
	s_mov_b32 m0, s18
	ds_read_b128 v[184:187], v183 offset:32768
	ds_read_b128 v[188:191], v183 offset:33792
	ds_read_b128 v[192:195], v183 offset:34816
	ds_read_b128 v[196:199], v183 offset:35840
	ds_read_b128 v[200:203], v183 offset:36864
	ds_read_b128 v[204:207], v183 offset:37888
	ds_read_b128 v[208:211], v183 offset:38912
	ds_read_b128 v[212:215], v183 offset:39936
	global_load_lds_dwordx4 v152, s[12:13]
	s_mov_b32 m0, s19
	s_nop 0
	global_load_lds_dwordx4 v156, s[12:13]
	s_waitcnt vmcnt(8)
	s_waitcnt lgkmcnt(0)
	s_barrier
	s_setprio 1
	s_waitcnt lgkmcnt(0)
	v_mfma_f32_16x16x32_bf16 v[124:127], v[128:131], v[184:187], v[124:127]
	v_mfma_f32_16x16x32_bf16 v[120:123], v[136:139], v[184:187], v[120:123]
	v_mfma_f32_16x16x32_bf16 v[112:115], v[128:131], v[192:195], v[112:115]
	v_mfma_f32_16x16x32_bf16 v[104:107], v[136:139], v[192:195], v[104:107]
	v_mfma_f32_16x16x32_bf16 v[92:95], v[128:131], v[200:203], v[92:95]
	v_mfma_f32_16x16x32_bf16 v[88:91], v[136:139], v[200:203], v[88:91]
	v_mfma_f32_16x16x32_bf16 v[80:83], v[128:131], v[208:211], v[80:83]
	v_mfma_f32_16x16x32_bf16 v[72:75], v[136:139], v[208:211], v[72:75]
	v_mfma_f32_16x16x32_bf16 v[124:127], v[132:135], v[188:191], v[124:127]
	v_mfma_f32_16x16x32_bf16 v[120:123], v[140:143], v[188:191], v[120:123]
	v_mfma_f32_16x16x32_bf16 v[112:115], v[132:135], v[196:199], v[112:115]
	v_mfma_f32_16x16x32_bf16 v[104:107], v[140:143], v[196:199], v[104:107]
	v_mfma_f32_16x16x32_bf16 v[92:95], v[132:135], v[204:207], v[92:95]
	v_mfma_f32_16x16x32_bf16 v[88:91], v[140:143], v[204:207], v[88:91]
	v_mfma_f32_16x16x32_bf16 v[80:83], v[132:135], v[212:215], v[80:83]
	v_mfma_f32_16x16x32_bf16 v[72:75], v[140:143], v[212:215], v[72:75]
	s_setprio 0
	s_setprio 1
	v_mfma_f32_16x16x32_bf16 v[116:119], v[144:147], v[184:187], v[116:119]
	v_mfma_f32_16x16x32_bf16 v[108:111], v[170:173], v[184:187], v[108:111]
	v_mfma_f32_16x16x32_bf16 v[100:103], v[144:147], v[192:195], v[100:103]
	v_mfma_f32_16x16x32_bf16 v[96:99], v[170:173], v[192:195], v[96:99]
	v_mfma_f32_16x16x32_bf16 v[84:87], v[144:147], v[200:203], v[84:87]
	v_mfma_f32_16x16x32_bf16 v[76:79], v[170:173], v[200:203], v[76:79]
	v_mfma_f32_16x16x32_bf16 v[68:71], v[144:147], v[208:211], v[68:71]
	v_mfma_f32_16x16x32_bf16 v[64:67], v[170:173], v[208:211], v[64:67]
	v_mfma_f32_16x16x32_bf16 v[116:119], v[148:151], v[188:191], v[116:119]
	v_mfma_f32_16x16x32_bf16 v[108:111], v[178:181], v[188:191], v[108:111]
	v_mfma_f32_16x16x32_bf16 v[100:103], v[148:151], v[196:199], v[100:103]
	v_mfma_f32_16x16x32_bf16 v[96:99], v[178:181], v[196:199], v[96:99]
	v_mfma_f32_16x16x32_bf16 v[84:87], v[148:151], v[204:207], v[84:87]
	v_mfma_f32_16x16x32_bf16 v[76:79], v[178:181], v[204:207], v[76:79]
	v_mfma_f32_16x16x32_bf16 v[68:71], v[148:151], v[212:215], v[68:71]
	v_mfma_f32_16x16x32_bf16 v[64:67], v[178:181], v[212:215], v[64:67]
	s_setprio 0
	s_barrier
	s_add_i32 s12, s31, s8
	s_mov_b32 m0, s12
	ds_read_b128 v[184:187], v183 offset:49152
	ds_read_b128 v[188:191], v183 offset:50176
	ds_read_b128 v[192:195], v183 offset:51200
	ds_read_b128 v[196:199], v183 offset:52224
	ds_read_b128 v[200:203], v183 offset:53248
	ds_read_b128 v[204:207], v183 offset:54272
	ds_read_b128 v[208:211], v183 offset:55296
	ds_read_b128 v[212:215], v183 offset:56320
	s_add_u32 s100, s84, s16
	s_addc_u32 s101, s85, s17
	global_load_lds_dwordx4 v154, s[100:101]
	s_add_i32 m0, s12, 0x2000
	s_add_u32 s12, s84, 0x80080
	s_addc_u32 s13, s85, 0
	s_add_i32 s31, s33, s8
	global_load_lds_dwordx4 v158, s[100:101]
	s_mov_b32 m0, s31
	s_nop 0
	global_load_lds_dwordx4 v154, s[12:13]
	s_add_i32 m0, s31, 0x2000
	s_nop 0
	global_load_lds_dwordx4 v158, s[12:13]
	s_mov_b32 m0, s20
	s_nop 0
	s_add_u32 s100, s86, s16
	s_addc_u32 s101, s87, s17
	global_load_lds_dwordx4 v152, s[100:101]
	s_mov_b32 m0, s21
	s_nop 0
	global_load_lds_dwordx4 v156, s[100:101]
	s_waitcnt vmcnt(8)
	s_waitcnt lgkmcnt(0)
	s_barrier
	s_setprio 1
	s_waitcnt lgkmcnt(0)
	v_mfma_f32_16x16x32_bf16 v[60:63], v[128:131], v[184:187], v[60:63]
	v_mfma_f32_16x16x32_bf16 v[56:59], v[136:139], v[184:187], v[56:59]
	v_mfma_f32_16x16x32_bf16 v[48:51], v[128:131], v[192:195], v[48:51]
	v_mfma_f32_16x16x32_bf16 v[40:43], v[136:139], v[192:195], v[40:43]
	v_mfma_f32_16x16x32_bf16 v[28:31], v[128:131], v[200:203], v[28:31]
	v_mfma_f32_16x16x32_bf16 v[24:27], v[136:139], v[200:203], v[24:27]
	v_mfma_f32_16x16x32_bf16 v[16:19], v[128:131], v[208:211], v[16:19]
	v_mfma_f32_16x16x32_bf16 v[8:11], v[136:139], v[208:211], v[8:11]
	v_mfma_f32_16x16x32_bf16 v[60:63], v[132:135], v[188:191], v[60:63]
	v_mfma_f32_16x16x32_bf16 v[56:59], v[140:143], v[188:191], v[56:59]
	v_mfma_f32_16x16x32_bf16 v[48:51], v[132:135], v[196:199], v[48:51]
	v_mfma_f32_16x16x32_bf16 v[40:43], v[140:143], v[196:199], v[40:43]
	v_mfma_f32_16x16x32_bf16 v[28:31], v[132:135], v[204:207], v[28:31]
	v_mfma_f32_16x16x32_bf16 v[24:27], v[140:143], v[204:207], v[24:27]
	v_mfma_f32_16x16x32_bf16 v[16:19], v[132:135], v[212:215], v[16:19]
	v_mfma_f32_16x16x32_bf16 v[8:11], v[140:143], v[212:215], v[8:11]
	s_setprio 0
	s_setprio 1
	v_mfma_f32_16x16x32_bf16 v[52:55], v[144:147], v[184:187], v[52:55]
	v_mfma_f32_16x16x32_bf16 v[44:47], v[170:173], v[184:187], v[44:47]
	v_mfma_f32_16x16x32_bf16 v[36:39], v[144:147], v[192:195], v[36:39]
	v_mfma_f32_16x16x32_bf16 v[32:35], v[170:173], v[192:195], v[32:35]
	v_mfma_f32_16x16x32_bf16 v[20:23], v[144:147], v[200:203], v[20:23]
	v_mfma_f32_16x16x32_bf16 v[12:15], v[170:173], v[200:203], v[12:15]
	v_mfma_f32_16x16x32_bf16 v[4:7], v[144:147], v[208:211], v[4:7]
	v_mfma_f32_16x16x32_bf16 v[0:3], v[170:173], v[208:211], v[0:3]
	v_mfma_f32_16x16x32_bf16 v[52:55], v[148:151], v[188:191], v[52:55]
	v_mfma_f32_16x16x32_bf16 v[44:47], v[178:181], v[188:191], v[44:47]
	v_mfma_f32_16x16x32_bf16 v[36:39], v[148:151], v[196:199], v[36:39]
	v_mfma_f32_16x16x32_bf16 v[32:35], v[178:181], v[196:199], v[32:35]
	v_mfma_f32_16x16x32_bf16 v[20:23], v[148:151], v[204:207], v[20:23]
	v_mfma_f32_16x16x32_bf16 v[12:15], v[178:181], v[204:207], v[12:15]
	v_mfma_f32_16x16x32_bf16 v[4:7], v[148:151], v[212:215], v[4:7]
	v_mfma_f32_16x16x32_bf16 v[0:3], v[178:181], v[212:215], v[0:3]
	s_setprio 0
	s_barrier
	s_add_i32 s3, s3, 2
	s_add_u32 s82, s82, 0x100
	s_addc_u32 s83, s83, 0
	s_add_u32 s30, s30, 0x100
	s_addc_u32 s2, s2, 0
	s_cmp_gt_u32 s3, 29
	s_cbranch_scc0 .LBB0_856
	s_and_b64 vcc, exec, s[70:71]
	s_cbranch_vccz .LBB0_859
	s_barrier

; #define PG8_STAGE(bufoff, gbase, voff) do { _Pragma("unroll") for (int _i = 0; _i < 2; ++_i) \
;         __builtin_amdgcn_global_load_lds((const unsigned*)((const char*)(gbase) + (voff)[_i]), (PG8_LAS unsigned*)(lds + (bufoff) + ldsw + _i * 8192), 16, 0, 0); } while (0)
; #define PG8_LDA(dst, b, h) do { _Pragma("unroll") for (int m = 0; m < 4; ++m) _Pragma("unroll") for (int k = 0; k < 2; ++k) dst[m][k] = *(const PG8_LAS bf16x8*)(lds + PG8_SA(b, h) + aoff + m * 2048 + k * 1024); } while (0)
; #define PG8_LDB(dst, b, h) do { _Pragma("unroll") for (int n = 0; n < 2; ++n) _Pragma("unroll") for (int k = 0; k < 2; ++k) dst[n][k] = *(const PG8_LAS bf16x8*)(lds + PG8_SB(b, h) + boff + n * 2048 + k * 1024); } while (0)
; #define PG8_MMA(ai, bj, At, Bt) do { __builtin_amdgcn_s_setprio(1); _Pragma("unroll") for (int m = 0; m < 4; ++m) _Pragma("unroll") for (int n = 0; n < 2; ++n) _Pragma("unroll") for (int k = 0; k < 2; ++k) \
;         acc[ai][bj][m][n] = __builtin_amdgcn_mfma_f32_16x16x32_bf16(Bt[n][k], At[m][k], acc[ai][bj][m][n], 0, 0, 0); __builtin_amdgcn_s_setprio(0); } while (0)
; #define PG8_WAIT_V(n) asm volatile("s_waitcnt vmcnt(" #n ")" ::: "memory")
; #define PG8_WAIT_L(n) asm volatile("s_waitcnt lgkmcnt(" #n ")" ::: "memory")
; #define PG8_BAR __builtin_amdgcn_s_barrier()
; #define PG8_SCHED __builtin_amdgcn_sched_barrier(0)
;     ...
;             const bool last = (t == nt - 2);
;             const char* a1 = PG8_KADV(cA, (size_t)(t + 1) * kstep);
;             const char* a2 = last ? nA : PG8_KADV(cA, (size_t)(t + 2) * kstep); const char* b2 = last ? nB : PG8_KADV(cB, (size_t)(t + 2) * kstep);
;             const char* a3 = PG8_KADV(a2, kstep); const char* b3 = PG8_KADV(b2, kstep);
;             if (last && has_next) S.a_ready(nxt);
;             if constexpr (SP2) {
;             PG8_LDB(B0, 0, 0); PG8_LDB(B1, 0, 1); PG8_SCHED; PG8_LDA(At, 0, 0); PG8_STAGE(PG8_SA(1, 1), a1 + hstep, voffA);
;             PG8_WAIT_V(8); PG8_WAIT_L(0); PG8_BAR; PG8_MMA(0, 0, At, B0); PG8_MMA(0, 1, At, B1); PG8_BAR; PG8_SCHED;
;             PG8_LDA(At, 0, 1); PG8_STAGE(PG8_SB(0, 0), b2, voffB); PG8_STAGE(PG8_SB(0, 1), b2 + hstep, voffB); PG8_STAGE(PG8_SA(0, 0), a2, voffA);
;             PG8_WAIT_V(8); PG8_WAIT_L(0); PG8_BAR; PG8_MMA(1, 0, At, B0); PG8_MMA(1, 1, At, B1); PG8_BAR; PG8_SCHED;
.LBB0_983:
	s_add_u32 s12, s70, 0xfff80080
	s_addc_u32 s13, s71, -1
	s_add_i32 s31, 0, 0x10000
	s_cmp_eq_u32 s3, 28
	s_cselect_b32 s75, s15, s13
	s_cselect_b32 s74, s28, s12
	s_cselect_b32 s73, s30, s2
	s_cselect_b32 s72, s33, s40
	s_add_i32 s42, 0, 0x14000
	v_add_u32_e32 v156, s31, v141
	v_add_u32_e32 v168, s42, v141
	ds_read_b128 v[144:147], v156
	ds_read_b128 v[148:151], v156 offset:1024
	ds_read_b128 v[152:155], v156 offset:2048
	ds_read_b128 v[156:159], v156 offset:3072
	ds_read_b128 v[160:163], v168
	ds_read_b128 v[164:167], v168 offset:1024
	ds_read_b128 v[170:173], v168 offset:2048
	ds_read_b128 v[178:181], v168 offset:3072
	s_add_i32 m0, s18, 0xc000
	ds_read_b128 v[182:185], v143
	ds_read_b128 v[186:189], v143 offset:1024
	ds_read_b128 v[190:193], v143 offset:2048
	ds_read_b128 v[194:197], v143 offset:3072
	ds_read_b128 v[198:201], v143 offset:4096
	ds_read_b128 v[202:205], v143 offset:5120
	ds_read_b128 v[206:209], v143 offset:6144
	ds_read_b128 v[210:213], v143 offset:7168
	global_load_lds_dwordx4 v136, s[70:71]
	s_add_i32 m0, s18, 0xe000
	s_nop 0
	global_load_lds_dwordx4 v138, s[70:71]
	s_waitcnt vmcnt(8)
	s_waitcnt lgkmcnt(0)
	s_barrier
	s_setprio 1
	s_waitcnt lgkmcnt(0)
	v_mfma_f32_16x16x32_bf16 v[124:127], v[144:147], v[182:185], v[124:127]
	v_mfma_f32_16x16x32_bf16 v[120:123], v[152:155], v[182:185], v[120:123]
	v_mfma_f32_16x16x32_bf16 v[108:111], v[144:147], v[190:193], v[108:111]
	v_mfma_f32_16x16x32_bf16 v[104:107], v[152:155], v[190:193], v[104:107]
	v_mfma_f32_16x16x32_bf16 v[92:95], v[144:147], v[198:201], v[92:95]
	v_mfma_f32_16x16x32_bf16 v[88:91], v[152:155], v[198:201], v[88:91]
	v_mfma_f32_16x16x32_bf16 v[76:79], v[144:147], v[206:209], v[76:79]
	v_mfma_f32_16x16x32_bf16 v[72:75], v[152:155], v[206:209], v[72:75]
	v_mfma_f32_16x16x32_bf16 v[124:127], v[148:151], v[186:189], v[124:127]
	v_mfma_f32_16x16x32_bf16 v[120:123], v[156:159], v[186:189], v[120:123]
	v_mfma_f32_16x16x32_bf16 v[108:111], v[148:151], v[194:197], v[108:111]
	v_mfma_f32_16x16x32_bf16 v[104:107], v[156:159], v[194:197], v[104:107]
	v_mfma_f32_16x16x32_bf16 v[92:95], v[148:151], v[202:205], v[92:95]
	v_mfma_f32_16x16x32_bf16 v[88:91], v[156:159], v[202:205], v[88:91]
	v_mfma_f32_16x16x32_bf16 v[76:79], v[148:151], v[210:213], v[76:79]
	v_mfma_f32_16x16x32_bf16 v[72:75], v[156:159], v[210:213], v[72:75]
	s_setprio 0
	s_setprio 1
	v_mfma_f32_16x16x32_bf16 v[116:119], v[160:163], v[182:185], v[116:119]
	v_mfma_f32_16x16x32_bf16 v[112:115], v[170:173], v[182:185], v[112:115]
	v_mfma_f32_16x16x32_bf16 v[100:103], v[160:163], v[190:193], v[100:103]
	v_mfma_f32_16x16x32_bf16 v[96:99], v[170:173], v[190:193], v[96:99]
	v_mfma_f32_16x16x32_bf16 v[84:87], v[160:163], v[198:201], v[84:87]
	v_mfma_f32_16x16x32_bf16 v[80:83], v[170:173], v[198:201], v[80:83]
	v_mfma_f32_16x16x32_bf16 v[68:71], v[160:163], v[206:209], v[68:71]
	v_mfma_f32_16x16x32_bf16 v[64:67], v[170:173], v[206:209], v[64:67]
	v_mfma_f32_16x16x32_bf16 v[116:119], v[164:167], v[186:189], v[116:119]
	v_mfma_f32_16x16x32_bf16 v[112:115], v[178:181], v[186:189], v[112:115]
	v_mfma_f32_16x16x32_bf16 v[100:103], v[164:167], v[194:197], v[100:103]
	v_mfma_f32_16x16x32_bf16 v[96:99], v[178:181], v[194:197], v[96:99]
	v_mfma_f32_16x16x32_bf16 v[84:87], v[164:167], v[202:205], v[84:87]
	v_mfma_f32_16x16x32_bf16 v[80:83], v[178:181], v[202:205], v[80:83]
	v_mfma_f32_16x16x32_bf16 v[68:71], v[164:167], v[210:213], v[68:71]
	v_mfma_f32_16x16x32_bf16 v[64:67], v[178:181], v[210:213], v[64:67]
	s_setprio 0
	s_barrier
	s_add_i32 s12, s31, s10
	s_mov_b32 m0, s12
	ds_read_b128 v[182:185], v143 offset:16384
	ds_read_b128 v[186:189], v143 offset:17408
	ds_read_b128 v[190:193], v143 offset:18432
	ds_read_b128 v[194:197], v143 offset:19456
	ds_read_b128 v[198:201], v143 offset:20480
	ds_read_b128 v[202:205], v143 offset:21504
	ds_read_b128 v[206:209], v143 offset:22528
	ds_read_b128 v[210:213], v143 offset:23552
	global_load_lds_dwordx4 v132, s[72:73]
	s_add_i32 m0, s12, 0x2000
	s_add_u32 s12, s72, 0x80000
	s_addc_u32 s13, s73, 0
	s_add_i32 s31, s42, s10
	global_load_lds_dwordx4 v128, s[72:73]
	s_mov_b32 m0, s31
	s_nop 0
	global_load_lds_dwordx4 v132, s[12:13]
	s_add_i32 m0, s31, 0x2000
	s_nop 0
	global_load_lds_dwordx4 v128, s[12:13]
	s_mov_b32 m0, s18
	s_nop 0
	global_load_lds_dwordx4 v134, s[74:75]
	s_mov_b32 m0, s19
	s_nop 0
	global_load_lds_dwordx4 v130, s[74:75]
	s_waitcnt vmcnt(8)
	s_waitcnt lgkmcnt(0)
	s_barrier
	s_setprio 1
	s_waitcnt lgkmcnt(0)
	v_mfma_f32_16x16x32_bf16 v[60:63], v[144:147], v[182:185], v[60:63]
	v_mfma_f32_16x16x32_bf16 v[56:59], v[152:155], v[182:185], v[56:59]
	v_mfma_f32_16x16x32_bf16 v[44:47], v[144:147], v[190:193], v[44:47]
	v_mfma_f32_16x16x32_bf16 v[40:43], v[152:155], v[190:193], v[40:43]
	v_mfma_f32_16x16x32_bf16 v[28:31], v[144:147], v[198:201], v[28:31]
	v_mfma_f32_16x16x32_bf16 v[24:27], v[152:155], v[198:201], v[24:27]
	v_mfma_f32_16x16x32_bf16 v[12:15], v[144:147], v[206:209], v[12:15]
	v_mfma_f32_16x16x32_bf16 v[8:11], v[152:155], v[206:209], v[8:11]
	v_mfma_f32_16x16x32_bf16 v[60:63], v[148:151], v[186:189], v[60:63]
	v_mfma_f32_16x16x32_bf16 v[56:59], v[156:159], v[186:189], v[56:59]
	v_mfma_f32_16x16x32_bf16 v[44:47], v[148:151], v[194:197], v[44:47]
	v_mfma_f32_16x16x32_bf16 v[40:43], v[156:159], v[194:197], v[40:43]
	v_mfma_f32_16x16x32_bf16 v[28:31], v[148:151], v[202:205], v[28:31]
	v_mfma_f32_16x16x32_bf16 v[24:27], v[156:159], v[202:205], v[24:27]
	v_mfma_f32_16x16x32_bf16 v[12:15], v[148:151], v[210:213], v[12:15]
	v_mfma_f32_16x16x32_bf16 v[8:11], v[156:159], v[210:213], v[8:11]
	s_setprio 0
	s_setprio 1
	v_mfma_f32_16x16x32_bf16 v[52:55], v[160:163], v[182:185], v[52:55]
	v_mfma_f32_16x16x32_bf16 v[48:51], v[170:173], v[182:185], v[48:51]
	v_mfma_f32_16x16x32_bf16 v[36:39], v[160:163], v[190:193], v[36:39]
	v_mfma_f32_16x16x32_bf16 v[32:35], v[170:173], v[190:193], v[32:35]
	v_mfma_f32_16x16x32_bf16 v[20:23], v[160:163], v[198:201], v[20:23]
	v_mfma_f32_16x16x32_bf16 v[16:19], v[170:173], v[198:201], v[16:19]
	v_mfma_f32_16x16x32_bf16 v[4:7], v[160:163], v[206:209], v[4:7]
	v_mfma_f32_16x16x32_bf16 v[0:3], v[170:173], v[206:209], v[0:3]
	v_mfma_f32_16x16x32_bf16 v[52:55], v[164:167], v[186:189], v[52:55]
	v_mfma_f32_16x16x32_bf16 v[48:51], v[178:181], v[186:189], v[48:51]
	v_mfma_f32_16x16x32_bf16 v[36:39], v[164:167], v[194:197], v[36:39]
	v_mfma_f32_16x16x32_bf16 v[32:35], v[178:181], v[194:197], v[32:35]
	v_mfma_f32_16x16x32_bf16 v[20:23], v[164:167], v[202:205], v[20:23]
	v_mfma_f32_16x16x32_bf16 v[16:19], v[178:181], v[202:205], v[16:19]
	v_mfma_f32_16x16x32_bf16 v[4:7], v[164:167], v[210:213], v[4:7]
	v_mfma_f32_16x16x32_bf16 v[0:3], v[178:181], v[210:213], v[0:3]
	s_setprio 0
	s_barrier
; #define PG8_STAGE(bufoff, gbase, voff) do { _Pragma("unroll") for (int _i = 0; _i < 2; ++_i) \
;         __builtin_amdgcn_global_load_lds((const unsigned*)((const char*)(gbase) + (voff)[_i]), (PG8_LAS unsigned*)(lds + (bufoff) + ldsw + _i * 8192), 16, 0, 0); } while (0)
; #define PG8_LDA(dst, b, h) do { _Pragma("unroll") for (int m = 0; m < 4; ++m) _Pragma("unroll") for (int k = 0; k < 2; ++k) dst[m][k] = *(const PG8_LAS bf16x8*)(lds + PG8_SA(b, h) + aoff + m * 2048 + k * 1024); } while (0)
; #define PG8_LDB(dst, b, h) do { _Pragma("unroll") for (int n = 0; n < 2; ++n) _Pragma("unroll") for (int k = 0; k < 2; ++k) dst[n][k] = *(const PG8_LAS bf16x8*)(lds + PG8_SB(b, h) + boff + n * 2048 + k * 1024); } while (0)
; #define PG8_MMA(ai, bj, At, Bt) do { __builtin_amdgcn_s_setprio(1); _Pragma("unroll") for (int m = 0; m < 4; ++m) _Pragma("unroll") for (int n = 0; n < 2; ++n) _Pragma("unroll") for (int k = 0; k < 2; ++k) \
;         acc[ai][bj][m][n] = __builtin_amdgcn_mfma_f32_16x16x32_bf16(Bt[n][k], At[m][k], acc[ai][bj][m][n], 0, 0, 0); __builtin_amdgcn_s_setprio(0); } while (0)
; #define PG8_WAIT_V(n) asm volatile("s_waitcnt vmcnt(" #n ")" ::: "memory")
; #define PG8_WAIT_L(n) asm volatile("s_waitcnt lgkmcnt(" #n ")" ::: "memory")
; #define PG8_BAR __builtin_amdgcn_s_barrier()
; #define PG8_SCHED __builtin_amdgcn_sched_barrier(0)
;     ...
;             PG8_LDB(B0, 1, 0); PG8_LDB(B1, 1, 1); PG8_SCHED; PG8_LDA(At, 1, 0); PG8_STAGE(PG8_SA(0, 1), a2 + hstep, voffA);
;             PG8_WAIT_V(8); PG8_WAIT_L(0); PG8_BAR; PG8_MMA(0, 0, At, B0); PG8_MMA(0, 1, At, B1); PG8_BAR; PG8_SCHED;
;             PG8_LDA(At, 1, 1); PG8_STAGE(PG8_SB(1, 0), b3, voffB); PG8_STAGE(PG8_SB(1, 1), b3 + hstep, voffB); PG8_STAGE(PG8_SA(1, 0), a3, voffA);
;             PG8_WAIT_V(8); PG8_WAIT_L(0); PG8_BAR; PG8_MMA(1, 0, At, B0); PG8_MMA(1, 1, At, B1); PG8_BAR; PG8_SCHED;
	s_add_i32 s31, 0, 0x18000
	s_add_i32 s42, 0, 0x1c000
	v_add_u32_e32 v156, s31, v141
	v_add_u32_e32 v168, s42, v141
	ds_read_b128 v[144:147], v156
	ds_read_b128 v[148:151], v156 offset:1024
	ds_read_b128 v[152:155], v156 offset:2048
	ds_read_b128 v[156:159], v156 offset:3072
	ds_read_b128 v[160:163], v168
	ds_read_b128 v[164:167], v168 offset:1024
	ds_read_b128 v[170:173], v168 offset:2048
	ds_read_b128 v[178:181], v168 offset:3072
	s_add_u32 s12, s74, 0x80000
	s_addc_u32 s13, s75, 0
	s_mov_b32 m0, s20
	ds_read_b128 v[182:185], v143 offset:32768
	ds_read_b128 v[186:189], v143 offset:33792
	ds_read_b128 v[190:193], v143 offset:34816
	ds_read_b128 v[194:197], v143 offset:35840
	ds_read_b128 v[198:201], v143 offset:36864
	ds_read_b128 v[202:205], v143 offset:37888
	ds_read_b128 v[206:209], v143 offset:38912
	ds_read_b128 v[210:213], v143 offset:39936
	global_load_lds_dwordx4 v134, s[12:13]
	s_mov_b32 m0, s21
	s_nop 0
	global_load_lds_dwordx4 v130, s[12:13]
	s_waitcnt vmcnt(8)
	s_waitcnt lgkmcnt(0)
	s_barrier
	s_setprio 1
	s_waitcnt lgkmcnt(0)
	v_mfma_f32_16x16x32_bf16 v[124:127], v[144:147], v[182:185], v[124:127]
	v_mfma_f32_16x16x32_bf16 v[120:123], v[152:155], v[182:185], v[120:123]
	v_mfma_f32_16x16x32_bf16 v[108:111], v[144:147], v[190:193], v[108:111]
	v_mfma_f32_16x16x32_bf16 v[104:107], v[152:155], v[190:193], v[104:107]
	v_mfma_f32_16x16x32_bf16 v[92:95], v[144:147], v[198:201], v[92:95]
	v_mfma_f32_16x16x32_bf16 v[88:91], v[152:155], v[198:201], v[88:91]
	v_mfma_f32_16x16x32_bf16 v[76:79], v[144:147], v[206:209], v[76:79]
	v_mfma_f32_16x16x32_bf16 v[72:75], v[152:155], v[206:209], v[72:75]
	v_mfma_f32_16x16x32_bf16 v[124:127], v[148:151], v[186:189], v[124:127]
	v_mfma_f32_16x16x32_bf16 v[120:123], v[156:159], v[186:189], v[120:123]
	v_mfma_f32_16x16x32_bf16 v[108:111], v[148:151], v[194:197], v[108:111]
	v_mfma_f32_16x16x32_bf16 v[104:107], v[156:159], v[194:197], v[104:107]
	v_mfma_f32_16x16x32_bf16 v[92:95], v[148:151], v[202:205], v[92:95]
	v_mfma_f32_16x16x32_bf16 v[88:91], v[156:159], v[202:205], v[88:91]
	v_mfma_f32_16x16x32_bf16 v[76:79], v[148:151], v[210:213], v[76:79]
	v_mfma_f32_16x16x32_bf16 v[72:75], v[156:159], v[210:213], v[72:75]
	s_setprio 0
	s_setprio 1
	v_mfma_f32_16x16x32_bf16 v[116:119], v[160:163], v[182:185], v[116:119]
	v_mfma_f32_16x16x32_bf16 v[112:115], v[170:173], v[182:185], v[112:115]
	v_mfma_f32_16x16x32_bf16 v[100:103], v[160:163], v[190:193], v[100:103]
	v_mfma_f32_16x16x32_bf16 v[96:99], v[170:173], v[190:193], v[96:99]
	v_mfma_f32_16x16x32_bf16 v[84:87], v[160:163], v[198:201], v[84:87]
	v_mfma_f32_16x16x32_bf16 v[80:83], v[170:173], v[198:201], v[80:83]
	v_mfma_f32_16x16x32_bf16 v[68:71], v[160:163], v[206:209], v[68:71]
	v_mfma_f32_16x16x32_bf16 v[64:67], v[170:173], v[206:209], v[64:67]
	v_mfma_f32_16x16x32_bf16 v[116:119], v[164:167], v[186:189], v[116:119]
	v_mfma_f32_16x16x32_bf16 v[112:115], v[178:181], v[186:189], v[112:115]
	v_mfma_f32_16x16x32_bf16 v[100:103], v[164:167], v[194:197], v[100:103]
	v_mfma_f32_16x16x32_bf16 v[96:99], v[178:181], v[194:197], v[96:99]
	v_mfma_f32_16x16x32_bf16 v[84:87], v[164:167], v[202:205], v[84:87]
	v_mfma_f32_16x16x32_bf16 v[80:83], v[178:181], v[202:205], v[80:83]
	v_mfma_f32_16x16x32_bf16 v[68:71], v[164:167], v[210:213], v[68:71]
	v_mfma_f32_16x16x32_bf16 v[64:67], v[178:181], v[210:213], v[64:67]
	s_setprio 0
	s_barrier
	s_add_i32 s12, s31, s10
	s_mov_b32 m0, s12
	ds_read_b128 v[182:185], v143 offset:49152
	ds_read_b128 v[186:189], v143 offset:50176
	ds_read_b128 v[190:193], v143 offset:51200
	ds_read_b128 v[194:197], v143 offset:52224
	ds_read_b128 v[198:201], v143 offset:53248
	ds_read_b128 v[202:205], v143 offset:54272
	ds_read_b128 v[206:209], v143 offset:55296
	ds_read_b128 v[210:213], v143 offset:56320
	s_add_u32 s100, s72, s16
	s_addc_u32 s101, s73, s17
	global_load_lds_dwordx4 v132, s[100:101]
	s_add_i32 m0, s12, 0x2000
	s_add_u32 s12, s72, 0x80080
	s_addc_u32 s13, s73, 0
	s_add_i32 s31, s42, s10
	global_load_lds_dwordx4 v128, s[100:101]
	s_mov_b32 m0, s31
	s_nop 0
	global_load_lds_dwordx4 v132, s[12:13]
	s_add_i32 m0, s31, 0x2000
	s_nop 0
	global_load_lds_dwordx4 v128, s[12:13]
	s_mov_b32 m0, s22
	s_nop 0
	s_add_u32 s100, s74, s16
	s_addc_u32 s101, s75, s17
	global_load_lds_dwordx4 v134, s[100:101]
	s_mov_b32 m0, s23
	s_nop 0
	global_load_lds_dwordx4 v130, s[100:101]
	s_waitcnt vmcnt(8)
	s_waitcnt lgkmcnt(0)
	s_barrier
	s_setprio 1
	s_waitcnt lgkmcnt(0)
	v_mfma_f32_16x16x32_bf16 v[60:63], v[144:147], v[182:185], v[60:63]
	v_mfma_f32_16x16x32_bf16 v[56:59], v[152:155], v[182:185], v[56:59]
	v_mfma_f32_16x16x32_bf16 v[44:47], v[144:147], v[190:193], v[44:47]
	v_mfma_f32_16x16x32_bf16 v[40:43], v[152:155], v[190:193], v[40:43]
	v_mfma_f32_16x16x32_bf16 v[28:31], v[144:147], v[198:201], v[28:31]
	v_mfma_f32_16x16x32_bf16 v[24:27], v[152:155], v[198:201], v[24:27]
	v_mfma_f32_16x16x32_bf16 v[12:15], v[144:147], v[206:209], v[12:15]
	v_mfma_f32_16x16x32_bf16 v[8:11], v[152:155], v[206:209], v[8:11]
	v_mfma_f32_16x16x32_bf16 v[60:63], v[148:151], v[186:189], v[60:63]
	v_mfma_f32_16x16x32_bf16 v[56:59], v[156:159], v[186:189], v[56:59]
	v_mfma_f32_16x16x32_bf16 v[44:47], v[148:151], v[194:197], v[44:47]
	v_mfma_f32_16x16x32_bf16 v[40:43], v[156:159], v[194:197], v[40:43]
	v_mfma_f32_16x16x32_bf16 v[28:31], v[148:151], v[202:205], v[28:31]
	v_mfma_f32_16x16x32_bf16 v[24:27], v[156:159], v[202:205], v[24:27]
	v_mfma_f32_16x16x32_bf16 v[12:15], v[148:151], v[210:213], v[12:15]
	v_mfma_f32_16x16x32_bf16 v[8:11], v[156:159], v[210:213], v[8:11]
	s_setprio 0
	s_setprio 1
	v_mfma_f32_16x16x32_bf16 v[52:55], v[160:163], v[182:185], v[52:55]
	v_mfma_f32_16x16x32_bf16 v[48:51], v[170:173], v[182:185], v[48:51]
	v_mfma_f32_16x16x32_bf16 v[36:39], v[160:163], v[190:193], v[36:39]
	v_mfma_f32_16x16x32_bf16 v[32:35], v[170:173], v[190:193], v[32:35]
	v_mfma_f32_16x16x32_bf16 v[20:23], v[160:163], v[198:201], v[20:23]
	v_mfma_f32_16x16x32_bf16 v[16:19], v[170:173], v[198:201], v[16:19]
	v_mfma_f32_16x16x32_bf16 v[4:7], v[160:163], v[206:209], v[4:7]
	v_mfma_f32_16x16x32_bf16 v[0:3], v[170:173], v[206:209], v[0:3]
	v_mfma_f32_16x16x32_bf16 v[52:55], v[164:167], v[186:189], v[52:55]
	v_mfma_f32_16x16x32_bf16 v[48:51], v[178:181], v[186:189], v[48:51]
	v_mfma_f32_16x16x32_bf16 v[36:39], v[164:167], v[194:197], v[36:39]
	v_mfma_f32_16x16x32_bf16 v[32:35], v[178:181], v[194:197], v[32:35]
	v_mfma_f32_16x16x32_bf16 v[20:23], v[164:167], v[202:205], v[20:23]
	v_mfma_f32_16x16x32_bf16 v[16:19], v[178:181], v[202:205], v[16:19]
	v_mfma_f32_16x16x32_bf16 v[4:7], v[164:167], v[210:213], v[4:7]
	v_mfma_f32_16x16x32_bf16 v[0:3], v[178:181], v[210:213], v[0:3]
	s_setprio 0
	s_barrier
	s_add_i32 s3, s3, 2
	s_add_u32 s70, s70, 0x100
	s_addc_u32 s71, s71, 0
	s_add_u32 s40, s40, 0x100
	s_addc_u32 s2, s2, 0
	s_cmp_gt_u32 s3, 29
	s_cbranch_scc0 .LBB0_983
	s_and_b64 vcc, exec, s[56:57]
	s_cbranch_vccz .LBB0_986
	s_barrier

; #define PG8_STAGE(bufoff, gbase, voff) do { _Pragma("unroll") for (int _i = 0; _i < 2; ++_i) \
;         __builtin_amdgcn_global_load_lds((const unsigned*)((const char*)(gbase) + (voff)[_i]), (PG8_LAS unsigned*)(lds + (bufoff) + ldsw + _i * 8192), 16, 0, 0); } while (0)
; #define PG8_LDA(dst, b, h) do { _Pragma("unroll") for (int m = 0; m < 4; ++m) _Pragma("unroll") for (int k = 0; k < 2; ++k) dst[m][k] = *(const PG8_LAS bf16x8*)(lds + PG8_SA(b, h) + aoff + m * 2048 + k * 1024); } while (0)
; #define PG8_LDB(dst, b, h) do { _Pragma("unroll") for (int n = 0; n < 2; ++n) _Pragma("unroll") for (int k = 0; k < 2; ++k) dst[n][k] = *(const PG8_LAS bf16x8*)(lds + PG8_SB(b, h) + boff + n * 2048 + k * 1024); } while (0)
; #define PG8_MMA(ai, bj, At, Bt) do { __builtin_amdgcn_s_setprio(1); _Pragma("unroll") for (int m = 0; m < 4; ++m) _Pragma("unroll") for (int n = 0; n < 2; ++n) _Pragma("unroll") for (int k = 0; k < 2; ++k) \
;         acc[ai][bj][m][n] = __builtin_amdgcn_mfma_f32_16x16x32_bf16(Bt[n][k], At[m][k], acc[ai][bj][m][n], 0, 0, 0); __builtin_amdgcn_s_setprio(0); } while (0)
; #define PG8_WAIT_V(n) asm volatile("s_waitcnt vmcnt(" #n ")" ::: "memory")
; #define PG8_WAIT_L(n) asm volatile("s_waitcnt lgkmcnt(" #n ")" ::: "memory")
; #define PG8_BAR __builtin_amdgcn_s_barrier()
; #define PG8_SCHED __builtin_amdgcn_sched_barrier(0)
;     ...
;             const bool last = (t == nt - 2);
;             const char* a1 = PG8_KADV(cA, (size_t)(t + 1) * kstep);
;             const char* a2 = last ? nA : PG8_KADV(cA, (size_t)(t + 2) * kstep); const char* b2 = last ? nB : PG8_KADV(cB, (size_t)(t + 2) * kstep);
;             const char* a3 = PG8_KADV(a2, kstep); const char* b3 = PG8_KADV(b2, kstep);
;             if (last && has_next) S.a_ready(nxt);
;             if constexpr (SP2) {
;             PG8_LDB(B0, 0, 0); PG8_LDB(B1, 0, 1); PG8_SCHED; PG8_LDA(At, 0, 0); PG8_STAGE(PG8_SA(1, 1), a1 + hstep, voffA);
;             PG8_WAIT_V(8); PG8_WAIT_L(0); PG8_BAR; PG8_MMA(0, 0, At, B0); PG8_MMA(0, 1, At, B1); PG8_BAR; PG8_SCHED;
;             PG8_LDA(At, 0, 1); PG8_STAGE(PG8_SB(0, 0), b2, voffB); PG8_STAGE(PG8_SB(0, 1), b2 + hstep, voffB); PG8_STAGE(PG8_SA(0, 0), a2, voffA);
;             PG8_WAIT_V(8); PG8_WAIT_L(0); PG8_BAR; PG8_MMA(1, 0, At, B0); PG8_MMA(1, 1, At, B1); PG8_BAR; PG8_SCHED;
.LBB0_1066:
	s_add_u32 s62, s60, 0xffffff00
	s_addc_u32 s63, s61, -1
	s_add_i32 s26, 0, 0x10000
	s_cmpk_eq_i32 s3, 0x54
	s_cselect_b32 s67, s5, s63
	s_cselect_b32 s66, s4, s62
	s_cselect_b32 s65, s59, s25
	s_cselect_b32 s64, s58, s2
	s_add_i32 s28, 0, 0x14000
	v_add_u32_e32 v152, s26, v166
	v_add_u32_e32 v164, s28, v166
	ds_read_b128 v[128:131], v152
	ds_read_b128 v[132:135], v152 offset:1024
	ds_read_b128 v[148:151], v152 offset:2048
	ds_read_b128 v[152:155], v152 offset:3072
	ds_read_b128 v[156:159], v164
	ds_read_b128 v[160:163], v164 offset:1024
	ds_read_b128 v[170:173], v164 offset:2048
	ds_read_b128 v[178:181], v164 offset:3072
	s_add_i32 m0, s13, 0xc000
	ds_read_b128 v[184:187], v183
	ds_read_b128 v[188:191], v183 offset:1024
	ds_read_b128 v[192:195], v183 offset:2048
	ds_read_b128 v[196:199], v183 offset:3072
	ds_read_b128 v[200:203], v183 offset:4096
	ds_read_b128 v[204:207], v183 offset:5120
	ds_read_b128 v[208:211], v183 offset:6144
	ds_read_b128 v[212:215], v183 offset:7168
	global_load_lds_dwordx4 v144, s[60:61]
	s_add_i32 m0, s13, 0xe000
	s_nop 0
	global_load_lds_dwordx4 v146, s[60:61]
	s_waitcnt vmcnt(8)
	s_waitcnt lgkmcnt(0)
	s_barrier
	s_setprio 1
	s_waitcnt lgkmcnt(0)
	v_mfma_f32_16x16x32_bf16 v[124:127], v[128:131], v[184:187], v[124:127]
	v_mfma_f32_16x16x32_bf16 v[120:123], v[148:151], v[184:187], v[120:123]
	v_mfma_f32_16x16x32_bf16 v[112:115], v[128:131], v[192:195], v[112:115]
	v_mfma_f32_16x16x32_bf16 v[104:107], v[148:151], v[192:195], v[104:107]
	v_mfma_f32_16x16x32_bf16 v[92:95], v[128:131], v[200:203], v[92:95]
	v_mfma_f32_16x16x32_bf16 v[88:91], v[148:151], v[200:203], v[88:91]
	v_mfma_f32_16x16x32_bf16 v[80:83], v[128:131], v[208:211], v[80:83]
	v_mfma_f32_16x16x32_bf16 v[72:75], v[148:151], v[208:211], v[72:75]
	v_mfma_f32_16x16x32_bf16 v[124:127], v[132:135], v[188:191], v[124:127]
	v_mfma_f32_16x16x32_bf16 v[120:123], v[152:155], v[188:191], v[120:123]
	v_mfma_f32_16x16x32_bf16 v[112:115], v[132:135], v[196:199], v[112:115]
	v_mfma_f32_16x16x32_bf16 v[104:107], v[152:155], v[196:199], v[104:107]
	v_mfma_f32_16x16x32_bf16 v[92:95], v[132:135], v[204:207], v[92:95]
	v_mfma_f32_16x16x32_bf16 v[88:91], v[152:155], v[204:207], v[88:91]
	v_mfma_f32_16x16x32_bf16 v[80:83], v[132:135], v[212:215], v[80:83]
	v_mfma_f32_16x16x32_bf16 v[72:75], v[152:155], v[212:215], v[72:75]
	s_setprio 0
	s_setprio 1
	v_mfma_f32_16x16x32_bf16 v[116:119], v[156:159], v[184:187], v[116:119]
	v_mfma_f32_16x16x32_bf16 v[108:111], v[170:173], v[184:187], v[108:111]
	v_mfma_f32_16x16x32_bf16 v[100:103], v[156:159], v[192:195], v[100:103]
	v_mfma_f32_16x16x32_bf16 v[96:99], v[170:173], v[192:195], v[96:99]
	v_mfma_f32_16x16x32_bf16 v[84:87], v[156:159], v[200:203], v[84:87]
	v_mfma_f32_16x16x32_bf16 v[76:79], v[170:173], v[200:203], v[76:79]
	v_mfma_f32_16x16x32_bf16 v[68:71], v[156:159], v[208:211], v[68:71]
	v_mfma_f32_16x16x32_bf16 v[64:67], v[170:173], v[208:211], v[64:67]
	v_mfma_f32_16x16x32_bf16 v[116:119], v[160:163], v[188:191], v[116:119]
	v_mfma_f32_16x16x32_bf16 v[108:111], v[178:181], v[188:191], v[108:111]
	v_mfma_f32_16x16x32_bf16 v[100:103], v[160:163], v[196:199], v[100:103]
	v_mfma_f32_16x16x32_bf16 v[96:99], v[178:181], v[196:199], v[96:99]
	v_mfma_f32_16x16x32_bf16 v[84:87], v[160:163], v[204:207], v[84:87]
	v_mfma_f32_16x16x32_bf16 v[76:79], v[178:181], v[204:207], v[76:79]
	v_mfma_f32_16x16x32_bf16 v[68:71], v[160:163], v[212:215], v[68:71]
	v_mfma_f32_16x16x32_bf16 v[64:67], v[178:181], v[212:215], v[64:67]
	s_setprio 0
	s_barrier
	s_add_i32 s26, s26, s10
	s_mov_b32 m0, s26
	ds_read_b128 v[184:187], v183 offset:16384
	ds_read_b128 v[188:191], v183 offset:17408
	ds_read_b128 v[192:195], v183 offset:18432
	ds_read_b128 v[196:199], v183 offset:19456
	ds_read_b128 v[200:203], v183 offset:20480
	ds_read_b128 v[204:207], v183 offset:21504
	ds_read_b128 v[208:211], v183 offset:22528
	ds_read_b128 v[212:215], v183 offset:23552
	global_load_lds_dwordx4 v138, s[64:65]
	s_add_i32 m0, s26, 0x2000
	s_add_u32 s42, s64, 0x160000
	s_addc_u32 s43, s65, 0
	s_add_i32 s26, s28, s10
	global_load_lds_dwordx4 v142, s[64:65]
	s_mov_b32 m0, s26
	s_nop 0
	global_load_lds_dwordx4 v138, s[42:43]
	s_add_i32 m0, s26, 0x2000
	s_nop 0
	global_load_lds_dwordx4 v142, s[42:43]
	s_mov_b32 m0, s13
	s_nop 0
	global_load_lds_dwordx4 v136, s[66:67]
	s_mov_b32 m0, s18
	s_nop 0
	global_load_lds_dwordx4 v140, s[66:67]
	s_waitcnt vmcnt(8)
	s_waitcnt lgkmcnt(0)
	s_barrier
	s_setprio 1
	s_waitcnt lgkmcnt(0)
	v_mfma_f32_16x16x32_bf16 v[60:63], v[128:131], v[184:187], v[60:63]
	v_mfma_f32_16x16x32_bf16 v[56:59], v[148:151], v[184:187], v[56:59]
	v_mfma_f32_16x16x32_bf16 v[48:51], v[128:131], v[192:195], v[48:51]
	v_mfma_f32_16x16x32_bf16 v[40:43], v[148:151], v[192:195], v[40:43]
	v_mfma_f32_16x16x32_bf16 v[28:31], v[128:131], v[200:203], v[28:31]
	v_mfma_f32_16x16x32_bf16 v[24:27], v[148:151], v[200:203], v[24:27]
	v_mfma_f32_16x16x32_bf16 v[16:19], v[128:131], v[208:211], v[16:19]
	v_mfma_f32_16x16x32_bf16 v[8:11], v[148:151], v[208:211], v[8:11]
	v_mfma_f32_16x16x32_bf16 v[60:63], v[132:135], v[188:191], v[60:63]
	v_mfma_f32_16x16x32_bf16 v[56:59], v[152:155], v[188:191], v[56:59]
	v_mfma_f32_16x16x32_bf16 v[48:51], v[132:135], v[196:199], v[48:51]
	v_mfma_f32_16x16x32_bf16 v[40:43], v[152:155], v[196:199], v[40:43]
	v_mfma_f32_16x16x32_bf16 v[28:31], v[132:135], v[204:207], v[28:31]
	v_mfma_f32_16x16x32_bf16 v[24:27], v[152:155], v[204:207], v[24:27]
	v_mfma_f32_16x16x32_bf16 v[16:19], v[132:135], v[212:215], v[16:19]
	v_mfma_f32_16x16x32_bf16 v[8:11], v[152:155], v[212:215], v[8:11]
	s_setprio 0
	s_setprio 1
	v_mfma_f32_16x16x32_bf16 v[52:55], v[156:159], v[184:187], v[52:55]
	v_mfma_f32_16x16x32_bf16 v[44:47], v[170:173], v[184:187], v[44:47]
	v_mfma_f32_16x16x32_bf16 v[36:39], v[156:159], v[192:195], v[36:39]
	v_mfma_f32_16x16x32_bf16 v[32:35], v[170:173], v[192:195], v[32:35]
	v_mfma_f32_16x16x32_bf16 v[20:23], v[156:159], v[200:203], v[20:23]
	v_mfma_f32_16x16x32_bf16 v[12:15], v[170:173], v[200:203], v[12:15]
	v_mfma_f32_16x16x32_bf16 v[4:7], v[156:159], v[208:211], v[4:7]
	v_mfma_f32_16x16x32_bf16 v[0:3], v[170:173], v[208:211], v[0:3]
	v_mfma_f32_16x16x32_bf16 v[52:55], v[160:163], v[188:191], v[52:55]
	v_mfma_f32_16x16x32_bf16 v[44:47], v[178:181], v[188:191], v[44:47]
	v_mfma_f32_16x16x32_bf16 v[36:39], v[160:163], v[196:199], v[36:39]
	v_mfma_f32_16x16x32_bf16 v[32:35], v[178:181], v[196:199], v[32:35]
	v_mfma_f32_16x16x32_bf16 v[20:23], v[160:163], v[204:207], v[20:23]
	v_mfma_f32_16x16x32_bf16 v[12:15], v[178:181], v[204:207], v[12:15]
	v_mfma_f32_16x16x32_bf16 v[4:7], v[160:163], v[212:215], v[4:7]
	v_mfma_f32_16x16x32_bf16 v[0:3], v[178:181], v[212:215], v[0:3]
	s_setprio 0
	s_barrier
; #define PG8_STAGE(bufoff, gbase, voff) do { _Pragma("unroll") for (int _i = 0; _i < 2; ++_i) \
;         __builtin_amdgcn_global_load_lds((const unsigned*)((const char*)(gbase) + (voff)[_i]), (PG8_LAS unsigned*)(lds + (bufoff) + ldsw + _i * 8192), 16, 0, 0); } while (0)
; #define PG8_LDA(dst, b, h) do { _Pragma("unroll") for (int m = 0; m < 4; ++m) _Pragma("unroll") for (int k = 0; k < 2; ++k) dst[m][k] = *(const PG8_LAS bf16x8*)(lds + PG8_SA(b, h) + aoff + m * 2048 + k * 1024); } while (0)
; #define PG8_LDB(dst, b, h) do { _Pragma("unroll") for (int n = 0; n < 2; ++n) _Pragma("unroll") for (int k = 0; k < 2; ++k) dst[n][k] = *(const PG8_LAS bf16x8*)(lds + PG8_SB(b, h) + boff + n * 2048 + k * 1024); } while (0)
; #define PG8_MMA(ai, bj, At, Bt) do { __builtin_amdgcn_s_setprio(1); _Pragma("unroll") for (int m = 0; m < 4; ++m) _Pragma("unroll") for (int n = 0; n < 2; ++n) _Pragma("unroll") for (int k = 0; k < 2; ++k) \
;         acc[ai][bj][m][n] = __builtin_amdgcn_mfma_f32_16x16x32_bf16(Bt[n][k], At[m][k], acc[ai][bj][m][n], 0, 0, 0); __builtin_amdgcn_s_setprio(0); } while (0)
; #define PG8_WAIT_V(n) asm volatile("s_waitcnt vmcnt(" #n ")" ::: "memory")
; #define PG8_WAIT_L(n) asm volatile("s_waitcnt lgkmcnt(" #n ")" ::: "memory")
; #define PG8_BAR __builtin_amdgcn_s_barrier()
; #define PG8_SCHED __builtin_amdgcn_sched_barrier(0)
;     ...
;             PG8_LDB(B0, 1, 0); PG8_LDB(B1, 1, 1); PG8_SCHED; PG8_LDA(At, 1, 0); PG8_STAGE(PG8_SA(0, 1), a2 + hstep, voffA);
;             PG8_WAIT_V(8); PG8_WAIT_L(0); PG8_BAR; PG8_MMA(0, 0, At, B0); PG8_MMA(0, 1, At, B1); PG8_BAR; PG8_SCHED;
;             PG8_LDA(At, 1, 1); PG8_STAGE(PG8_SB(1, 0), b3, voffB); PG8_STAGE(PG8_SB(1, 1), b3 + hstep, voffB); PG8_STAGE(PG8_SA(1, 0), a3, voffA);
;             PG8_WAIT_V(8); PG8_WAIT_L(0); PG8_BAR; PG8_MMA(1, 0, At, B0); PG8_MMA(1, 1, At, B1); PG8_BAR; PG8_SCHED;
	s_add_i32 s26, 0, 0x18000
	s_add_i32 s28, 0, 0x1c000
	v_add_u32_e32 v152, s26, v166
	v_add_u32_e32 v168, s28, v166
	ds_read_b128 v[128:131], v152
	ds_read_b128 v[132:135], v152 offset:1024
	ds_read_b128 v[148:151], v152 offset:2048
	ds_read_b128 v[152:155], v152 offset:3072
	ds_read_b128 v[156:159], v168
	ds_read_b128 v[160:163], v168 offset:1024
	ds_read_b128 v[170:173], v168 offset:2048
	ds_read_b128 v[178:181], v168 offset:3072
	s_add_u32 s42, s66, 0x160000
	s_addc_u32 s43, s67, 0
	s_mov_b32 m0, s19
	ds_read_b128 v[184:187], v183 offset:32768
	ds_read_b128 v[188:191], v183 offset:33792
	ds_read_b128 v[192:195], v183 offset:34816
	ds_read_b128 v[196:199], v183 offset:35840
	ds_read_b128 v[200:203], v183 offset:36864
	ds_read_b128 v[204:207], v183 offset:37888
	ds_read_b128 v[208:211], v183 offset:38912
	ds_read_b128 v[212:215], v183 offset:39936
	global_load_lds_dwordx4 v136, s[42:43]
	s_mov_b32 m0, s20
	s_nop 0
	global_load_lds_dwordx4 v140, s[42:43]
	s_waitcnt vmcnt(8)
	s_waitcnt lgkmcnt(0)
	s_barrier
	s_setprio 1
	s_waitcnt lgkmcnt(0)
	v_mfma_f32_16x16x32_bf16 v[124:127], v[128:131], v[184:187], v[124:127]
	v_mfma_f32_16x16x32_bf16 v[120:123], v[148:151], v[184:187], v[120:123]
	v_mfma_f32_16x16x32_bf16 v[112:115], v[128:131], v[192:195], v[112:115]
	v_mfma_f32_16x16x32_bf16 v[104:107], v[148:151], v[192:195], v[104:107]
	v_mfma_f32_16x16x32_bf16 v[92:95], v[128:131], v[200:203], v[92:95]
	v_mfma_f32_16x16x32_bf16 v[88:91], v[148:151], v[200:203], v[88:91]
	v_mfma_f32_16x16x32_bf16 v[80:83], v[128:131], v[208:211], v[80:83]
	v_mfma_f32_16x16x32_bf16 v[72:75], v[148:151], v[208:211], v[72:75]
	v_mfma_f32_16x16x32_bf16 v[124:127], v[132:135], v[188:191], v[124:127]
	v_mfma_f32_16x16x32_bf16 v[120:123], v[152:155], v[188:191], v[120:123]
	v_mfma_f32_16x16x32_bf16 v[112:115], v[132:135], v[196:199], v[112:115]
	v_mfma_f32_16x16x32_bf16 v[104:107], v[152:155], v[196:199], v[104:107]
	v_mfma_f32_16x16x32_bf16 v[92:95], v[132:135], v[204:207], v[92:95]
	v_mfma_f32_16x16x32_bf16 v[88:91], v[152:155], v[204:207], v[88:91]
	v_mfma_f32_16x16x32_bf16 v[80:83], v[132:135], v[212:215], v[80:83]
	v_mfma_f32_16x16x32_bf16 v[72:75], v[152:155], v[212:215], v[72:75]
	s_setprio 0
	s_setprio 1
	v_mfma_f32_16x16x32_bf16 v[116:119], v[156:159], v[184:187], v[116:119]
	v_mfma_f32_16x16x32_bf16 v[108:111], v[170:173], v[184:187], v[108:111]
	v_mfma_f32_16x16x32_bf16 v[100:103], v[156:159], v[192:195], v[100:103]
	v_mfma_f32_16x16x32_bf16 v[96:99], v[170:173], v[192:195], v[96:99]
	v_mfma_f32_16x16x32_bf16 v[84:87], v[156:159], v[200:203], v[84:87]
	v_mfma_f32_16x16x32_bf16 v[76:79], v[170:173], v[200:203], v[76:79]
	v_mfma_f32_16x16x32_bf16 v[68:71], v[156:159], v[208:211], v[68:71]
	v_mfma_f32_16x16x32_bf16 v[64:67], v[170:173], v[208:211], v[64:67]
	v_mfma_f32_16x16x32_bf16 v[116:119], v[160:163], v[188:191], v[116:119]
	v_mfma_f32_16x16x32_bf16 v[108:111], v[178:181], v[188:191], v[108:111]
	v_mfma_f32_16x16x32_bf16 v[100:103], v[160:163], v[196:199], v[100:103]
	v_mfma_f32_16x16x32_bf16 v[96:99], v[178:181], v[196:199], v[96:99]
	v_mfma_f32_16x16x32_bf16 v[84:87], v[160:163], v[204:207], v[84:87]
	v_mfma_f32_16x16x32_bf16 v[76:79], v[178:181], v[204:207], v[76:79]
	v_mfma_f32_16x16x32_bf16 v[68:71], v[160:163], v[212:215], v[68:71]
	v_mfma_f32_16x16x32_bf16 v[64:67], v[178:181], v[212:215], v[64:67]
	s_setprio 0
	s_barrier
	s_add_i32 s26, s26, s10
	s_mov_b32 m0, s26
	ds_read_b128 v[184:187], v183 offset:49152
	ds_read_b128 v[188:191], v183 offset:50176
	ds_read_b128 v[192:195], v183 offset:51200
	ds_read_b128 v[196:199], v183 offset:52224
	ds_read_b128 v[200:203], v183 offset:53248
	ds_read_b128 v[204:207], v183 offset:54272
	ds_read_b128 v[208:211], v183 offset:55296
	ds_read_b128 v[212:215], v183 offset:56320
	s_add_u32 s100, s64, s38
	s_addc_u32 s101, s65, s39
	global_load_lds_dwordx4 v138, s[100:101]
	s_add_i32 m0, s26, 0x2000
	s_add_u32 s42, s64, 0x15ff80
	s_addc_u32 s43, s65, 0
	s_add_i32 s26, s28, s10
	global_load_lds_dwordx4 v142, s[100:101]
	s_mov_b32 m0, s26
	s_nop 0
	global_load_lds_dwordx4 v138, s[42:43]
	s_add_i32 m0, s26, 0x2000
	s_nop 0
	global_load_lds_dwordx4 v142, s[42:43]
	s_mov_b32 m0, s12
	s_nop 0
	s_add_u32 s100, s66, s38
	s_addc_u32 s101, s67, s39
	global_load_lds_dwordx4 v136, s[100:101]
	s_mov_b32 m0, s21
	s_nop 0
	global_load_lds_dwordx4 v140, s[100:101]
	s_waitcnt vmcnt(8)
	s_waitcnt lgkmcnt(0)
	s_barrier
	s_setprio 1
	s_waitcnt lgkmcnt(0)
	v_mfma_f32_16x16x32_bf16 v[60:63], v[128:131], v[184:187], v[60:63]
	v_mfma_f32_16x16x32_bf16 v[56:59], v[148:151], v[184:187], v[56:59]
	v_mfma_f32_16x16x32_bf16 v[48:51], v[128:131], v[192:195], v[48:51]
	v_mfma_f32_16x16x32_bf16 v[40:43], v[148:151], v[192:195], v[40:43]
	v_mfma_f32_16x16x32_bf16 v[28:31], v[128:131], v[200:203], v[28:31]
	v_mfma_f32_16x16x32_bf16 v[24:27], v[148:151], v[200:203], v[24:27]
	v_mfma_f32_16x16x32_bf16 v[16:19], v[128:131], v[208:211], v[16:19]
	v_mfma_f32_16x16x32_bf16 v[8:11], v[148:151], v[208:211], v[8:11]
	v_mfma_f32_16x16x32_bf16 v[60:63], v[132:135], v[188:191], v[60:63]
	v_mfma_f32_16x16x32_bf16 v[56:59], v[152:155], v[188:191], v[56:59]
	v_mfma_f32_16x16x32_bf16 v[48:51], v[132:135], v[196:199], v[48:51]
	v_mfma_f32_16x16x32_bf16 v[40:43], v[152:155], v[196:199], v[40:43]
	v_mfma_f32_16x16x32_bf16 v[28:31], v[132:135], v[204:207], v[28:31]
	v_mfma_f32_16x16x32_bf16 v[24:27], v[152:155], v[204:207], v[24:27]
	v_mfma_f32_16x16x32_bf16 v[16:19], v[132:135], v[212:215], v[16:19]
	v_mfma_f32_16x16x32_bf16 v[8:11], v[152:155], v[212:215], v[8:11]
	s_setprio 0
	s_setprio 1
	v_mfma_f32_16x16x32_bf16 v[52:55], v[156:159], v[184:187], v[52:55]
	v_mfma_f32_16x16x32_bf16 v[44:47], v[170:173], v[184:187], v[44:47]
	v_mfma_f32_16x16x32_bf16 v[36:39], v[156:159], v[192:195], v[36:39]
	v_mfma_f32_16x16x32_bf16 v[32:35], v[170:173], v[192:195], v[32:35]
	v_mfma_f32_16x16x32_bf16 v[20:23], v[156:159], v[200:203], v[20:23]
	v_mfma_f32_16x16x32_bf16 v[12:15], v[170:173], v[200:203], v[12:15]
	v_mfma_f32_16x16x32_bf16 v[4:7], v[156:159], v[208:211], v[4:7]
	v_mfma_f32_16x16x32_bf16 v[0:3], v[170:173], v[208:211], v[0:3]
	v_mfma_f32_16x16x32_bf16 v[52:55], v[160:163], v[188:191], v[52:55]
	v_mfma_f32_16x16x32_bf16 v[44:47], v[178:181], v[188:191], v[44:47]
	v_mfma_f32_16x16x32_bf16 v[36:39], v[160:163], v[196:199], v[36:39]
	v_mfma_f32_16x16x32_bf16 v[32:35], v[178:181], v[196:199], v[32:35]
	v_mfma_f32_16x16x32_bf16 v[20:23], v[160:163], v[204:207], v[20:23]
	v_mfma_f32_16x16x32_bf16 v[12:15], v[178:181], v[204:207], v[12:15]
	v_mfma_f32_16x16x32_bf16 v[4:7], v[160:163], v[212:215], v[4:7]
	v_mfma_f32_16x16x32_bf16 v[0:3], v[178:181], v[212:215], v[0:3]
	s_setprio 0
	s_barrier
	s_add_i32 s3, s3, 2
	s_add_u32 s2, s2, 0xffffff00
	s_addc_u32 s25, s25, -1
	s_cmpk_gt_u32 s3, 0x55
	s_mov_b64 s[60:61], s[62:63]
	s_cbranch_scc0 .LBB0_1066
	s_and_b64 vcc, exec, s[56:57]
	s_cbranch_vccz .LBB0_1069
	s_barrier

; __global__ void __launch_bounds__(NWAVES * 64, 2) hybrid_fwd(Args args) {
	.amdhsa_kernel _Z10hybrid_fwd4Args
		.amdhsa_group_segment_fixed_size 0
		.amdhsa_private_segment_fixed_size 0
		.amdhsa_kernarg_size 384
		.amdhsa_user_sgpr_count 2
		.amdhsa_user_sgpr_dispatch_ptr 0
		.amdhsa_user_sgpr_queue_ptr 0
		.amdhsa_user_sgpr_kernarg_segment_ptr 1
		.amdhsa_user_sgpr_dispatch_id 0
		.amdhsa_user_sgpr_kernarg_preload_length 0
		.amdhsa_user_sgpr_kernarg_preload_offset 0
		.amdhsa_user_sgpr_private_segment_size 0
		.amdhsa_uses_dynamic_stack 0
		.amdhsa_enable_private_segment 0
		.amdhsa_system_sgpr_workgroup_id_x 1
		.amdhsa_system_sgpr_workgroup_id_y 0
		.amdhsa_system_sgpr_workgroup_id_z 0
		.amdhsa_system_sgpr_workgroup_info 0
		.amdhsa_system_vgpr_workitem_id 0
		.amdhsa_next_free_vgpr 256
		.amdhsa_next_free_sgpr 102
		.amdhsa_accum_offset 256
		.amdhsa_reserve_vcc 1
		.amdhsa_float_round_mode_32 0
		.amdhsa_float_round_mode_16_64 0
		.amdhsa_float_denorm_mode_32 3
		.amdhsa_float_denorm_mode_16_64 3
		.amdhsa_dx10_clamp 1
		.amdhsa_ieee_mode 1
		.amdhsa_fp16_overflow 0
		.amdhsa_tg_split 0
		.amdhsa_exception_fp_ieee_invalid_op 0
		.amdhsa_exception_fp_denorm_src 0
		.amdhsa_exception_fp_ieee_div_zero 0
		.amdhsa_exception_fp_ieee_overflow 0
		.amdhsa_exception_fp_ieee_underflow 0
		.amdhsa_exception_fp_ieee_inexact 0
		.amdhsa_exception_int_div_zero 0
	.end_amdhsa_kernel

; __global__ void __launch_bounds__(NWAVES * 64, 2) hybrid_fwd(Args args) {
amdhsa.kernels:
  - .agpr_count:     0
    .args:
      - .offset:         0
        .size:           128
        .value_kind:     by_value
      - .offset:         128
        .size:           4
        .value_kind:     hidden_block_count_x
      - .offset:         132
        .size:           4
        .value_kind:     hidden_block_count_y
      - .offset:         136
        .size:           4
        .value_kind:     hidden_block_count_z
      - .offset:         140
        .size:           2
        .value_kind:     hidden_group_size_x
      - .offset:         142
        .size:           2
        .value_kind:     hidden_group_size_y
      - .offset:         144
        .size:           2
        .value_kind:     hidden_group_size_z
      - .offset:         146
        .size:           2
        .value_kind:     hidden_remainder_x
      - .offset:         148
        .size:           2
        .value_kind:     hidden_remainder_y
      - .offset:         150
        .size:           2
        .value_kind:     hidden_remainder_z
      - .offset:         168
        .size:           8
        .value_kind:     hidden_global_offset_x
      - .offset:         176
        .size:           8
        .value_kind:     hidden_global_offset_y
      - .offset:         184
        .size:           8
        .value_kind:     hidden_global_offset_z
      - .offset:         192
        .size:           2
        .value_kind:     hidden_grid_dims
      - .offset:         248
        .size:           4
        .value_kind:     hidden_dynamic_lds_size
    .group_segment_fixed_size: 0
    .kernarg_segment_align: 8
    .kernarg_segment_size: 384
    .language:       OpenCL C
    .language_version:
      - 2
      - 0
    .max_flat_workgroup_size: 512
    .name:           _Z10hybrid_fwd4Args
    .private_segment_fixed_size: 0
    .sgpr_count:     108
    .sgpr_spill_count: 54
    .symbol:         _Z10hybrid_fwd4Args.kd
    .uniform_work_group_size: 1
    .uses_dynamic_stack: false
    .vgpr_count:     256
    .vgpr_spill_count: 0
    .wavefront_size: 64
